# v17 + static-priority experiment: loading wave runs at s_setprio 2 during every GEMM load segment (above the MFMA wave's prio 1), timing-only
# speedup vs baseline: 1.0052x; 1.0052x over previous
; #define PG8_STAGE(bufoff, gbase, voff) do { _Pragma("unroll") for (int _i = 0; _i < 2; ++_i) \
;         __builtin_amdgcn_global_load_lds((const unsigned*)((const char*)(gbase) + (voff)[_i]), (PG8_LAS unsigned*)(lds + (bufoff) + ldsw + _i * 8192), 16, 0, 0); } while (0)
; #define PG8_LDA(dst, b, h) do { _Pragma("unroll") for (int m = 0; m < 4; ++m) _Pragma("unroll") for (int k = 0; k < 2; ++k) dst[m][k] = *(const PG8_LAS bf16x8*)(lds + PG8_SA(b, h) + aoff + m * 2048 + k * 1024); } while (0)
; #define PG8_LDB(dst, b, h) do { _Pragma("unroll") for (int n = 0; n < 2; ++n) _Pragma("unroll") for (int k = 0; k < 2; ++k) dst[n][k] = *(const PG8_LAS bf16x8*)(lds + PG8_SB(b, h) + boff + n * 2048 + k * 1024); } while (0)
; #define PG8_WAIT_V(n) asm volatile("s_waitcnt vmcnt(" #n ")" ::: "memory")
; #define PG8_WAIT_L(n) asm volatile("s_waitcnt lgkmcnt(" #n ")" ::: "memory")
; #define PG8_BAR __builtin_amdgcn_s_barrier()
; #define PG8_SCHED __builtin_amdgcn_sched_barrier(0)
; template <class Epi, class Sched, bool ALIGN_EPI = false, bool SP2 = false>
; __device__ __forceinline__ void gemm_phase(PG8_LAS unsigned char* lds, const Gemm g, const Sched& S, const Epi& E) {
;     ...
;         const bool has_next = S.next(ui + 1, nxt);
;         const char* nA = has_next ? (const char*)g.A + (size_t)nxt.pm * tstep : cA; const char* nB = has_next ? (const char*)g.Bt + (size_t)nxt.pn * tstep : cB;
;         for (int t = 0; t < nt; t += 2) {
;             const bool last = (t == nt - 2);
;             const char* a1 = cA + (size_t)(t + 1) * kstep;
;             const char* a2 = last ? nA : cA + (size_t)(t + 2) * kstep; const char* b2 = last ? nB : cB + (size_t)(t + 2) * kstep;
;             const char* a3 = a2 + kstep; const char* b3 = b2 + kstep;
;             if (last && has_next) S.a_ready(nxt);
;             if constexpr (SP2) {
;             PG8_LDB(B0, 0, 0); PG8_LDB(B1, 0, 1); PG8_SCHED; PG8_LDA(At, 0, 0); PG8_STAGE(PG8_SA(1, 1), a1 + hstep, voffA);
;             PG8_WAIT_V(8); PG8_WAIT_L(0); PG8_BAR; PG8_MMA(0, 0, At, B0); PG8_MMA(0, 1, At, B1); PG8_BAR; PG8_SCHED;
;             PG8_LDA(At, 0, 1); PG8_STAGE(PG8_SB(0, 0), b2, voffB); PG8_STAGE(PG8_SB(0, 1), b2 + hstep, voffB); PG8_STAGE(PG8_SA(0, 0), a2, voffA);
;             PG8_WAIT_V(8); PG8_WAIT_L(0); PG8_BAR; PG8_MMA(1, 0, At, B0); PG8_MMA(1, 1, At, B1); PG8_BAR; PG8_SCHED;
.LBB0_41:
	s_ashr_i32 s17, s16, 31
	s_lshl_b64 s[18:19], s[16:17], s28
	s_add_u32 s18, s26, s18
	s_addc_u32 s19, s27, s19
	s_and_b64 s[20:21], s[6:7], exec
	s_cselect_b32 s17, s19, s23
	s_cselect_b32 s42, s18, s22
	s_ashr_i32 s15, s14, 31
	s_lshl_b64 s[20:21], s[14:15], s28
	v_readlane_b32 s44, v251, 2
	v_readlane_b32 s45, v251, 3
	s_add_u32 s20, s44, s20
	s_addc_u32 s21, s45, s21
	s_and_b64 s[44:45], s[6:7], exec
	s_cselect_b32 s15, s21, s25
	s_cselect_b32 s43, s20, s24
	s_add_u32 s22, s22, 0x80
	s_addc_u32 s23, s23, 0
	s_add_u32 s44, s24, 0x100
	s_addc_u32 s45, s25, 0
	s_mov_b32 s24, 0
	s_waitcnt lgkmcnt(0)
	s_add_i32 s46, s24, 2
	s_add_u32 s47, s22, 0x80
	s_addc_u32 s25, s23, 0
	s_add_i32 s50, 0, 0x10000
	s_cmp_eq_u32 s37, s24
	s_cselect_b32 s25, s17, s25
	s_cselect_b32 s24, s42, s47
	s_cselect_b32 s49, s15, s45
	s_cselect_b32 s48, s43, s44
	s_add_i32 s47, 0, 0x14000
	v_add_u32_e32 v142, s50, v165
	v_add_u32_e32 v182, s47, v165
	ds_read_b128 v[130:133], v142
	ds_read_b128 v[134:137], v142 offset:1024
	ds_read_b128 v[138:141], v142 offset:2048
	ds_read_b128 v[142:145], v142 offset:3072
	ds_read_b128 v[146:149], v182
	ds_read_b128 v[150:153], v182 offset:1024
	ds_read_b128 v[154:157], v182 offset:2048
	ds_read_b128 v[182:185], v182 offset:3072
	v_lshl_add_u64 v[198:199], s[22:23], 0, v[178:179]
	s_add_i32 m0, s29, 0xc000
	ds_read_b128 v[186:189], v214
	ds_read_b128 v[190:193], v214 offset:1024
	ds_read_b128 v[194:197], v214 offset:2048
	ds_read_b128 v[216:219], v214 offset:3072
	ds_read_b128 v[220:223], v214 offset:4096
	ds_read_b128 v[224:227], v214 offset:5120
	ds_read_b128 v[228:231], v214 offset:6144
	ds_read_b128 v[232:235], v214 offset:7168
	global_load_lds_dwordx4 v[198:199], off
	v_lshl_add_u64 v[198:199], s[22:23], 0, v[180:181]
	s_add_i32 m0, s29, 0xe000
	s_nop 0
	global_load_lds_dwordx4 v[198:199], off
	s_setprio 0
	s_waitcnt vmcnt(8)
	s_waitcnt lgkmcnt(0)
	s_barrier
	s_setprio 1
	s_waitcnt lgkmcnt(0)
	v_mfma_f32_16x16x32_bf16 v[126:129], v[130:133], v[186:189], 0
	v_mfma_f32_16x16x32_bf16 v[122:125], v[138:141], v[186:189], 0
	v_mfma_f32_16x16x32_bf16 v[110:113], v[130:133], v[194:197], 0
	v_mfma_f32_16x16x32_bf16 v[106:109], v[138:141], v[194:197], 0
	v_mfma_f32_16x16x32_bf16 v[94:97], v[130:133], v[220:223], 0
	v_mfma_f32_16x16x32_bf16 v[90:93], v[138:141], v[220:223], 0
	v_mfma_f32_16x16x32_bf16 v[78:81], v[130:133], v[228:231], 0
	v_mfma_f32_16x16x32_bf16 v[74:77], v[138:141], v[228:231], 0
	v_mfma_f32_16x16x32_bf16 v[126:129], v[134:137], v[190:193], v[126:129]
	v_mfma_f32_16x16x32_bf16 v[122:125], v[142:145], v[190:193], v[122:125]
	v_mfma_f32_16x16x32_bf16 v[110:113], v[134:137], v[216:219], v[110:113]
	v_mfma_f32_16x16x32_bf16 v[106:109], v[142:145], v[216:219], v[106:109]
	v_mfma_f32_16x16x32_bf16 v[94:97], v[134:137], v[224:227], v[94:97]
	v_mfma_f32_16x16x32_bf16 v[90:93], v[142:145], v[224:227], v[90:93]
	v_mfma_f32_16x16x32_bf16 v[78:81], v[134:137], v[232:235], v[78:81]
	v_mfma_f32_16x16x32_bf16 v[74:77], v[142:145], v[232:235], v[74:77]
	s_setprio 0
	s_setprio 1
	v_mfma_f32_16x16x32_bf16 v[118:121], v[146:149], v[186:189], 0
	v_mfma_f32_16x16x32_bf16 v[114:117], v[154:157], v[186:189], 0
	v_mfma_f32_16x16x32_bf16 v[102:105], v[146:149], v[194:197], 0
	v_mfma_f32_16x16x32_bf16 v[98:101], v[154:157], v[194:197], 0
	v_mfma_f32_16x16x32_bf16 v[86:89], v[146:149], v[220:223], 0
	v_mfma_f32_16x16x32_bf16 v[82:85], v[154:157], v[220:223], 0
	v_mfma_f32_16x16x32_bf16 v[70:73], v[146:149], v[228:231], 0
	v_mfma_f32_16x16x32_bf16 v[66:69], v[154:157], v[228:231], 0
	v_mfma_f32_16x16x32_bf16 v[118:121], v[150:153], v[190:193], v[118:121]
	v_mfma_f32_16x16x32_bf16 v[114:117], v[182:185], v[190:193], v[114:117]
	v_mfma_f32_16x16x32_bf16 v[102:105], v[150:153], v[216:219], v[102:105]
	v_mfma_f32_16x16x32_bf16 v[98:101], v[182:185], v[216:219], v[98:101]
	v_mfma_f32_16x16x32_bf16 v[86:89], v[150:153], v[224:227], v[86:89]
	v_mfma_f32_16x16x32_bf16 v[82:85], v[182:185], v[224:227], v[82:85]
	v_mfma_f32_16x16x32_bf16 v[70:73], v[150:153], v[232:235], v[70:73]
	v_mfma_f32_16x16x32_bf16 v[66:69], v[182:185], v[232:235], v[66:69]
	s_setprio 0
	s_barrier
	s_setprio 2
	s_add_i32 s50, s50, s2
	v_lshl_add_u64 v[198:199], s[48:49], 0, v[0:1]
	s_mov_b32 m0, s50
	ds_read_b128 v[186:189], v214 offset:16384
	ds_read_b128 v[190:193], v214 offset:17408
	ds_read_b128 v[194:197], v214 offset:18432
	ds_read_b128 v[216:219], v214 offset:19456
	ds_read_b128 v[220:223], v214 offset:20480
	ds_read_b128 v[224:227], v214 offset:21504
	ds_read_b128 v[228:231], v214 offset:22528
	ds_read_b128 v[232:235], v214 offset:23552
	global_load_lds_dwordx4 v[198:199], off
	s_add_i32 m0, s50, 0x2000
	v_lshl_add_u64 v[236:237], s[48:49], 0, v[172:173]
	s_add_u32 s48, s48, s8
	s_addc_u32 s49, s49, 0
	s_add_i32 s47, s47, s2
	global_load_lds_dwordx4 v[236:237], off
	v_lshl_add_u64 v[238:239], s[48:49], 0, v[0:1]
	s_mov_b32 m0, s47
	v_lshl_add_u64 v[240:241], s[48:49], 0, v[172:173]
	global_load_lds_dwordx4 v[238:239], off
	s_add_i32 m0, s47, 0x2000
	v_lshl_add_u64 v[242:243], s[24:25], 0, v[176:177]
	global_load_lds_dwordx4 v[240:241], off
	s_mov_b32 m0, s29
	v_lshl_add_u64 v[244:245], s[24:25], 0, v[174:175]
	global_load_lds_dwordx4 v[242:243], off
	s_mov_b32 m0, s30
	s_nop 0
	global_load_lds_dwordx4 v[244:245], off
	s_setprio 0
	s_waitcnt vmcnt(8)
	s_waitcnt lgkmcnt(0)
	s_barrier
; #define PG8_STAGE(bufoff, gbase, voff) do { _Pragma("unroll") for (int _i = 0; _i < 2; ++_i) \
;         __builtin_amdgcn_global_load_lds((const unsigned*)((const char*)(gbase) + (voff)[_i]), (PG8_LAS unsigned*)(lds + (bufoff) + ldsw + _i * 8192), 16, 0, 0); } while (0)
; #define PG8_LDA(dst, b, h) do { _Pragma("unroll") for (int m = 0; m < 4; ++m) _Pragma("unroll") for (int k = 0; k < 2; ++k) dst[m][k] = *(const PG8_LAS bf16x8*)(lds + PG8_SA(b, h) + aoff + m * 2048 + k * 1024); } while (0)
; #define PG8_LDB(dst, b, h) do { _Pragma("unroll") for (int n = 0; n < 2; ++n) _Pragma("unroll") for (int k = 0; k < 2; ++k) dst[n][k] = *(const PG8_LAS bf16x8*)(lds + PG8_SB(b, h) + boff + n * 2048 + k * 1024); } while (0)
; #define PG8_MMA(ai, bj, At, Bt) do { __builtin_amdgcn_s_setprio(1); _Pragma("unroll") for (int m = 0; m < 4; ++m) _Pragma("unroll") for (int n = 0; n < 2; ++n) _Pragma("unroll") for (int k = 0; k < 2; ++k) \
;         acc[ai][bj][m][n] = __builtin_amdgcn_mfma_f32_16x16x32_bf16(Bt[n][k], At[m][k], acc[ai][bj][m][n], 0, 0, 0); __builtin_amdgcn_s_setprio(0); } while (0)
; #define PG8_WAIT_V(n) asm volatile("s_waitcnt vmcnt(" #n ")" ::: "memory")
; #define PG8_WAIT_L(n) asm volatile("s_waitcnt lgkmcnt(" #n ")" ::: "memory")
; #define PG8_BAR __builtin_amdgcn_s_barrier()
; #define PG8_SCHED __builtin_amdgcn_sched_barrier(0)
; template <class Epi, class Sched, bool ALIGN_EPI = false, bool SP2 = false>
; __device__ __forceinline__ void gemm_phase(PG8_LAS unsigned char* lds, const Gemm g, const Sched& S, const Epi& E) {
;     ...
;             PG8_WAIT_V(8); PG8_WAIT_L(0); PG8_BAR; PG8_MMA(1, 0, At, B0); PG8_MMA(1, 1, At, B1); PG8_BAR; PG8_SCHED;
;             PG8_LDB(B0, 1, 0); PG8_LDB(B1, 1, 1); PG8_SCHED; PG8_LDA(At, 1, 0); PG8_STAGE(PG8_SA(0, 1), a2 + hstep, voffA);
;             PG8_WAIT_V(8); PG8_WAIT_L(0); PG8_BAR; PG8_MMA(0, 0, At, B0); PG8_MMA(0, 1, At, B1); PG8_BAR; PG8_SCHED;
	s_setprio 1
	s_waitcnt lgkmcnt(0)
	v_mfma_f32_16x16x32_bf16 v[62:65], v[130:133], v[186:189], 0
	v_mfma_f32_16x16x32_bf16 v[58:61], v[138:141], v[186:189], 0
	v_mfma_f32_16x16x32_bf16 v[46:49], v[130:133], v[194:197], 0
	v_mfma_f32_16x16x32_bf16 v[42:45], v[138:141], v[194:197], 0
	v_mfma_f32_16x16x32_bf16 v[30:33], v[130:133], v[220:223], 0
	v_mfma_f32_16x16x32_bf16 v[26:29], v[138:141], v[220:223], 0
	v_mfma_f32_16x16x32_bf16 v[14:17], v[130:133], v[228:231], 0
	v_mfma_f32_16x16x32_bf16 v[10:13], v[138:141], v[228:231], 0
	v_mfma_f32_16x16x32_bf16 v[62:65], v[134:137], v[190:193], v[62:65]
	v_mfma_f32_16x16x32_bf16 v[58:61], v[142:145], v[190:193], v[58:61]
	v_mfma_f32_16x16x32_bf16 v[46:49], v[134:137], v[216:219], v[46:49]
	v_mfma_f32_16x16x32_bf16 v[42:45], v[142:145], v[216:219], v[42:45]
	v_mfma_f32_16x16x32_bf16 v[30:33], v[134:137], v[224:227], v[30:33]
	v_mfma_f32_16x16x32_bf16 v[26:29], v[142:145], v[224:227], v[26:29]
	v_mfma_f32_16x16x32_bf16 v[14:17], v[134:137], v[232:235], v[14:17]
	v_mfma_f32_16x16x32_bf16 v[10:13], v[142:145], v[232:235], v[10:13]
	s_setprio 0
	s_setprio 1
	v_mfma_f32_16x16x32_bf16 v[54:57], v[146:149], v[186:189], 0
	v_mfma_f32_16x16x32_bf16 v[50:53], v[154:157], v[186:189], 0
	v_mfma_f32_16x16x32_bf16 v[38:41], v[146:149], v[194:197], 0
	v_mfma_f32_16x16x32_bf16 v[34:37], v[154:157], v[194:197], 0
	v_mfma_f32_16x16x32_bf16 v[22:25], v[146:149], v[220:223], 0
	v_mfma_f32_16x16x32_bf16 v[18:21], v[154:157], v[220:223], 0
	v_mfma_f32_16x16x32_bf16 v[6:9], v[146:149], v[228:231], 0
	v_mfma_f32_16x16x32_bf16 v[2:5], v[154:157], v[228:231], 0
	v_mfma_f32_16x16x32_bf16 v[54:57], v[150:153], v[190:193], v[54:57]
	v_mfma_f32_16x16x32_bf16 v[50:53], v[182:185], v[190:193], v[50:53]
	v_mfma_f32_16x16x32_bf16 v[38:41], v[150:153], v[216:219], v[38:41]
	v_mfma_f32_16x16x32_bf16 v[34:37], v[182:185], v[216:219], v[34:37]
	v_mfma_f32_16x16x32_bf16 v[22:25], v[150:153], v[224:227], v[22:25]
	v_mfma_f32_16x16x32_bf16 v[18:21], v[182:185], v[224:227], v[18:21]
	v_mfma_f32_16x16x32_bf16 v[6:9], v[150:153], v[232:235], v[6:9]
	v_mfma_f32_16x16x32_bf16 v[2:5], v[182:185], v[232:235], v[2:5]
	s_setprio 0
	s_barrier
	s_setprio 2
	s_add_i32 s47, 0, 0x18000
	s_add_i32 s48, 0, 0x1c000
	v_add_u32_e32 v142, s47, v165
	v_add_u32_e32 v182, s48, v165
	ds_read_b128 v[130:133], v142
	ds_read_b128 v[134:137], v142 offset:1024
	ds_read_b128 v[138:141], v142 offset:2048
	ds_read_b128 v[142:145], v142 offset:3072
	ds_read_b128 v[146:149], v182
	ds_read_b128 v[150:153], v182 offset:1024
	ds_read_b128 v[154:157], v182 offset:2048
	ds_read_b128 v[182:185], v182 offset:3072
	s_add_u32 s24, s24, s8
	s_addc_u32 s25, s25, 0
	s_mov_b32 m0, s31
	v_lshl_add_u64 v[246:247], s[24:25], 0, v[176:177]
	ds_read_b128 v[186:189], v214 offset:32768
	ds_read_b128 v[190:193], v214 offset:33792
	ds_read_b128 v[194:197], v214 offset:34816
	ds_read_b128 v[216:219], v214 offset:35840
	ds_read_b128 v[220:223], v214 offset:36864
	ds_read_b128 v[224:227], v214 offset:37888
	ds_read_b128 v[228:231], v214 offset:38912
	ds_read_b128 v[232:235], v214 offset:39936
	global_load_lds_dwordx4 v[246:247], off
	v_lshl_add_u64 v[246:247], s[24:25], 0, v[174:175]
	s_mov_b32 m0, s34
	s_nop 0
	global_load_lds_dwordx4 v[246:247], off
	s_setprio 0
	s_waitcnt vmcnt(8)
	s_waitcnt lgkmcnt(0)
	s_barrier
	s_setprio 1
	s_waitcnt lgkmcnt(0)
	v_mfma_f32_16x16x32_bf16 v[126:129], v[130:133], v[186:189], v[126:129]
	v_mfma_f32_16x16x32_bf16 v[122:125], v[138:141], v[186:189], v[122:125]
	v_mfma_f32_16x16x32_bf16 v[110:113], v[130:133], v[194:197], v[110:113]
	v_mfma_f32_16x16x32_bf16 v[106:109], v[138:141], v[194:197], v[106:109]
	v_mfma_f32_16x16x32_bf16 v[94:97], v[130:133], v[220:223], v[94:97]
	v_mfma_f32_16x16x32_bf16 v[90:93], v[138:141], v[220:223], v[90:93]
	v_mfma_f32_16x16x32_bf16 v[78:81], v[130:133], v[228:231], v[78:81]
	v_mfma_f32_16x16x32_bf16 v[74:77], v[138:141], v[228:231], v[74:77]
	v_mfma_f32_16x16x32_bf16 v[126:129], v[134:137], v[190:193], v[126:129]
	v_mfma_f32_16x16x32_bf16 v[122:125], v[142:145], v[190:193], v[122:125]
	v_mfma_f32_16x16x32_bf16 v[110:113], v[134:137], v[216:219], v[110:113]
	v_mfma_f32_16x16x32_bf16 v[106:109], v[142:145], v[216:219], v[106:109]
	v_mfma_f32_16x16x32_bf16 v[94:97], v[134:137], v[224:227], v[94:97]
	v_mfma_f32_16x16x32_bf16 v[90:93], v[142:145], v[224:227], v[90:93]
	v_mfma_f32_16x16x32_bf16 v[78:81], v[134:137], v[232:235], v[78:81]
	v_mfma_f32_16x16x32_bf16 v[74:77], v[142:145], v[232:235], v[74:77]
	s_setprio 0
	s_setprio 1
	v_mfma_f32_16x16x32_bf16 v[118:121], v[146:149], v[186:189], v[118:121]
	v_mfma_f32_16x16x32_bf16 v[114:117], v[154:157], v[186:189], v[114:117]
	v_mfma_f32_16x16x32_bf16 v[102:105], v[146:149], v[194:197], v[102:105]
	v_mfma_f32_16x16x32_bf16 v[98:101], v[154:157], v[194:197], v[98:101]
	v_mfma_f32_16x16x32_bf16 v[86:89], v[146:149], v[220:223], v[86:89]
	v_mfma_f32_16x16x32_bf16 v[82:85], v[154:157], v[220:223], v[82:85]
	v_mfma_f32_16x16x32_bf16 v[70:73], v[146:149], v[228:231], v[70:73]
	v_mfma_f32_16x16x32_bf16 v[66:69], v[154:157], v[228:231], v[66:69]
	v_mfma_f32_16x16x32_bf16 v[118:121], v[150:153], v[190:193], v[118:121]
	v_mfma_f32_16x16x32_bf16 v[114:117], v[182:185], v[190:193], v[114:117]
	v_mfma_f32_16x16x32_bf16 v[102:105], v[150:153], v[216:219], v[102:105]
	v_mfma_f32_16x16x32_bf16 v[98:101], v[182:185], v[216:219], v[98:101]
	v_mfma_f32_16x16x32_bf16 v[86:89], v[150:153], v[224:227], v[86:89]
	v_mfma_f32_16x16x32_bf16 v[82:85], v[182:185], v[224:227], v[82:85]
	v_mfma_f32_16x16x32_bf16 v[70:73], v[150:153], v[232:235], v[70:73]
	v_mfma_f32_16x16x32_bf16 v[66:69], v[182:185], v[232:235], v[66:69]
	s_setprio 0
	s_barrier
; #define PG8_STAGE(bufoff, gbase, voff) do { _Pragma("unroll") for (int _i = 0; _i < 2; ++_i) \
;         __builtin_amdgcn_global_load_lds((const unsigned*)((const char*)(gbase) + (voff)[_i]), (PG8_LAS unsigned*)(lds + (bufoff) + ldsw + _i * 8192), 16, 0, 0); } while (0)
; #define PG8_LDA(dst, b, h) do { _Pragma("unroll") for (int m = 0; m < 4; ++m) _Pragma("unroll") for (int k = 0; k < 2; ++k) dst[m][k] = *(const PG8_LAS bf16x8*)(lds + PG8_SA(b, h) + aoff + m * 2048 + k * 1024); } while (0)
; #define PG8_LDB(dst, b, h) do { _Pragma("unroll") for (int n = 0; n < 2; ++n) _Pragma("unroll") for (int k = 0; k < 2; ++k) dst[n][k] = *(const PG8_LAS bf16x8*)(lds + PG8_SB(b, h) + boff + n * 2048 + k * 1024); } while (0)
; #define PG8_MMA(ai, bj, At, Bt) do { __builtin_amdgcn_s_setprio(1); _Pragma("unroll") for (int m = 0; m < 4; ++m) _Pragma("unroll") for (int n = 0; n < 2; ++n) _Pragma("unroll") for (int k = 0; k < 2; ++k) \
;         acc[ai][bj][m][n] = __builtin_amdgcn_mfma_f32_16x16x32_bf16(Bt[n][k], At[m][k], acc[ai][bj][m][n], 0, 0, 0); __builtin_amdgcn_s_setprio(0); } while (0)
; #define PG8_WAIT_V(n) asm volatile("s_waitcnt vmcnt(" #n ")" ::: "memory")
; template <class Epi, class Sched, bool ALIGN_EPI = false, bool SP2 = false>
; __device__ __forceinline__ void gemm_phase(PG8_LAS unsigned char* lds, const Gemm g, const Sched& S, const Epi& E) {
;     ...
;             PG8_LDB(B0, 0, 0); PG8_LDB(B1, 0, 1); PG8_SCHED; PG8_LDA(At, 0, 0); PG8_STAGE(PG8_SA(1, 1), a1 + hstep, voffA);
;             PG8_WAIT_V(8); PG8_WAIT_L(0); PG8_BAR; PG8_MMA(0, 0, At, B0); PG8_MMA(0, 1, At, B1); PG8_BAR; PG8_SCHED;
;             PG8_LDA(At, 0, 1); PG8_STAGE(PG8_SB(0, 0), b2, voffB); PG8_STAGE(PG8_SB(0, 1), b2 + hstep, voffB); PG8_STAGE(PG8_SA(0, 0), a2, voffA);
;             PG8_WAIT_V(8); PG8_WAIT_L(0); PG8_BAR; PG8_MMA(1, 0, At, B0); PG8_MMA(1, 1, At, B1); PG8_BAR; PG8_SCHED;
;             PG8_LDB(B0, 1, 0); PG8_LDB(B1, 1, 1); PG8_SCHED; PG8_LDA(At, 1, 0); PG8_STAGE(PG8_SA(0, 1), a2 + hstep, voffA);
;             PG8_WAIT_V(8); PG8_WAIT_L(0); PG8_BAR; PG8_MMA(0, 0, At, B0); PG8_MMA(0, 1, At, B1); PG8_BAR; PG8_SCHED;
;             PG8_LDA(At, 1, 1); PG8_STAGE(PG8_SB(1, 0), b3, voffB); PG8_STAGE(PG8_SB(1, 1), b3 + hstep, voffB); PG8_STAGE(PG8_SA(1, 0), a3, voffA);
;             PG8_WAIT_V(8); PG8_WAIT_L(0); PG8_BAR; PG8_MMA(1, 0, At, B0); PG8_MMA(1, 1, At, B1); PG8_BAR; PG8_SCHED;
	s_setprio 2
	s_add_i32 s24, s47, s2
	v_lshl_add_u64 v[198:199], v[198:199], 0, s[90:91]
	s_mov_b32 m0, s24
	ds_read_b128 v[186:189], v214 offset:49152
	ds_read_b128 v[190:193], v214 offset:50176
	ds_read_b128 v[194:197], v214 offset:51200
	ds_read_b128 v[216:219], v214 offset:52224
	ds_read_b128 v[220:223], v214 offset:53248
	ds_read_b128 v[224:227], v214 offset:54272
	ds_read_b128 v[228:231], v214 offset:55296
	ds_read_b128 v[232:235], v214 offset:56320
	global_load_lds_dwordx4 v[198:199], off
	v_lshl_add_u64 v[198:199], v[236:237], 0, s[90:91]
	s_add_i32 m0, s24, 0x2000
	s_add_i32 s24, s48, s2
	global_load_lds_dwordx4 v[198:199], off
	v_lshl_add_u64 v[198:199], v[238:239], 0, s[90:91]
	s_mov_b32 m0, s24
	s_nop 0
	global_load_lds_dwordx4 v[198:199], off
	v_lshl_add_u64 v[198:199], v[240:241], 0, s[90:91]
	s_add_i32 m0, s24, 0x2000
	s_nop 0
	global_load_lds_dwordx4 v[198:199], off
	v_lshl_add_u64 v[198:199], v[242:243], 0, s[90:91]
	s_mov_b32 m0, s38
	s_nop 0
	global_load_lds_dwordx4 v[198:199], off
	v_lshl_add_u64 v[198:199], v[244:245], 0, s[90:91]
	s_mov_b32 m0, s39
	s_nop 0
	global_load_lds_dwordx4 v[198:199], off
	s_setprio 0
	s_waitcnt vmcnt(8)
	s_waitcnt lgkmcnt(0)
	s_barrier
	s_setprio 1
	s_waitcnt lgkmcnt(0)
	v_mfma_f32_16x16x32_bf16 v[62:65], v[130:133], v[186:189], v[62:65]
	v_mfma_f32_16x16x32_bf16 v[58:61], v[138:141], v[186:189], v[58:61]
	v_mfma_f32_16x16x32_bf16 v[46:49], v[130:133], v[194:197], v[46:49]
	v_mfma_f32_16x16x32_bf16 v[42:45], v[138:141], v[194:197], v[42:45]
	v_mfma_f32_16x16x32_bf16 v[30:33], v[130:133], v[220:223], v[30:33]
	v_mfma_f32_16x16x32_bf16 v[26:29], v[138:141], v[220:223], v[26:29]
	v_mfma_f32_16x16x32_bf16 v[14:17], v[130:133], v[228:231], v[14:17]
	v_mfma_f32_16x16x32_bf16 v[10:13], v[138:141], v[228:231], v[10:13]
	v_mfma_f32_16x16x32_bf16 v[62:65], v[134:137], v[190:193], v[62:65]
	v_mfma_f32_16x16x32_bf16 v[58:61], v[142:145], v[190:193], v[58:61]
	v_mfma_f32_16x16x32_bf16 v[46:49], v[134:137], v[216:219], v[46:49]
	v_mfma_f32_16x16x32_bf16 v[42:45], v[142:145], v[216:219], v[42:45]
	v_mfma_f32_16x16x32_bf16 v[30:33], v[134:137], v[224:227], v[30:33]
	v_mfma_f32_16x16x32_bf16 v[26:29], v[142:145], v[224:227], v[26:29]
	v_mfma_f32_16x16x32_bf16 v[14:17], v[134:137], v[232:235], v[14:17]
	v_mfma_f32_16x16x32_bf16 v[10:13], v[142:145], v[232:235], v[10:13]
	s_setprio 0
	s_setprio 1
	v_mfma_f32_16x16x32_bf16 v[54:57], v[146:149], v[186:189], v[54:57]
	v_mfma_f32_16x16x32_bf16 v[50:53], v[154:157], v[186:189], v[50:53]
	v_mfma_f32_16x16x32_bf16 v[38:41], v[146:149], v[194:197], v[38:41]
	v_mfma_f32_16x16x32_bf16 v[34:37], v[154:157], v[194:197], v[34:37]
	v_mfma_f32_16x16x32_bf16 v[22:25], v[146:149], v[220:223], v[22:25]
	v_mfma_f32_16x16x32_bf16 v[18:21], v[154:157], v[220:223], v[18:21]
	v_mfma_f32_16x16x32_bf16 v[6:9], v[146:149], v[228:231], v[6:9]
	v_mfma_f32_16x16x32_bf16 v[2:5], v[154:157], v[228:231], v[2:5]
	v_mfma_f32_16x16x32_bf16 v[54:57], v[150:153], v[190:193], v[54:57]
	v_mfma_f32_16x16x32_bf16 v[50:53], v[182:185], v[190:193], v[50:53]
	v_mfma_f32_16x16x32_bf16 v[38:41], v[150:153], v[216:219], v[38:41]
	v_mfma_f32_16x16x32_bf16 v[34:37], v[182:185], v[216:219], v[34:37]
	v_mfma_f32_16x16x32_bf16 v[22:25], v[150:153], v[224:227], v[22:25]
	v_mfma_f32_16x16x32_bf16 v[18:21], v[182:185], v[224:227], v[18:21]
	v_mfma_f32_16x16x32_bf16 v[6:9], v[150:153], v[232:235], v[6:9]
	v_mfma_f32_16x16x32_bf16 v[2:5], v[182:185], v[232:235], v[2:5]
	s_setprio 0
	s_barrier
	s_setprio 2
	s_add_u32 s22, s22, 0x100
	s_addc_u32 s23, s23, 0
	s_add_u32 s44, s44, 0x100
	s_addc_u32 s45, s45, 0
	s_mov_b32 s24, s46
.LBB0_42:
	s_add_i32 s46, s24, 2
	s_add_u32 s47, s22, 0x80
	s_addc_u32 s25, s23, 0
	s_add_i32 s50, 0, 0x10000
	s_cmp_eq_u32 s37, s24
	s_cselect_b32 s25, s17, s25
	s_cselect_b32 s24, s42, s47
	s_cselect_b32 s49, s15, s45
	s_cselect_b32 s48, s43, s44
	s_add_i32 s47, 0, 0x14000
	v_add_u32_e32 v142, s50, v165
	v_add_u32_e32 v182, s47, v165
	ds_read_b128 v[130:133], v142
	ds_read_b128 v[134:137], v142 offset:1024
	ds_read_b128 v[138:141], v142 offset:2048
	ds_read_b128 v[142:145], v142 offset:3072
	ds_read_b128 v[146:149], v182
	ds_read_b128 v[150:153], v182 offset:1024
	ds_read_b128 v[154:157], v182 offset:2048
	ds_read_b128 v[182:185], v182 offset:3072
	v_lshl_add_u64 v[198:199], s[22:23], 0, v[178:179]
	s_add_i32 m0, s29, 0xc000
	ds_read_b128 v[186:189], v214
	ds_read_b128 v[190:193], v214 offset:1024
	ds_read_b128 v[194:197], v214 offset:2048
	ds_read_b128 v[216:219], v214 offset:3072
	ds_read_b128 v[220:223], v214 offset:4096
	ds_read_b128 v[224:227], v214 offset:5120
	ds_read_b128 v[228:231], v214 offset:6144
	ds_read_b128 v[232:235], v214 offset:7168
	global_load_lds_dwordx4 v[198:199], off
	v_lshl_add_u64 v[198:199], s[22:23], 0, v[180:181]
	s_add_i32 m0, s29, 0xe000
	s_nop 0
	global_load_lds_dwordx4 v[198:199], off
	s_setprio 0
	s_waitcnt vmcnt(8)
	s_waitcnt lgkmcnt(0)
	s_barrier
; #define PG8_STAGE(bufoff, gbase, voff) do { _Pragma("unroll") for (int _i = 0; _i < 2; ++_i) \
;         __builtin_amdgcn_global_load_lds((const unsigned*)((const char*)(gbase) + (voff)[_i]), (PG8_LAS unsigned*)(lds + (bufoff) + ldsw + _i * 8192), 16, 0, 0); } while (0)
; #define PG8_LDA(dst, b, h) do { _Pragma("unroll") for (int m = 0; m < 4; ++m) _Pragma("unroll") for (int k = 0; k < 2; ++k) dst[m][k] = *(const PG8_LAS bf16x8*)(lds + PG8_SA(b, h) + aoff + m * 2048 + k * 1024); } while (0)
; #define PG8_LDB(dst, b, h) do { _Pragma("unroll") for (int n = 0; n < 2; ++n) _Pragma("unroll") for (int k = 0; k < 2; ++k) dst[n][k] = *(const PG8_LAS bf16x8*)(lds + PG8_SB(b, h) + boff + n * 2048 + k * 1024); } while (0)
; #define PG8_MMA(ai, bj, At, Bt) do { __builtin_amdgcn_s_setprio(1); _Pragma("unroll") for (int m = 0; m < 4; ++m) _Pragma("unroll") for (int n = 0; n < 2; ++n) _Pragma("unroll") for (int k = 0; k < 2; ++k) \
;         acc[ai][bj][m][n] = __builtin_amdgcn_mfma_f32_16x16x32_bf16(Bt[n][k], At[m][k], acc[ai][bj][m][n], 0, 0, 0); __builtin_amdgcn_s_setprio(0); } while (0)
; #define PG8_WAIT_V(n) asm volatile("s_waitcnt vmcnt(" #n ")" ::: "memory")
; #define PG8_WAIT_L(n) asm volatile("s_waitcnt lgkmcnt(" #n ")" ::: "memory")
; #define PG8_BAR __builtin_amdgcn_s_barrier()
; #define PG8_SCHED __builtin_amdgcn_sched_barrier(0)
; template <class Epi, class Sched, bool ALIGN_EPI = false, bool SP2 = false>
; __device__ __forceinline__ void gemm_phase(PG8_LAS unsigned char* lds, const Gemm g, const Sched& S, const Epi& E) {
;     ...
;             PG8_WAIT_V(8); PG8_WAIT_L(0); PG8_BAR; PG8_MMA(0, 0, At, B0); PG8_MMA(0, 1, At, B1); PG8_BAR; PG8_SCHED;
;             PG8_LDA(At, 0, 1); PG8_STAGE(PG8_SB(0, 0), b2, voffB); PG8_STAGE(PG8_SB(0, 1), b2 + hstep, voffB); PG8_STAGE(PG8_SA(0, 0), a2, voffA);
;             PG8_WAIT_V(8); PG8_WAIT_L(0); PG8_BAR; PG8_MMA(1, 0, At, B0); PG8_MMA(1, 1, At, B1); PG8_BAR; PG8_SCHED;
;             PG8_LDB(B0, 1, 0); PG8_LDB(B1, 1, 1); PG8_SCHED; PG8_LDA(At, 1, 0); PG8_STAGE(PG8_SA(0, 1), a2 + hstep, voffA);
;             PG8_WAIT_V(8); PG8_WAIT_L(0); PG8_BAR; PG8_MMA(0, 0, At, B0); PG8_MMA(0, 1, At, B1); PG8_BAR; PG8_SCHED;
	s_setprio 1
	s_waitcnt lgkmcnt(0)
	v_mfma_f32_16x16x32_bf16 v[126:129], v[130:133], v[186:189], v[126:129]
	v_mfma_f32_16x16x32_bf16 v[122:125], v[138:141], v[186:189], v[122:125]
	v_mfma_f32_16x16x32_bf16 v[110:113], v[130:133], v[194:197], v[110:113]
	v_mfma_f32_16x16x32_bf16 v[106:109], v[138:141], v[194:197], v[106:109]
	v_mfma_f32_16x16x32_bf16 v[94:97], v[130:133], v[220:223], v[94:97]
	v_mfma_f32_16x16x32_bf16 v[90:93], v[138:141], v[220:223], v[90:93]
	v_mfma_f32_16x16x32_bf16 v[78:81], v[130:133], v[228:231], v[78:81]
	v_mfma_f32_16x16x32_bf16 v[74:77], v[138:141], v[228:231], v[74:77]
	v_mfma_f32_16x16x32_bf16 v[126:129], v[134:137], v[190:193], v[126:129]
	v_mfma_f32_16x16x32_bf16 v[122:125], v[142:145], v[190:193], v[122:125]
	v_mfma_f32_16x16x32_bf16 v[110:113], v[134:137], v[216:219], v[110:113]
	v_mfma_f32_16x16x32_bf16 v[106:109], v[142:145], v[216:219], v[106:109]
	v_mfma_f32_16x16x32_bf16 v[94:97], v[134:137], v[224:227], v[94:97]
	v_mfma_f32_16x16x32_bf16 v[90:93], v[142:145], v[224:227], v[90:93]
	v_mfma_f32_16x16x32_bf16 v[78:81], v[134:137], v[232:235], v[78:81]
	v_mfma_f32_16x16x32_bf16 v[74:77], v[142:145], v[232:235], v[74:77]
	s_setprio 0
	s_setprio 1
	v_mfma_f32_16x16x32_bf16 v[118:121], v[146:149], v[186:189], v[118:121]
	v_mfma_f32_16x16x32_bf16 v[114:117], v[154:157], v[186:189], v[114:117]
	v_mfma_f32_16x16x32_bf16 v[102:105], v[146:149], v[194:197], v[102:105]
	v_mfma_f32_16x16x32_bf16 v[98:101], v[154:157], v[194:197], v[98:101]
	v_mfma_f32_16x16x32_bf16 v[86:89], v[146:149], v[220:223], v[86:89]
	v_mfma_f32_16x16x32_bf16 v[82:85], v[154:157], v[220:223], v[82:85]
	v_mfma_f32_16x16x32_bf16 v[70:73], v[146:149], v[228:231], v[70:73]
	v_mfma_f32_16x16x32_bf16 v[66:69], v[154:157], v[228:231], v[66:69]
	v_mfma_f32_16x16x32_bf16 v[118:121], v[150:153], v[190:193], v[118:121]
	v_mfma_f32_16x16x32_bf16 v[114:117], v[182:185], v[190:193], v[114:117]
	v_mfma_f32_16x16x32_bf16 v[102:105], v[150:153], v[216:219], v[102:105]
	v_mfma_f32_16x16x32_bf16 v[98:101], v[182:185], v[216:219], v[98:101]
	v_mfma_f32_16x16x32_bf16 v[86:89], v[150:153], v[224:227], v[86:89]
	v_mfma_f32_16x16x32_bf16 v[82:85], v[182:185], v[224:227], v[82:85]
	v_mfma_f32_16x16x32_bf16 v[70:73], v[150:153], v[232:235], v[70:73]
	v_mfma_f32_16x16x32_bf16 v[66:69], v[182:185], v[232:235], v[66:69]
	s_setprio 0
	s_barrier
	s_setprio 2
	s_add_i32 s50, s50, s2
	v_lshl_add_u64 v[198:199], s[48:49], 0, v[0:1]
	s_mov_b32 m0, s50
	ds_read_b128 v[186:189], v214 offset:16384
	ds_read_b128 v[190:193], v214 offset:17408
	ds_read_b128 v[194:197], v214 offset:18432
	ds_read_b128 v[216:219], v214 offset:19456
	ds_read_b128 v[220:223], v214 offset:20480
	ds_read_b128 v[224:227], v214 offset:21504
	ds_read_b128 v[228:231], v214 offset:22528
	ds_read_b128 v[232:235], v214 offset:23552
	global_load_lds_dwordx4 v[198:199], off
	s_add_i32 m0, s50, 0x2000
	v_lshl_add_u64 v[236:237], s[48:49], 0, v[172:173]
	s_add_u32 s48, s48, s8
	s_addc_u32 s49, s49, 0
	s_add_i32 s47, s47, s2
	global_load_lds_dwordx4 v[236:237], off
	v_lshl_add_u64 v[238:239], s[48:49], 0, v[0:1]
	s_mov_b32 m0, s47
	v_lshl_add_u64 v[240:241], s[48:49], 0, v[172:173]
	global_load_lds_dwordx4 v[238:239], off
	s_add_i32 m0, s47, 0x2000
	v_lshl_add_u64 v[242:243], s[24:25], 0, v[176:177]
	global_load_lds_dwordx4 v[240:241], off
	s_mov_b32 m0, s29
	v_lshl_add_u64 v[244:245], s[24:25], 0, v[174:175]
	global_load_lds_dwordx4 v[242:243], off
	s_mov_b32 m0, s30
	s_nop 0
	global_load_lds_dwordx4 v[244:245], off
	s_setprio 0
	s_waitcnt vmcnt(8)
	s_waitcnt lgkmcnt(0)
	s_barrier
	s_setprio 1
	s_waitcnt lgkmcnt(0)
	v_mfma_f32_16x16x32_bf16 v[62:65], v[130:133], v[186:189], v[62:65]
	v_mfma_f32_16x16x32_bf16 v[58:61], v[138:141], v[186:189], v[58:61]
	v_mfma_f32_16x16x32_bf16 v[46:49], v[130:133], v[194:197], v[46:49]
	v_mfma_f32_16x16x32_bf16 v[42:45], v[138:141], v[194:197], v[42:45]
	v_mfma_f32_16x16x32_bf16 v[30:33], v[130:133], v[220:223], v[30:33]
	v_mfma_f32_16x16x32_bf16 v[26:29], v[138:141], v[220:223], v[26:29]
	v_mfma_f32_16x16x32_bf16 v[14:17], v[130:133], v[228:231], v[14:17]
	v_mfma_f32_16x16x32_bf16 v[10:13], v[138:141], v[228:231], v[10:13]
	v_mfma_f32_16x16x32_bf16 v[62:65], v[134:137], v[190:193], v[62:65]
	v_mfma_f32_16x16x32_bf16 v[58:61], v[142:145], v[190:193], v[58:61]
	v_mfma_f32_16x16x32_bf16 v[46:49], v[134:137], v[216:219], v[46:49]
	v_mfma_f32_16x16x32_bf16 v[42:45], v[142:145], v[216:219], v[42:45]
	v_mfma_f32_16x16x32_bf16 v[30:33], v[134:137], v[224:227], v[30:33]
	v_mfma_f32_16x16x32_bf16 v[26:29], v[142:145], v[224:227], v[26:29]
	v_mfma_f32_16x16x32_bf16 v[14:17], v[134:137], v[232:235], v[14:17]
	v_mfma_f32_16x16x32_bf16 v[10:13], v[142:145], v[232:235], v[10:13]
	s_setprio 0
	s_setprio 1
	v_mfma_f32_16x16x32_bf16 v[54:57], v[146:149], v[186:189], v[54:57]
	v_mfma_f32_16x16x32_bf16 v[50:53], v[154:157], v[186:189], v[50:53]
	v_mfma_f32_16x16x32_bf16 v[38:41], v[146:149], v[194:197], v[38:41]
	v_mfma_f32_16x16x32_bf16 v[34:37], v[154:157], v[194:197], v[34:37]
	v_mfma_f32_16x16x32_bf16 v[22:25], v[146:149], v[220:223], v[22:25]
	v_mfma_f32_16x16x32_bf16 v[18:21], v[154:157], v[220:223], v[18:21]
	v_mfma_f32_16x16x32_bf16 v[6:9], v[146:149], v[228:231], v[6:9]
	v_mfma_f32_16x16x32_bf16 v[2:5], v[154:157], v[228:231], v[2:5]
	v_mfma_f32_16x16x32_bf16 v[54:57], v[150:153], v[190:193], v[54:57]
	v_mfma_f32_16x16x32_bf16 v[50:53], v[182:185], v[190:193], v[50:53]
	v_mfma_f32_16x16x32_bf16 v[38:41], v[150:153], v[216:219], v[38:41]
	v_mfma_f32_16x16x32_bf16 v[34:37], v[182:185], v[216:219], v[34:37]
	v_mfma_f32_16x16x32_bf16 v[22:25], v[150:153], v[224:227], v[22:25]
	v_mfma_f32_16x16x32_bf16 v[18:21], v[182:185], v[224:227], v[18:21]
	v_mfma_f32_16x16x32_bf16 v[6:9], v[150:153], v[232:235], v[6:9]
	v_mfma_f32_16x16x32_bf16 v[2:5], v[182:185], v[232:235], v[2:5]
	s_setprio 0
	s_barrier
; #define PG8_STAGE(bufoff, gbase, voff) do { _Pragma("unroll") for (int _i = 0; _i < 2; ++_i) \
;         __builtin_amdgcn_global_load_lds((const unsigned*)((const char*)(gbase) + (voff)[_i]), (PG8_LAS unsigned*)(lds + (bufoff) + ldsw + _i * 8192), 16, 0, 0); } while (0)
; #define PG8_LDA(dst, b, h) do { _Pragma("unroll") for (int m = 0; m < 4; ++m) _Pragma("unroll") for (int k = 0; k < 2; ++k) dst[m][k] = *(const PG8_LAS bf16x8*)(lds + PG8_SA(b, h) + aoff + m * 2048 + k * 1024); } while (0)
; #define PG8_LDB(dst, b, h) do { _Pragma("unroll") for (int n = 0; n < 2; ++n) _Pragma("unroll") for (int k = 0; k < 2; ++k) dst[n][k] = *(const PG8_LAS bf16x8*)(lds + PG8_SB(b, h) + boff + n * 2048 + k * 1024); } while (0)
; #define PG8_MMA(ai, bj, At, Bt) do { __builtin_amdgcn_s_setprio(1); _Pragma("unroll") for (int m = 0; m < 4; ++m) _Pragma("unroll") for (int n = 0; n < 2; ++n) _Pragma("unroll") for (int k = 0; k < 2; ++k) \
;         acc[ai][bj][m][n] = __builtin_amdgcn_mfma_f32_16x16x32_bf16(Bt[n][k], At[m][k], acc[ai][bj][m][n], 0, 0, 0); __builtin_amdgcn_s_setprio(0); } while (0)
; #define PG8_WAIT_V(n) asm volatile("s_waitcnt vmcnt(" #n ")" ::: "memory")
; #define PG8_WAIT_L(n) asm volatile("s_waitcnt lgkmcnt(" #n ")" ::: "memory")
; #define PG8_BAR __builtin_amdgcn_s_barrier()
; #define PG8_SCHED __builtin_amdgcn_sched_barrier(0)
; template <class Epi, class Sched, bool ALIGN_EPI = false, bool SP2 = false>
; __device__ __forceinline__ void gemm_phase(PG8_LAS unsigned char* lds, const Gemm g, const Sched& S, const Epi& E) {
;     ...
;             PG8_LDB(B0, 1, 0); PG8_LDB(B1, 1, 1); PG8_SCHED; PG8_LDA(At, 1, 0); PG8_STAGE(PG8_SA(0, 1), a2 + hstep, voffA);
;             PG8_WAIT_V(8); PG8_WAIT_L(0); PG8_BAR; PG8_MMA(0, 0, At, B0); PG8_MMA(0, 1, At, B1); PG8_BAR; PG8_SCHED;
;             PG8_LDA(At, 1, 1); PG8_STAGE(PG8_SB(1, 0), b3, voffB); PG8_STAGE(PG8_SB(1, 1), b3 + hstep, voffB); PG8_STAGE(PG8_SA(1, 0), a3, voffA);
;             PG8_WAIT_V(8); PG8_WAIT_L(0); PG8_BAR; PG8_MMA(1, 0, At, B0); PG8_MMA(1, 1, At, B1); PG8_BAR; PG8_SCHED;
	s_setprio 2
	s_add_i32 s47, 0, 0x18000
	s_add_i32 s48, 0, 0x1c000
	v_add_u32_e32 v142, s47, v165
	v_add_u32_e32 v182, s48, v165
	ds_read_b128 v[130:133], v142
	ds_read_b128 v[134:137], v142 offset:1024
	ds_read_b128 v[138:141], v142 offset:2048
	ds_read_b128 v[142:145], v142 offset:3072
	ds_read_b128 v[146:149], v182
	ds_read_b128 v[150:153], v182 offset:1024
	ds_read_b128 v[154:157], v182 offset:2048
	ds_read_b128 v[182:185], v182 offset:3072
	s_add_u32 s24, s24, s8
	s_addc_u32 s25, s25, 0
	s_mov_b32 m0, s31
	v_lshl_add_u64 v[246:247], s[24:25], 0, v[176:177]
	ds_read_b128 v[186:189], v214 offset:32768
	ds_read_b128 v[190:193], v214 offset:33792
	ds_read_b128 v[194:197], v214 offset:34816
	ds_read_b128 v[216:219], v214 offset:35840
	ds_read_b128 v[220:223], v214 offset:36864
	ds_read_b128 v[224:227], v214 offset:37888
	ds_read_b128 v[228:231], v214 offset:38912
	ds_read_b128 v[232:235], v214 offset:39936
	global_load_lds_dwordx4 v[246:247], off
	v_lshl_add_u64 v[246:247], s[24:25], 0, v[174:175]
	s_mov_b32 m0, s34
	s_nop 0
	global_load_lds_dwordx4 v[246:247], off
	s_setprio 0
	s_waitcnt vmcnt(8)
	s_waitcnt lgkmcnt(0)
	s_barrier
	s_setprio 1
	s_waitcnt lgkmcnt(0)
	v_mfma_f32_16x16x32_bf16 v[126:129], v[130:133], v[186:189], v[126:129]
	v_mfma_f32_16x16x32_bf16 v[122:125], v[138:141], v[186:189], v[122:125]
	v_mfma_f32_16x16x32_bf16 v[110:113], v[130:133], v[194:197], v[110:113]
	v_mfma_f32_16x16x32_bf16 v[106:109], v[138:141], v[194:197], v[106:109]
	v_mfma_f32_16x16x32_bf16 v[94:97], v[130:133], v[220:223], v[94:97]
	v_mfma_f32_16x16x32_bf16 v[90:93], v[138:141], v[220:223], v[90:93]
	v_mfma_f32_16x16x32_bf16 v[78:81], v[130:133], v[228:231], v[78:81]
	v_mfma_f32_16x16x32_bf16 v[74:77], v[138:141], v[228:231], v[74:77]
	v_mfma_f32_16x16x32_bf16 v[126:129], v[134:137], v[190:193], v[126:129]
	v_mfma_f32_16x16x32_bf16 v[122:125], v[142:145], v[190:193], v[122:125]
	v_mfma_f32_16x16x32_bf16 v[110:113], v[134:137], v[216:219], v[110:113]
	v_mfma_f32_16x16x32_bf16 v[106:109], v[142:145], v[216:219], v[106:109]
	v_mfma_f32_16x16x32_bf16 v[94:97], v[134:137], v[224:227], v[94:97]
	v_mfma_f32_16x16x32_bf16 v[90:93], v[142:145], v[224:227], v[90:93]
	v_mfma_f32_16x16x32_bf16 v[78:81], v[134:137], v[232:235], v[78:81]
	v_mfma_f32_16x16x32_bf16 v[74:77], v[142:145], v[232:235], v[74:77]
	s_setprio 0
	s_setprio 1
	v_mfma_f32_16x16x32_bf16 v[118:121], v[146:149], v[186:189], v[118:121]
	v_mfma_f32_16x16x32_bf16 v[114:117], v[154:157], v[186:189], v[114:117]
	v_mfma_f32_16x16x32_bf16 v[102:105], v[146:149], v[194:197], v[102:105]
	v_mfma_f32_16x16x32_bf16 v[98:101], v[154:157], v[194:197], v[98:101]
	v_mfma_f32_16x16x32_bf16 v[86:89], v[146:149], v[220:223], v[86:89]
	v_mfma_f32_16x16x32_bf16 v[82:85], v[154:157], v[220:223], v[82:85]
	v_mfma_f32_16x16x32_bf16 v[70:73], v[146:149], v[228:231], v[70:73]
	v_mfma_f32_16x16x32_bf16 v[66:69], v[154:157], v[228:231], v[66:69]
	v_mfma_f32_16x16x32_bf16 v[118:121], v[150:153], v[190:193], v[118:121]
	v_mfma_f32_16x16x32_bf16 v[114:117], v[182:185], v[190:193], v[114:117]
	v_mfma_f32_16x16x32_bf16 v[102:105], v[150:153], v[216:219], v[102:105]
	v_mfma_f32_16x16x32_bf16 v[98:101], v[182:185], v[216:219], v[98:101]
	v_mfma_f32_16x16x32_bf16 v[86:89], v[150:153], v[224:227], v[86:89]
	v_mfma_f32_16x16x32_bf16 v[82:85], v[182:185], v[224:227], v[82:85]
	v_mfma_f32_16x16x32_bf16 v[70:73], v[150:153], v[232:235], v[70:73]
	v_mfma_f32_16x16x32_bf16 v[66:69], v[182:185], v[232:235], v[66:69]
	s_setprio 0
	s_barrier
	s_setprio 2
	s_add_i32 s24, s47, s2
	v_lshl_add_u64 v[198:199], v[198:199], 0, s[90:91]
	s_mov_b32 m0, s24
	ds_read_b128 v[186:189], v214 offset:49152
	ds_read_b128 v[190:193], v214 offset:50176
	ds_read_b128 v[194:197], v214 offset:51200
	ds_read_b128 v[216:219], v214 offset:52224
	ds_read_b128 v[220:223], v214 offset:53248
	ds_read_b128 v[224:227], v214 offset:54272
	ds_read_b128 v[228:231], v214 offset:55296
	ds_read_b128 v[232:235], v214 offset:56320
	global_load_lds_dwordx4 v[198:199], off
	v_lshl_add_u64 v[198:199], v[236:237], 0, s[90:91]
	s_add_i32 m0, s24, 0x2000
	s_add_i32 s24, s48, s2
	global_load_lds_dwordx4 v[198:199], off
	v_lshl_add_u64 v[198:199], v[238:239], 0, s[90:91]
	s_mov_b32 m0, s24
	s_nop 0
	global_load_lds_dwordx4 v[198:199], off
	v_lshl_add_u64 v[198:199], v[240:241], 0, s[90:91]
	s_add_i32 m0, s24, 0x2000
	s_nop 0
	global_load_lds_dwordx4 v[198:199], off
	v_lshl_add_u64 v[198:199], v[242:243], 0, s[90:91]
	s_mov_b32 m0, s38
	s_nop 0
	global_load_lds_dwordx4 v[198:199], off
	v_lshl_add_u64 v[198:199], v[244:245], 0, s[90:91]
	s_mov_b32 m0, s39
	s_nop 0
	global_load_lds_dwordx4 v[198:199], off
	s_setprio 0
	s_waitcnt vmcnt(8)
	s_waitcnt lgkmcnt(0)
	s_barrier
; #define PG8_MMA(ai, bj, At, Bt) do { __builtin_amdgcn_s_setprio(1); _Pragma("unroll") for (int m = 0; m < 4; ++m) _Pragma("unroll") for (int n = 0; n < 2; ++n) _Pragma("unroll") for (int k = 0; k < 2; ++k) \
;         acc[ai][bj][m][n] = __builtin_amdgcn_mfma_f32_16x16x32_bf16(Bt[n][k], At[m][k], acc[ai][bj][m][n], 0, 0, 0); __builtin_amdgcn_s_setprio(0); } while (0)
; #define PG8_WAIT_V(n) asm volatile("s_waitcnt vmcnt(" #n ")" ::: "memory")
; #define PG8_WAIT_L(n) asm volatile("s_waitcnt lgkmcnt(" #n ")" ::: "memory")
; #define PG8_BAR __builtin_amdgcn_s_barrier()
; #define PG8_SCHED __builtin_amdgcn_sched_barrier(0)
; template <class Epi, class Sched, bool ALIGN_EPI = false, bool SP2 = false>
; __device__ __forceinline__ void gemm_phase(PG8_LAS unsigned char* lds, const Gemm g, const Sched& S, const Epi& E) {
;     ...
;             PG8_WAIT_V(8); PG8_WAIT_L(0); PG8_BAR; PG8_MMA(1, 0, At, B0); PG8_MMA(1, 1, At, B1); PG8_BAR; PG8_SCHED;
;     __device__ __forceinline__ void operator()(const f32x4 (&acc)[2][2][4][2], const Unit& u, int wr, int wc, int fr, int fq) const {
;     ...
; #pragma unroll
;         for (int ai = 0; ai < 2; ++ai) {
;             u32x4 xv[4][2];
; #pragma unroll
;             for (int m = 0; m < 4; ++m)
; #pragma unroll
;                 for (int bj = 0; bj < 2; ++bj) xv[m][bj] = *(const u32x4*)(XB + (size_t)(row0 + ai * HALF + m * 16) * 1024 + col0 + bj * HALF);
;             asm volatile("" ::: "memory");
	s_setprio 1
	s_waitcnt lgkmcnt(0)
	v_mfma_f32_16x16x32_bf16 v[62:65], v[130:133], v[186:189], v[62:65]
	v_mfma_f32_16x16x32_bf16 v[58:61], v[138:141], v[186:189], v[58:61]
	v_mfma_f32_16x16x32_bf16 v[46:49], v[130:133], v[194:197], v[46:49]
	v_mfma_f32_16x16x32_bf16 v[42:45], v[138:141], v[194:197], v[42:45]
	v_mfma_f32_16x16x32_bf16 v[30:33], v[130:133], v[220:223], v[30:33]
	v_mfma_f32_16x16x32_bf16 v[26:29], v[138:141], v[220:223], v[26:29]
	v_mfma_f32_16x16x32_bf16 v[14:17], v[130:133], v[228:231], v[14:17]
	v_mfma_f32_16x16x32_bf16 v[10:13], v[138:141], v[228:231], v[10:13]
	v_mfma_f32_16x16x32_bf16 v[62:65], v[134:137], v[190:193], v[62:65]
	v_mfma_f32_16x16x32_bf16 v[58:61], v[142:145], v[190:193], v[58:61]
	v_mfma_f32_16x16x32_bf16 v[46:49], v[134:137], v[216:219], v[46:49]
	v_mfma_f32_16x16x32_bf16 v[42:45], v[142:145], v[216:219], v[42:45]
	v_mfma_f32_16x16x32_bf16 v[30:33], v[134:137], v[224:227], v[30:33]
	v_mfma_f32_16x16x32_bf16 v[26:29], v[142:145], v[224:227], v[26:29]
	v_mfma_f32_16x16x32_bf16 v[14:17], v[134:137], v[232:235], v[14:17]
	v_mfma_f32_16x16x32_bf16 v[10:13], v[142:145], v[232:235], v[10:13]
	s_setprio 0
	s_setprio 1
	v_mfma_f32_16x16x32_bf16 v[54:57], v[146:149], v[186:189], v[54:57]
	v_mfma_f32_16x16x32_bf16 v[50:53], v[154:157], v[186:189], v[50:53]
	v_mfma_f32_16x16x32_bf16 v[38:41], v[146:149], v[194:197], v[38:41]
	v_mfma_f32_16x16x32_bf16 v[34:37], v[154:157], v[194:197], v[34:37]
	v_mfma_f32_16x16x32_bf16 v[22:25], v[146:149], v[220:223], v[22:25]
	v_mfma_f32_16x16x32_bf16 v[18:21], v[154:157], v[220:223], v[18:21]
	v_mfma_f32_16x16x32_bf16 v[6:9], v[146:149], v[228:231], v[6:9]
	v_mfma_f32_16x16x32_bf16 v[2:5], v[154:157], v[228:231], v[2:5]
	v_mfma_f32_16x16x32_bf16 v[54:57], v[150:153], v[190:193], v[54:57]
	v_mfma_f32_16x16x32_bf16 v[50:53], v[182:185], v[190:193], v[50:53]
	v_mfma_f32_16x16x32_bf16 v[38:41], v[150:153], v[216:219], v[38:41]
	v_mfma_f32_16x16x32_bf16 v[34:37], v[182:185], v[216:219], v[34:37]
	v_mfma_f32_16x16x32_bf16 v[22:25], v[150:153], v[224:227], v[22:25]
	v_mfma_f32_16x16x32_bf16 v[18:21], v[182:185], v[224:227], v[18:21]
	v_mfma_f32_16x16x32_bf16 v[6:9], v[150:153], v[232:235], v[6:9]
	v_mfma_f32_16x16x32_bf16 v[2:5], v[182:185], v[232:235], v[2:5]
	s_setprio 0
	s_barrier
	s_setprio 2
	s_add_u32 s22, s22, 0x100
	s_addc_u32 s23, s23, 0
	s_add_u32 s44, s44, 0x100
	s_addc_u32 s45, s45, 0
	s_cmp_ge_u32 s46, s36
	s_mov_b32 s24, s46
	s_cbranch_scc0 .LBB0_42
	v_lshl_or_b32 v198, s9, 8, v213
	v_lshl_add_u32 v217, s41, 8, v158
	v_lshlrev_b32_e32 v246, 1, v198
	v_lshl_add_u32 v246, v217, 11, v246
	v_mov_b32_e32 v247, 0
	s_mov_b32 s22, 0x8000
	s_mov_b32 s23, 0
	s_mov_b32 s88, 0x28000
	v_lshl_add_u64 v[246:247], s[94:95], 0, v[246:247]
	v_xor_b32_e32 v215, 16, v201
	v_xor_b32_e32 v216, 32, v201
	v_mov_b32_e32 v198, v246
	v_mov_b32_e32 v199, v247
	global_load_dwordx4 v[130:133], v[246:247], off
	global_load_dwordx4 v[134:137], v[246:247], off offset:256
	v_lshl_add_u64 v[246:247], v[246:247], 0, s[22:23]
	global_load_dwordx4 v[138:141], v[246:247], off
	global_load_dwordx4 v[142:145], v[246:247], off offset:256
	v_lshl_add_u64 v[246:247], v[246:247], 0, s[22:23]
	global_load_dwordx4 v[146:149], v[246:247], off
	global_load_dwordx4 v[150:153], v[246:247], off offset:256
	v_lshl_add_u64 v[246:247], v[246:247], 0, s[22:23]
	global_load_dwordx4 v[154:157], v[246:247], off
	global_load_dwordx4 v[218:221], v[246:247], off offset:256
	v_lshl_add_u64 v[246:247], v[246:247], 0, s[88:89]
	global_load_dwordx4 v[182:185], v[246:247], off
	global_load_dwordx4 v[186:189], v[246:247], off offset:256
	v_lshl_add_u64 v[246:247], v[246:247], 0, s[22:23]
	global_load_dwordx4 v[190:193], v[246:247], off
	global_load_dwordx4 v[194:197], v[246:247], off offset:256
	v_lshl_add_u64 v[246:247], v[246:247], 0, s[22:23]
	global_load_dwordx4 v[222:225], v[246:247], off
	global_load_dwordx4 v[226:229], v[246:247], off offset:256
	v_lshl_add_u64 v[246:247], v[246:247], 0, s[22:23]
	global_load_dwordx4 v[230:233], v[246:247], off
	global_load_dwordx4 v[234:237], v[246:247], off offset:256
	v_lshlrev_b32_e32 v215, 2, v215
	v_lshlrev_b32_e32 v216, 2, v216
	s_and_b64 vcc, exec, s[12:13]
	s_cbranch_vccz .LBB0_45
	s_barrier

; #define PG8_STAGE(bufoff, gbase, voff) do { _Pragma("unroll") for (int _i = 0; _i < 2; ++_i) \
;         __builtin_amdgcn_global_load_lds((const unsigned*)((const char*)(gbase) + (voff)[_i]), (PG8_LAS unsigned*)(lds + (bufoff) + ldsw + _i * 8192), 16, 0, 0); } while (0)
; #define PG8_LDA(dst, b, h) do { _Pragma("unroll") for (int m = 0; m < 4; ++m) _Pragma("unroll") for (int k = 0; k < 2; ++k) dst[m][k] = *(const PG8_LAS bf16x8*)(lds + PG8_SA(b, h) + aoff + m * 2048 + k * 1024); } while (0)
; #define PG8_LDB(dst, b, h) do { _Pragma("unroll") for (int n = 0; n < 2; ++n) _Pragma("unroll") for (int k = 0; k < 2; ++k) dst[n][k] = *(const PG8_LAS bf16x8*)(lds + PG8_SB(b, h) + boff + n * 2048 + k * 1024); } while (0)
; #define PG8_WAIT_V(n) asm volatile("s_waitcnt vmcnt(" #n ")" ::: "memory")
; #define PG8_WAIT_L(n) asm volatile("s_waitcnt lgkmcnt(" #n ")" ::: "memory")
; #define PG8_BAR __builtin_amdgcn_s_barrier()
; #define PG8_SCHED __builtin_amdgcn_sched_barrier(0)
; template <class Epi, class Sched, bool ALIGN_EPI = false, bool SP2 = false>
; __device__ __forceinline__ void gemm_phase(PG8_LAS unsigned char* lds, const Gemm g, const Sched& S, const Epi& E) {
;     ...
;         const bool has_next = S.next(ui + 1, nxt);
;         const char* nA = has_next ? (const char*)g.A + (size_t)nxt.pm * tstep : cA; const char* nB = has_next ? (const char*)g.Bt + (size_t)nxt.pn * tstep : cB;
;         for (int t = 0; t < nt; t += 2) {
;             const bool last = (t == nt - 2);
;             const char* a1 = cA + (size_t)(t + 1) * kstep;
;             const char* a2 = last ? nA : cA + (size_t)(t + 2) * kstep; const char* b2 = last ? nB : cB + (size_t)(t + 2) * kstep;
;             const char* a3 = a2 + kstep; const char* b3 = b2 + kstep;
;             if (last && has_next) S.a_ready(nxt);
;             if constexpr (SP2) {
;             PG8_LDB(B0, 0, 0); PG8_LDB(B1, 0, 1); PG8_SCHED; PG8_LDA(At, 0, 0); PG8_STAGE(PG8_SA(1, 1), a1 + hstep, voffA);
;             PG8_WAIT_V(8); PG8_WAIT_L(0); PG8_BAR; PG8_MMA(0, 0, At, B0); PG8_MMA(0, 1, At, B1); PG8_BAR; PG8_SCHED;
;             PG8_LDA(At, 0, 1); PG8_STAGE(PG8_SB(0, 0), b2, voffB); PG8_STAGE(PG8_SB(0, 1), b2 + hstep, voffB); PG8_STAGE(PG8_SA(0, 0), a2, voffA);
;             PG8_WAIT_V(8); PG8_WAIT_L(0); PG8_BAR; PG8_MMA(1, 0, At, B0); PG8_MMA(1, 1, At, B1); PG8_BAR; PG8_SCHED;
.LBB0_329:
	s_ashr_i32 s21, s20, 31
	s_lshl_b64 s[22:23], s[20:21], 19
	s_add_u32 s22, s94, s22
	s_addc_u32 s23, s95, s23
	s_and_b64 s[24:25], s[4:5], exec
	s_cselect_b32 s21, s23, s29
	s_cselect_b32 s27, s22, s28
	s_ashr_i32 s19, s18, 31
	s_lshl_b64 s[24:25], s[18:19], 19
	v_readlane_b32 s34, v251, 0
	v_readlane_b32 s35, v251, 1
	s_add_u32 s24, s34, s24
	s_addc_u32 s25, s35, s25
	s_and_b64 s[34:35], s[4:5], exec
	s_cselect_b32 s19, s25, s31
	s_cselect_b32 s60, s24, s30
	s_add_u32 s28, s28, 0x40080
	s_addc_u32 s29, s29, 0
	s_add_u32 s61, s30, 0x100
	s_waitcnt vmcnt(0)
	s_addc_u32 s62, s31, 0
	s_mov_b32 s63, -2
	s_add_u32 s30, s28, 0xfffc0080
	s_addc_u32 s31, s29, -1
	s_add_i32 s64, 0, 0x10000
	s_cmp_eq_u32 s63, 12
	s_cselect_b32 s35, s21, s31
	s_cselect_b32 s34, s27, s30
	v_add_u32_e32 v156, s64, v149
	s_cselect_b32 s31, s19, s62
	s_cselect_b32 s30, s60, s61
	s_add_i32 s66, 0, 0x14000
	ds_read_b128 v[144:147], v156
	ds_read_b128 v[152:155], v156 offset:1024
	ds_read_b128 v[172:175], v156 offset:2048
	ds_read_b128 v[176:179], v156 offset:3072
	v_add_u32_e32 v156, s66, v149
	ds_read_b128 v[180:183], v156
	ds_read_b128 v[184:187], v156 offset:1024
	ds_read_b128 v[188:191], v156 offset:2048
	ds_read_b128 v[192:195], v156 offset:3072
	s_add_i32 m0, s46, 0xc000
	ds_read_b128 v[196:199], v151
	ds_read_b128 v[214:217], v151 offset:1024
	ds_read_b128 v[218:221], v151 offset:2048
	ds_read_b128 v[222:225], v151 offset:3072
	ds_read_b128 v[226:229], v151 offset:4096
	ds_read_b128 v[230:233], v151 offset:5120
	ds_read_b128 v[234:237], v151 offset:6144
	ds_read_b128 v[238:241], v151 offset:7168
	global_load_lds_dwordx4 v140, s[28:29]
	s_add_i32 m0, s46, 0xe000
	s_nop 0
	global_load_lds_dwordx4 v142, s[28:29]
	s_setprio 0
	s_waitcnt vmcnt(8)
	s_waitcnt lgkmcnt(0)
	s_barrier
	s_setprio 1
	s_waitcnt lgkmcnt(0)
	v_mfma_f32_16x16x32_bf16 v[62:65], v[144:147], v[196:199], 0
	v_mfma_f32_16x16x32_bf16 v[58:61], v[172:175], v[196:199], 0
	v_mfma_f32_16x16x32_bf16 v[54:57], v[144:147], v[218:221], 0
	v_mfma_f32_16x16x32_bf16 v[50:53], v[172:175], v[218:221], 0
	v_mfma_f32_16x16x32_bf16 v[46:49], v[144:147], v[226:229], 0
	v_mfma_f32_16x16x32_bf16 v[42:45], v[172:175], v[226:229], 0
	v_mfma_f32_16x16x32_bf16 v[38:41], v[144:147], v[234:237], 0
	v_mfma_f32_16x16x32_bf16 v[34:37], v[172:175], v[234:237], 0
	v_mfma_f32_16x16x32_bf16 v[62:65], v[152:155], v[214:217], v[62:65]
	v_mfma_f32_16x16x32_bf16 v[58:61], v[176:179], v[214:217], v[58:61]
	v_mfma_f32_16x16x32_bf16 v[54:57], v[152:155], v[222:225], v[54:57]
	v_mfma_f32_16x16x32_bf16 v[50:53], v[176:179], v[222:225], v[50:53]
	v_mfma_f32_16x16x32_bf16 v[46:49], v[152:155], v[230:233], v[46:49]
	v_mfma_f32_16x16x32_bf16 v[42:45], v[176:179], v[230:233], v[42:45]
	v_mfma_f32_16x16x32_bf16 v[38:41], v[152:155], v[238:241], v[38:41]
	v_mfma_f32_16x16x32_bf16 v[34:37], v[176:179], v[238:241], v[34:37]
	s_setprio 0
	s_setprio 1
	v_mfma_f32_16x16x32_bf16 v[126:129], v[180:183], v[196:199], 0
	v_mfma_f32_16x16x32_bf16 v[122:125], v[188:191], v[196:199], 0
	v_mfma_f32_16x16x32_bf16 v[118:121], v[180:183], v[218:221], 0
	v_mfma_f32_16x16x32_bf16 v[114:117], v[188:191], v[218:221], 0
	v_mfma_f32_16x16x32_bf16 v[110:113], v[180:183], v[226:229], 0
	v_mfma_f32_16x16x32_bf16 v[106:109], v[188:191], v[226:229], 0
	v_mfma_f32_16x16x32_bf16 v[102:105], v[180:183], v[234:237], 0
	v_mfma_f32_16x16x32_bf16 v[98:101], v[188:191], v[234:237], 0
	v_mfma_f32_16x16x32_bf16 v[126:129], v[184:187], v[214:217], v[126:129]
	v_mfma_f32_16x16x32_bf16 v[122:125], v[192:195], v[214:217], v[122:125]
	v_mfma_f32_16x16x32_bf16 v[118:121], v[184:187], v[222:225], v[118:121]
	v_mfma_f32_16x16x32_bf16 v[114:117], v[192:195], v[222:225], v[114:117]
	v_mfma_f32_16x16x32_bf16 v[110:113], v[184:187], v[230:233], v[110:113]
	v_mfma_f32_16x16x32_bf16 v[106:109], v[192:195], v[230:233], v[106:109]
	v_mfma_f32_16x16x32_bf16 v[102:105], v[184:187], v[238:241], v[102:105]
	v_mfma_f32_16x16x32_bf16 v[98:101], v[192:195], v[238:241], v[98:101]
	s_setprio 0
	s_barrier
	s_setprio 2
	s_add_i32 s64, s64, s2
	s_mov_b32 m0, s64
	ds_read_b128 v[196:199], v151 offset:16384
	ds_read_b128 v[214:217], v151 offset:17408
	ds_read_b128 v[218:221], v151 offset:18432
	ds_read_b128 v[222:225], v151 offset:19456
	ds_read_b128 v[226:229], v151 offset:20480
	ds_read_b128 v[230:233], v151 offset:21504
	ds_read_b128 v[234:237], v151 offset:22528
	ds_read_b128 v[238:241], v151 offset:23552
	global_load_lds_dwordx4 v0, s[30:31]
	s_add_i32 m0, s64, 0x2000
	s_add_u32 s64, s30, 0x40000
	s_addc_u32 s65, s31, 0
	s_add_i32 s66, s66, s2
	global_load_lds_dwordx4 v130, s[30:31]
	s_mov_b32 m0, s66
	s_nop 0
	global_load_lds_dwordx4 v0, s[64:65]
	s_add_i32 m0, s66, 0x2000
	s_nop 0
	global_load_lds_dwordx4 v130, s[64:65]
	s_mov_b32 m0, s46
	s_nop 0
	global_load_lds_dwordx4 v134, s[34:35]
	s_mov_b32 m0, s47
	s_nop 0
	global_load_lds_dwordx4 v132, s[34:35]
	s_setprio 0
	s_waitcnt vmcnt(8)
	s_waitcnt lgkmcnt(0)
	s_barrier
; #define PG8_STAGE(bufoff, gbase, voff) do { _Pragma("unroll") for (int _i = 0; _i < 2; ++_i) \
;         __builtin_amdgcn_global_load_lds((const unsigned*)((const char*)(gbase) + (voff)[_i]), (PG8_LAS unsigned*)(lds + (bufoff) + ldsw + _i * 8192), 16, 0, 0); } while (0)
; #define PG8_LDA(dst, b, h) do { _Pragma("unroll") for (int m = 0; m < 4; ++m) _Pragma("unroll") for (int k = 0; k < 2; ++k) dst[m][k] = *(const PG8_LAS bf16x8*)(lds + PG8_SA(b, h) + aoff + m * 2048 + k * 1024); } while (0)
; #define PG8_LDB(dst, b, h) do { _Pragma("unroll") for (int n = 0; n < 2; ++n) _Pragma("unroll") for (int k = 0; k < 2; ++k) dst[n][k] = *(const PG8_LAS bf16x8*)(lds + PG8_SB(b, h) + boff + n * 2048 + k * 1024); } while (0)
; #define PG8_MMA(ai, bj, At, Bt) do { __builtin_amdgcn_s_setprio(1); _Pragma("unroll") for (int m = 0; m < 4; ++m) _Pragma("unroll") for (int n = 0; n < 2; ++n) _Pragma("unroll") for (int k = 0; k < 2; ++k) \
;         acc[ai][bj][m][n] = __builtin_amdgcn_mfma_f32_16x16x32_bf16(Bt[n][k], At[m][k], acc[ai][bj][m][n], 0, 0, 0); __builtin_amdgcn_s_setprio(0); } while (0)
; #define PG8_WAIT_V(n) asm volatile("s_waitcnt vmcnt(" #n ")" ::: "memory")
; #define PG8_WAIT_L(n) asm volatile("s_waitcnt lgkmcnt(" #n ")" ::: "memory")
; #define PG8_BAR __builtin_amdgcn_s_barrier()
; #define PG8_SCHED __builtin_amdgcn_sched_barrier(0)
; template <class Epi, class Sched, bool ALIGN_EPI = false, bool SP2 = false>
; __device__ __forceinline__ void gemm_phase(PG8_LAS unsigned char* lds, const Gemm g, const Sched& S, const Epi& E) {
;     ...
;             PG8_WAIT_V(8); PG8_WAIT_L(0); PG8_BAR; PG8_MMA(1, 0, At, B0); PG8_MMA(1, 1, At, B1); PG8_BAR; PG8_SCHED;
;             PG8_LDB(B0, 1, 0); PG8_LDB(B1, 1, 1); PG8_SCHED; PG8_LDA(At, 1, 0); PG8_STAGE(PG8_SA(0, 1), a2 + hstep, voffA);
;             PG8_WAIT_V(8); PG8_WAIT_L(0); PG8_BAR; PG8_MMA(0, 0, At, B0); PG8_MMA(0, 1, At, B1); PG8_BAR; PG8_SCHED;
;             PG8_LDA(At, 1, 1); PG8_STAGE(PG8_SB(1, 0), b3, voffB); PG8_STAGE(PG8_SB(1, 1), b3 + hstep, voffB); PG8_STAGE(PG8_SA(1, 0), a3, voffA);
	s_setprio 1
	s_waitcnt lgkmcnt(0)
	v_mfma_f32_16x16x32_bf16 v[30:33], v[144:147], v[196:199], 0
	v_mfma_f32_16x16x32_bf16 v[26:29], v[172:175], v[196:199], 0
	v_mfma_f32_16x16x32_bf16 v[22:25], v[144:147], v[218:221], 0
	v_mfma_f32_16x16x32_bf16 v[18:21], v[172:175], v[218:221], 0
	v_mfma_f32_16x16x32_bf16 v[14:17], v[144:147], v[226:229], 0
	v_mfma_f32_16x16x32_bf16 v[10:13], v[172:175], v[226:229], 0
	v_mfma_f32_16x16x32_bf16 v[6:9], v[144:147], v[234:237], 0
	v_mfma_f32_16x16x32_bf16 v[2:5], v[172:175], v[234:237], 0
	v_mfma_f32_16x16x32_bf16 v[30:33], v[152:155], v[214:217], v[30:33]
	v_mfma_f32_16x16x32_bf16 v[26:29], v[176:179], v[214:217], v[26:29]
	v_mfma_f32_16x16x32_bf16 v[22:25], v[152:155], v[222:225], v[22:25]
	v_mfma_f32_16x16x32_bf16 v[18:21], v[176:179], v[222:225], v[18:21]
	v_mfma_f32_16x16x32_bf16 v[14:17], v[152:155], v[230:233], v[14:17]
	v_mfma_f32_16x16x32_bf16 v[10:13], v[176:179], v[230:233], v[10:13]
	v_mfma_f32_16x16x32_bf16 v[6:9], v[152:155], v[238:241], v[6:9]
	v_mfma_f32_16x16x32_bf16 v[2:5], v[176:179], v[238:241], v[2:5]
	s_setprio 0
	s_setprio 1
	v_mfma_f32_16x16x32_bf16 v[94:97], v[180:183], v[196:199], 0
	v_mfma_f32_16x16x32_bf16 v[90:93], v[188:191], v[196:199], 0
	v_mfma_f32_16x16x32_bf16 v[86:89], v[180:183], v[218:221], 0
	v_mfma_f32_16x16x32_bf16 v[82:85], v[188:191], v[218:221], 0
	v_mfma_f32_16x16x32_bf16 v[78:81], v[180:183], v[226:229], 0
	v_mfma_f32_16x16x32_bf16 v[74:77], v[188:191], v[226:229], 0
	v_mfma_f32_16x16x32_bf16 v[70:73], v[180:183], v[234:237], 0
	v_mfma_f32_16x16x32_bf16 v[66:69], v[188:191], v[234:237], 0
	v_mfma_f32_16x16x32_bf16 v[94:97], v[184:187], v[214:217], v[94:97]
	v_mfma_f32_16x16x32_bf16 v[90:93], v[192:195], v[214:217], v[90:93]
	v_mfma_f32_16x16x32_bf16 v[86:89], v[184:187], v[222:225], v[86:89]
	v_mfma_f32_16x16x32_bf16 v[82:85], v[192:195], v[222:225], v[82:85]
	v_mfma_f32_16x16x32_bf16 v[78:81], v[184:187], v[230:233], v[78:81]
	v_mfma_f32_16x16x32_bf16 v[74:77], v[192:195], v[230:233], v[74:77]
	v_mfma_f32_16x16x32_bf16 v[70:73], v[184:187], v[238:241], v[70:73]
	v_mfma_f32_16x16x32_bf16 v[66:69], v[192:195], v[238:241], v[66:69]
	s_setprio 0
	s_barrier
	s_setprio 2
	s_add_i32 s64, 0, 0x18000
	v_add_u32_e32 v158, s64, v149
	s_add_i32 s65, 0, 0x1c000
	ds_read_b128 v[144:147], v158
	ds_read_b128 v[152:155], v158 offset:1024
	ds_read_b128 v[172:175], v158 offset:2048
	ds_read_b128 v[176:179], v158 offset:3072
	v_add_u32_e32 v158, s65, v149
	ds_read_b128 v[180:183], v158
	ds_read_b128 v[184:187], v158 offset:1024
	ds_read_b128 v[188:191], v158 offset:2048
	ds_read_b128 v[192:195], v158 offset:3072
	s_add_u32 s34, s34, 0x40000
	s_addc_u32 s35, s35, 0
	s_mov_b32 m0, s48
	ds_read_b128 v[196:199], v151 offset:32768
	ds_read_b128 v[214:217], v151 offset:33792
	ds_read_b128 v[218:221], v151 offset:34816
	ds_read_b128 v[222:225], v151 offset:35840
	ds_read_b128 v[226:229], v151 offset:36864
	ds_read_b128 v[230:233], v151 offset:37888
	ds_read_b128 v[234:237], v151 offset:38912
	ds_read_b128 v[238:241], v151 offset:39936
	global_load_lds_dwordx4 v134, s[34:35]
	s_mov_b32 m0, s49
	s_nop 0
	global_load_lds_dwordx4 v132, s[34:35]
	s_setprio 0
	s_waitcnt vmcnt(8)
	s_waitcnt lgkmcnt(0)
	s_barrier
	s_setprio 1
	s_waitcnt lgkmcnt(0)
	v_mfma_f32_16x16x32_bf16 v[62:65], v[144:147], v[196:199], v[62:65]
	v_mfma_f32_16x16x32_bf16 v[58:61], v[172:175], v[196:199], v[58:61]
	v_mfma_f32_16x16x32_bf16 v[54:57], v[144:147], v[218:221], v[54:57]
	v_mfma_f32_16x16x32_bf16 v[50:53], v[172:175], v[218:221], v[50:53]
	v_mfma_f32_16x16x32_bf16 v[46:49], v[144:147], v[226:229], v[46:49]
	v_mfma_f32_16x16x32_bf16 v[42:45], v[172:175], v[226:229], v[42:45]
	v_mfma_f32_16x16x32_bf16 v[38:41], v[144:147], v[234:237], v[38:41]
	v_mfma_f32_16x16x32_bf16 v[34:37], v[172:175], v[234:237], v[34:37]
	v_mfma_f32_16x16x32_bf16 v[62:65], v[152:155], v[214:217], v[62:65]
	v_mfma_f32_16x16x32_bf16 v[58:61], v[176:179], v[214:217], v[58:61]
	v_mfma_f32_16x16x32_bf16 v[54:57], v[152:155], v[222:225], v[54:57]
	v_mfma_f32_16x16x32_bf16 v[50:53], v[176:179], v[222:225], v[50:53]
	v_mfma_f32_16x16x32_bf16 v[46:49], v[152:155], v[230:233], v[46:49]
	v_mfma_f32_16x16x32_bf16 v[42:45], v[176:179], v[230:233], v[42:45]
	v_mfma_f32_16x16x32_bf16 v[38:41], v[152:155], v[238:241], v[38:41]
	v_mfma_f32_16x16x32_bf16 v[34:37], v[176:179], v[238:241], v[34:37]
	s_setprio 0
	s_setprio 1
	v_mfma_f32_16x16x32_bf16 v[126:129], v[180:183], v[196:199], v[126:129]
	v_mfma_f32_16x16x32_bf16 v[122:125], v[188:191], v[196:199], v[122:125]
	v_mfma_f32_16x16x32_bf16 v[118:121], v[180:183], v[218:221], v[118:121]
	v_mfma_f32_16x16x32_bf16 v[114:117], v[188:191], v[218:221], v[114:117]
	v_mfma_f32_16x16x32_bf16 v[110:113], v[180:183], v[226:229], v[110:113]
	v_mfma_f32_16x16x32_bf16 v[106:109], v[188:191], v[226:229], v[106:109]
	v_mfma_f32_16x16x32_bf16 v[102:105], v[180:183], v[234:237], v[102:105]
	v_mfma_f32_16x16x32_bf16 v[98:101], v[188:191], v[234:237], v[98:101]
	v_mfma_f32_16x16x32_bf16 v[126:129], v[184:187], v[214:217], v[126:129]
	v_mfma_f32_16x16x32_bf16 v[122:125], v[192:195], v[214:217], v[122:125]
	v_mfma_f32_16x16x32_bf16 v[118:121], v[184:187], v[222:225], v[118:121]
	v_mfma_f32_16x16x32_bf16 v[114:117], v[192:195], v[222:225], v[114:117]
	v_mfma_f32_16x16x32_bf16 v[110:113], v[184:187], v[230:233], v[110:113]
	v_mfma_f32_16x16x32_bf16 v[106:109], v[192:195], v[230:233], v[106:109]
	v_mfma_f32_16x16x32_bf16 v[102:105], v[184:187], v[238:241], v[102:105]
	v_mfma_f32_16x16x32_bf16 v[98:101], v[192:195], v[238:241], v[98:101]
	s_setprio 0
	s_barrier
; #define PG8_STAGE(bufoff, gbase, voff) do { _Pragma("unroll") for (int _i = 0; _i < 2; ++_i) \
;         __builtin_amdgcn_global_load_lds((const unsigned*)((const char*)(gbase) + (voff)[_i]), (PG8_LAS unsigned*)(lds + (bufoff) + ldsw + _i * 8192), 16, 0, 0); } while (0)
; #define PG8_LDA(dst, b, h) do { _Pragma("unroll") for (int m = 0; m < 4; ++m) _Pragma("unroll") for (int k = 0; k < 2; ++k) dst[m][k] = *(const PG8_LAS bf16x8*)(lds + PG8_SA(b, h) + aoff + m * 2048 + k * 1024); } while (0)
; #define PG8_LDB(dst, b, h) do { _Pragma("unroll") for (int n = 0; n < 2; ++n) _Pragma("unroll") for (int k = 0; k < 2; ++k) dst[n][k] = *(const PG8_LAS bf16x8*)(lds + PG8_SB(b, h) + boff + n * 2048 + k * 1024); } while (0)
; #define PG8_MMA(ai, bj, At, Bt) do { __builtin_amdgcn_s_setprio(1); _Pragma("unroll") for (int m = 0; m < 4; ++m) _Pragma("unroll") for (int n = 0; n < 2; ++n) _Pragma("unroll") for (int k = 0; k < 2; ++k) \
;         acc[ai][bj][m][n] = __builtin_amdgcn_mfma_f32_16x16x32_bf16(Bt[n][k], At[m][k], acc[ai][bj][m][n], 0, 0, 0); __builtin_amdgcn_s_setprio(0); } while (0)
; #define PG8_WAIT_V(n) asm volatile("s_waitcnt vmcnt(" #n ")" ::: "memory")
; template <class Epi, class Sched, bool ALIGN_EPI = false, bool SP2 = false>
; __device__ __forceinline__ void gemm_phase(PG8_LAS unsigned char* lds, const Gemm g, const Sched& S, const Epi& E) {
;     ...
;             PG8_LDB(B0, 0, 0); PG8_LDB(B1, 0, 1); PG8_SCHED; PG8_LDA(At, 0, 0); PG8_STAGE(PG8_SA(1, 1), a1 + hstep, voffA);
;             PG8_WAIT_V(8); PG8_WAIT_L(0); PG8_BAR; PG8_MMA(0, 0, At, B0); PG8_MMA(0, 1, At, B1); PG8_BAR; PG8_SCHED;
;             PG8_LDA(At, 0, 1); PG8_STAGE(PG8_SB(0, 0), b2, voffB); PG8_STAGE(PG8_SB(0, 1), b2 + hstep, voffB); PG8_STAGE(PG8_SA(0, 0), a2, voffA);
;             PG8_WAIT_V(8); PG8_WAIT_L(0); PG8_BAR; PG8_MMA(1, 0, At, B0); PG8_MMA(1, 1, At, B1); PG8_BAR; PG8_SCHED;
;             PG8_LDB(B0, 1, 0); PG8_LDB(B1, 1, 1); PG8_SCHED; PG8_LDA(At, 1, 0); PG8_STAGE(PG8_SA(0, 1), a2 + hstep, voffA);
;             PG8_WAIT_V(8); PG8_WAIT_L(0); PG8_BAR; PG8_MMA(0, 0, At, B0); PG8_MMA(0, 1, At, B1); PG8_BAR; PG8_SCHED;
;             PG8_LDA(At, 1, 1); PG8_STAGE(PG8_SB(1, 0), b3, voffB); PG8_STAGE(PG8_SB(1, 1), b3 + hstep, voffB); PG8_STAGE(PG8_SA(1, 0), a3, voffA);
;             PG8_WAIT_V(8); PG8_WAIT_L(0); PG8_BAR; PG8_MMA(1, 0, At, B0); PG8_MMA(1, 1, At, B1); PG8_BAR; PG8_SCHED;
	s_setprio 2
	s_add_u32 s98, s34, 0xfffc0080
	s_addc_u32 s99, s35, -1
	s_add_i32 s34, s64, s2
	s_add_u32 s100, s30, 0x80
	s_addc_u32 s101, s31, 0
	s_mov_b32 m0, s34
	ds_read_b128 v[196:199], v151 offset:49152
	ds_read_b128 v[214:217], v151 offset:50176
	ds_read_b128 v[218:221], v151 offset:51200
	ds_read_b128 v[222:225], v151 offset:52224
	ds_read_b128 v[226:229], v151 offset:53248
	ds_read_b128 v[230:233], v151 offset:54272
	ds_read_b128 v[234:237], v151 offset:55296
	ds_read_b128 v[238:241], v151 offset:56320
	global_load_lds_dwordx4 v0, s[100:101]
	s_add_i32 m0, s34, 0x2000
	s_add_u32 s30, s30, 0x40080
	s_addc_u32 s31, s31, 0
	s_add_i32 s34, s65, s2
	global_load_lds_dwordx4 v130, s[100:101]
	s_mov_b32 m0, s34
	s_nop 0
	global_load_lds_dwordx4 v0, s[30:31]
	s_add_i32 m0, s34, 0x2000
	s_nop 0
	global_load_lds_dwordx4 v130, s[30:31]
	s_mov_b32 m0, s52
	s_nop 0
	global_load_lds_dwordx4 v134, s[98:99]
	s_mov_b32 m0, s53
	s_nop 0
	global_load_lds_dwordx4 v132, s[98:99]
	s_setprio 0
	s_waitcnt vmcnt(8)
	s_waitcnt lgkmcnt(0)
	s_barrier
	s_setprio 1
	s_waitcnt lgkmcnt(0)
	v_mfma_f32_16x16x32_bf16 v[30:33], v[144:147], v[196:199], v[30:33]
	v_mfma_f32_16x16x32_bf16 v[26:29], v[172:175], v[196:199], v[26:29]
	v_mfma_f32_16x16x32_bf16 v[22:25], v[144:147], v[218:221], v[22:25]
	v_mfma_f32_16x16x32_bf16 v[18:21], v[172:175], v[218:221], v[18:21]
	v_mfma_f32_16x16x32_bf16 v[14:17], v[144:147], v[226:229], v[14:17]
	v_mfma_f32_16x16x32_bf16 v[10:13], v[172:175], v[226:229], v[10:13]
	v_mfma_f32_16x16x32_bf16 v[6:9], v[144:147], v[234:237], v[6:9]
	v_mfma_f32_16x16x32_bf16 v[2:5], v[172:175], v[234:237], v[2:5]
	v_mfma_f32_16x16x32_bf16 v[30:33], v[152:155], v[214:217], v[30:33]
	v_mfma_f32_16x16x32_bf16 v[26:29], v[176:179], v[214:217], v[26:29]
	v_mfma_f32_16x16x32_bf16 v[22:25], v[152:155], v[222:225], v[22:25]
	v_mfma_f32_16x16x32_bf16 v[18:21], v[176:179], v[222:225], v[18:21]
	v_mfma_f32_16x16x32_bf16 v[14:17], v[152:155], v[230:233], v[14:17]
	v_mfma_f32_16x16x32_bf16 v[10:13], v[176:179], v[230:233], v[10:13]
	v_mfma_f32_16x16x32_bf16 v[6:9], v[152:155], v[238:241], v[6:9]
	v_mfma_f32_16x16x32_bf16 v[2:5], v[176:179], v[238:241], v[2:5]
	s_setprio 0
	s_setprio 1
	v_mfma_f32_16x16x32_bf16 v[94:97], v[180:183], v[196:199], v[94:97]
	v_mfma_f32_16x16x32_bf16 v[90:93], v[188:191], v[196:199], v[90:93]
	v_mfma_f32_16x16x32_bf16 v[86:89], v[180:183], v[218:221], v[86:89]
	v_mfma_f32_16x16x32_bf16 v[82:85], v[188:191], v[218:221], v[82:85]
	v_mfma_f32_16x16x32_bf16 v[78:81], v[180:183], v[226:229], v[78:81]
	v_mfma_f32_16x16x32_bf16 v[74:77], v[188:191], v[226:229], v[74:77]
	v_mfma_f32_16x16x32_bf16 v[70:73], v[180:183], v[234:237], v[70:73]
	v_mfma_f32_16x16x32_bf16 v[66:69], v[188:191], v[234:237], v[66:69]
	v_mfma_f32_16x16x32_bf16 v[94:97], v[184:187], v[214:217], v[94:97]
	v_mfma_f32_16x16x32_bf16 v[90:93], v[192:195], v[214:217], v[90:93]
	v_mfma_f32_16x16x32_bf16 v[86:89], v[184:187], v[222:225], v[86:89]
	v_mfma_f32_16x16x32_bf16 v[82:85], v[192:195], v[222:225], v[82:85]
	v_mfma_f32_16x16x32_bf16 v[78:81], v[184:187], v[230:233], v[78:81]
	v_mfma_f32_16x16x32_bf16 v[74:77], v[192:195], v[230:233], v[74:77]
	v_mfma_f32_16x16x32_bf16 v[70:73], v[184:187], v[238:241], v[70:73]
	v_mfma_f32_16x16x32_bf16 v[66:69], v[192:195], v[238:241], v[66:69]
	s_setprio 0
	s_barrier
	s_setprio 2
	s_add_i32 s63, s63, 2
	s_add_u32 s28, s28, 0x100
	s_addc_u32 s29, s29, 0
	s_add_u32 s61, s61, 0x100
	s_addc_u32 s62, s62, 0
.LBB0_330:
	s_add_u32 s30, s28, 0xfffc0080
	s_addc_u32 s31, s29, -1
	s_add_i32 s64, 0, 0x10000
	s_cmp_eq_u32 s63, 12
	s_cselect_b32 s35, s21, s31
	s_cselect_b32 s34, s27, s30
	v_add_u32_e32 v156, s64, v149
	s_cselect_b32 s31, s19, s62
	s_cselect_b32 s30, s60, s61
	s_add_i32 s66, 0, 0x14000
	ds_read_b128 v[144:147], v156
	ds_read_b128 v[152:155], v156 offset:1024
	ds_read_b128 v[172:175], v156 offset:2048
	ds_read_b128 v[176:179], v156 offset:3072
	v_add_u32_e32 v156, s66, v149
	ds_read_b128 v[180:183], v156
	ds_read_b128 v[184:187], v156 offset:1024
	ds_read_b128 v[188:191], v156 offset:2048
	ds_read_b128 v[192:195], v156 offset:3072
	s_add_i32 m0, s46, 0xc000
	ds_read_b128 v[196:199], v151
	ds_read_b128 v[214:217], v151 offset:1024
	ds_read_b128 v[218:221], v151 offset:2048
	ds_read_b128 v[222:225], v151 offset:3072
	ds_read_b128 v[226:229], v151 offset:4096
	ds_read_b128 v[230:233], v151 offset:5120
	ds_read_b128 v[234:237], v151 offset:6144
	ds_read_b128 v[238:241], v151 offset:7168
	global_load_lds_dwordx4 v140, s[28:29]
	s_add_i32 m0, s46, 0xe000
	s_nop 0
	global_load_lds_dwordx4 v142, s[28:29]
	s_setprio 0
	s_waitcnt vmcnt(8)
	s_waitcnt lgkmcnt(0)
	s_barrier
; #define PG8_STAGE(bufoff, gbase, voff) do { _Pragma("unroll") for (int _i = 0; _i < 2; ++_i) \
;         __builtin_amdgcn_global_load_lds((const unsigned*)((const char*)(gbase) + (voff)[_i]), (PG8_LAS unsigned*)(lds + (bufoff) + ldsw + _i * 8192), 16, 0, 0); } while (0)
; #define PG8_LDA(dst, b, h) do { _Pragma("unroll") for (int m = 0; m < 4; ++m) _Pragma("unroll") for (int k = 0; k < 2; ++k) dst[m][k] = *(const PG8_LAS bf16x8*)(lds + PG8_SA(b, h) + aoff + m * 2048 + k * 1024); } while (0)
; #define PG8_LDB(dst, b, h) do { _Pragma("unroll") for (int n = 0; n < 2; ++n) _Pragma("unroll") for (int k = 0; k < 2; ++k) dst[n][k] = *(const PG8_LAS bf16x8*)(lds + PG8_SB(b, h) + boff + n * 2048 + k * 1024); } while (0)
; #define PG8_MMA(ai, bj, At, Bt) do { __builtin_amdgcn_s_setprio(1); _Pragma("unroll") for (int m = 0; m < 4; ++m) _Pragma("unroll") for (int n = 0; n < 2; ++n) _Pragma("unroll") for (int k = 0; k < 2; ++k) \
;         acc[ai][bj][m][n] = __builtin_amdgcn_mfma_f32_16x16x32_bf16(Bt[n][k], At[m][k], acc[ai][bj][m][n], 0, 0, 0); __builtin_amdgcn_s_setprio(0); } while (0)
; #define PG8_WAIT_V(n) asm volatile("s_waitcnt vmcnt(" #n ")" ::: "memory")
; #define PG8_WAIT_L(n) asm volatile("s_waitcnt lgkmcnt(" #n ")" ::: "memory")
; #define PG8_BAR __builtin_amdgcn_s_barrier()
; #define PG8_SCHED __builtin_amdgcn_sched_barrier(0)
; template <class Epi, class Sched, bool ALIGN_EPI = false, bool SP2 = false>
; __device__ __forceinline__ void gemm_phase(PG8_LAS unsigned char* lds, const Gemm g, const Sched& S, const Epi& E) {
;     ...
;             PG8_WAIT_V(8); PG8_WAIT_L(0); PG8_BAR; PG8_MMA(0, 0, At, B0); PG8_MMA(0, 1, At, B1); PG8_BAR; PG8_SCHED;
;             PG8_LDA(At, 0, 1); PG8_STAGE(PG8_SB(0, 0), b2, voffB); PG8_STAGE(PG8_SB(0, 1), b2 + hstep, voffB); PG8_STAGE(PG8_SA(0, 0), a2, voffA);
;             PG8_WAIT_V(8); PG8_WAIT_L(0); PG8_BAR; PG8_MMA(1, 0, At, B0); PG8_MMA(1, 1, At, B1); PG8_BAR; PG8_SCHED;
;             PG8_LDB(B0, 1, 0); PG8_LDB(B1, 1, 1); PG8_SCHED; PG8_LDA(At, 1, 0); PG8_STAGE(PG8_SA(0, 1), a2 + hstep, voffA);
;             PG8_WAIT_V(8); PG8_WAIT_L(0); PG8_BAR; PG8_MMA(0, 0, At, B0); PG8_MMA(0, 1, At, B1); PG8_BAR; PG8_SCHED;
	s_setprio 1
	s_waitcnt lgkmcnt(0)
	v_mfma_f32_16x16x32_bf16 v[62:65], v[144:147], v[196:199], v[62:65]
	v_mfma_f32_16x16x32_bf16 v[58:61], v[172:175], v[196:199], v[58:61]
	v_mfma_f32_16x16x32_bf16 v[54:57], v[144:147], v[218:221], v[54:57]
	v_mfma_f32_16x16x32_bf16 v[50:53], v[172:175], v[218:221], v[50:53]
	v_mfma_f32_16x16x32_bf16 v[46:49], v[144:147], v[226:229], v[46:49]
	v_mfma_f32_16x16x32_bf16 v[42:45], v[172:175], v[226:229], v[42:45]
	v_mfma_f32_16x16x32_bf16 v[38:41], v[144:147], v[234:237], v[38:41]
	v_mfma_f32_16x16x32_bf16 v[34:37], v[172:175], v[234:237], v[34:37]
	v_mfma_f32_16x16x32_bf16 v[62:65], v[152:155], v[214:217], v[62:65]
	v_mfma_f32_16x16x32_bf16 v[58:61], v[176:179], v[214:217], v[58:61]
	v_mfma_f32_16x16x32_bf16 v[54:57], v[152:155], v[222:225], v[54:57]
	v_mfma_f32_16x16x32_bf16 v[50:53], v[176:179], v[222:225], v[50:53]
	v_mfma_f32_16x16x32_bf16 v[46:49], v[152:155], v[230:233], v[46:49]
	v_mfma_f32_16x16x32_bf16 v[42:45], v[176:179], v[230:233], v[42:45]
	v_mfma_f32_16x16x32_bf16 v[38:41], v[152:155], v[238:241], v[38:41]
	v_mfma_f32_16x16x32_bf16 v[34:37], v[176:179], v[238:241], v[34:37]
	s_setprio 0
	s_setprio 1
	v_mfma_f32_16x16x32_bf16 v[126:129], v[180:183], v[196:199], v[126:129]
	v_mfma_f32_16x16x32_bf16 v[122:125], v[188:191], v[196:199], v[122:125]
	v_mfma_f32_16x16x32_bf16 v[118:121], v[180:183], v[218:221], v[118:121]
	v_mfma_f32_16x16x32_bf16 v[114:117], v[188:191], v[218:221], v[114:117]
	v_mfma_f32_16x16x32_bf16 v[110:113], v[180:183], v[226:229], v[110:113]
	v_mfma_f32_16x16x32_bf16 v[106:109], v[188:191], v[226:229], v[106:109]
	v_mfma_f32_16x16x32_bf16 v[102:105], v[180:183], v[234:237], v[102:105]
	v_mfma_f32_16x16x32_bf16 v[98:101], v[188:191], v[234:237], v[98:101]
	v_mfma_f32_16x16x32_bf16 v[126:129], v[184:187], v[214:217], v[126:129]
	v_mfma_f32_16x16x32_bf16 v[122:125], v[192:195], v[214:217], v[122:125]
	v_mfma_f32_16x16x32_bf16 v[118:121], v[184:187], v[222:225], v[118:121]
	v_mfma_f32_16x16x32_bf16 v[114:117], v[192:195], v[222:225], v[114:117]
	v_mfma_f32_16x16x32_bf16 v[110:113], v[184:187], v[230:233], v[110:113]
	v_mfma_f32_16x16x32_bf16 v[106:109], v[192:195], v[230:233], v[106:109]
	v_mfma_f32_16x16x32_bf16 v[102:105], v[184:187], v[238:241], v[102:105]
	v_mfma_f32_16x16x32_bf16 v[98:101], v[192:195], v[238:241], v[98:101]
	s_setprio 0
	s_barrier
	s_setprio 2
	s_add_i32 s64, s64, s2
	s_mov_b32 m0, s64
	ds_read_b128 v[196:199], v151 offset:16384
	ds_read_b128 v[214:217], v151 offset:17408
	ds_read_b128 v[218:221], v151 offset:18432
	ds_read_b128 v[222:225], v151 offset:19456
	ds_read_b128 v[226:229], v151 offset:20480
	ds_read_b128 v[230:233], v151 offset:21504
	ds_read_b128 v[234:237], v151 offset:22528
	ds_read_b128 v[238:241], v151 offset:23552
	global_load_lds_dwordx4 v0, s[30:31]
	s_add_i32 m0, s64, 0x2000
	s_add_u32 s64, s30, 0x40000
	s_addc_u32 s65, s31, 0
	s_add_i32 s66, s66, s2
	global_load_lds_dwordx4 v130, s[30:31]
	s_mov_b32 m0, s66
	s_nop 0
	global_load_lds_dwordx4 v0, s[64:65]
	s_add_i32 m0, s66, 0x2000
	s_nop 0
	global_load_lds_dwordx4 v130, s[64:65]
	s_mov_b32 m0, s46
	s_nop 0
	global_load_lds_dwordx4 v134, s[34:35]
	s_mov_b32 m0, s47
	s_nop 0
	global_load_lds_dwordx4 v132, s[34:35]
	s_setprio 0
	s_waitcnt vmcnt(8)
	s_waitcnt lgkmcnt(0)
	s_barrier
	s_setprio 1
	s_waitcnt lgkmcnt(0)
	v_mfma_f32_16x16x32_bf16 v[30:33], v[144:147], v[196:199], v[30:33]
	v_mfma_f32_16x16x32_bf16 v[26:29], v[172:175], v[196:199], v[26:29]
	v_mfma_f32_16x16x32_bf16 v[22:25], v[144:147], v[218:221], v[22:25]
	v_mfma_f32_16x16x32_bf16 v[18:21], v[172:175], v[218:221], v[18:21]
	v_mfma_f32_16x16x32_bf16 v[14:17], v[144:147], v[226:229], v[14:17]
	v_mfma_f32_16x16x32_bf16 v[10:13], v[172:175], v[226:229], v[10:13]
	v_mfma_f32_16x16x32_bf16 v[6:9], v[144:147], v[234:237], v[6:9]
	v_mfma_f32_16x16x32_bf16 v[2:5], v[172:175], v[234:237], v[2:5]
	v_mfma_f32_16x16x32_bf16 v[30:33], v[152:155], v[214:217], v[30:33]
	v_mfma_f32_16x16x32_bf16 v[26:29], v[176:179], v[214:217], v[26:29]
	v_mfma_f32_16x16x32_bf16 v[22:25], v[152:155], v[222:225], v[22:25]
	v_mfma_f32_16x16x32_bf16 v[18:21], v[176:179], v[222:225], v[18:21]
	v_mfma_f32_16x16x32_bf16 v[14:17], v[152:155], v[230:233], v[14:17]
	v_mfma_f32_16x16x32_bf16 v[10:13], v[176:179], v[230:233], v[10:13]
	v_mfma_f32_16x16x32_bf16 v[6:9], v[152:155], v[238:241], v[6:9]
	v_mfma_f32_16x16x32_bf16 v[2:5], v[176:179], v[238:241], v[2:5]
	s_setprio 0
	s_setprio 1
	v_mfma_f32_16x16x32_bf16 v[94:97], v[180:183], v[196:199], v[94:97]
	v_mfma_f32_16x16x32_bf16 v[90:93], v[188:191], v[196:199], v[90:93]
	v_mfma_f32_16x16x32_bf16 v[86:89], v[180:183], v[218:221], v[86:89]
	v_mfma_f32_16x16x32_bf16 v[82:85], v[188:191], v[218:221], v[82:85]
	v_mfma_f32_16x16x32_bf16 v[78:81], v[180:183], v[226:229], v[78:81]
	v_mfma_f32_16x16x32_bf16 v[74:77], v[188:191], v[226:229], v[74:77]
	v_mfma_f32_16x16x32_bf16 v[70:73], v[180:183], v[234:237], v[70:73]
	v_mfma_f32_16x16x32_bf16 v[66:69], v[188:191], v[234:237], v[66:69]
	v_mfma_f32_16x16x32_bf16 v[94:97], v[184:187], v[214:217], v[94:97]
	v_mfma_f32_16x16x32_bf16 v[90:93], v[192:195], v[214:217], v[90:93]
	v_mfma_f32_16x16x32_bf16 v[86:89], v[184:187], v[222:225], v[86:89]
	v_mfma_f32_16x16x32_bf16 v[82:85], v[192:195], v[222:225], v[82:85]
	v_mfma_f32_16x16x32_bf16 v[78:81], v[184:187], v[230:233], v[78:81]
	v_mfma_f32_16x16x32_bf16 v[74:77], v[192:195], v[230:233], v[74:77]
	v_mfma_f32_16x16x32_bf16 v[70:73], v[184:187], v[238:241], v[70:73]
	v_mfma_f32_16x16x32_bf16 v[66:69], v[192:195], v[238:241], v[66:69]
	s_setprio 0
	s_barrier
; #define PG8_STAGE(bufoff, gbase, voff) do { _Pragma("unroll") for (int _i = 0; _i < 2; ++_i) \
;         __builtin_amdgcn_global_load_lds((const unsigned*)((const char*)(gbase) + (voff)[_i]), (PG8_LAS unsigned*)(lds + (bufoff) + ldsw + _i * 8192), 16, 0, 0); } while (0)
; #define PG8_LDA(dst, b, h) do { _Pragma("unroll") for (int m = 0; m < 4; ++m) _Pragma("unroll") for (int k = 0; k < 2; ++k) dst[m][k] = *(const PG8_LAS bf16x8*)(lds + PG8_SA(b, h) + aoff + m * 2048 + k * 1024); } while (0)
; #define PG8_LDB(dst, b, h) do { _Pragma("unroll") for (int n = 0; n < 2; ++n) _Pragma("unroll") for (int k = 0; k < 2; ++k) dst[n][k] = *(const PG8_LAS bf16x8*)(lds + PG8_SB(b, h) + boff + n * 2048 + k * 1024); } while (0)
; #define PG8_MMA(ai, bj, At, Bt) do { __builtin_amdgcn_s_setprio(1); _Pragma("unroll") for (int m = 0; m < 4; ++m) _Pragma("unroll") for (int n = 0; n < 2; ++n) _Pragma("unroll") for (int k = 0; k < 2; ++k) \
;         acc[ai][bj][m][n] = __builtin_amdgcn_mfma_f32_16x16x32_bf16(Bt[n][k], At[m][k], acc[ai][bj][m][n], 0, 0, 0); __builtin_amdgcn_s_setprio(0); } while (0)
; #define PG8_WAIT_V(n) asm volatile("s_waitcnt vmcnt(" #n ")" ::: "memory")
; #define PG8_WAIT_L(n) asm volatile("s_waitcnt lgkmcnt(" #n ")" ::: "memory")
; #define PG8_BAR __builtin_amdgcn_s_barrier()
; #define PG8_SCHED __builtin_amdgcn_sched_barrier(0)
; template <class Epi, class Sched, bool ALIGN_EPI = false, bool SP2 = false>
; __device__ __forceinline__ void gemm_phase(PG8_LAS unsigned char* lds, const Gemm g, const Sched& S, const Epi& E) {
;     ...
;             PG8_LDB(B0, 1, 0); PG8_LDB(B1, 1, 1); PG8_SCHED; PG8_LDA(At, 1, 0); PG8_STAGE(PG8_SA(0, 1), a2 + hstep, voffA);
;             PG8_WAIT_V(8); PG8_WAIT_L(0); PG8_BAR; PG8_MMA(0, 0, At, B0); PG8_MMA(0, 1, At, B1); PG8_BAR; PG8_SCHED;
;             PG8_LDA(At, 1, 1); PG8_STAGE(PG8_SB(1, 0), b3, voffB); PG8_STAGE(PG8_SB(1, 1), b3 + hstep, voffB); PG8_STAGE(PG8_SA(1, 0), a3, voffA);
;             PG8_WAIT_V(8); PG8_WAIT_L(0); PG8_BAR; PG8_MMA(1, 0, At, B0); PG8_MMA(1, 1, At, B1); PG8_BAR; PG8_SCHED;
;     ...
;         if constexpr (ALIGN_EPI) { if (wr == 0) PG8_BAR; }
	s_setprio 2
	s_add_i32 s64, 0, 0x18000
	v_add_u32_e32 v158, s64, v149
	s_add_i32 s65, 0, 0x1c000
	ds_read_b128 v[144:147], v158
	ds_read_b128 v[152:155], v158 offset:1024
	ds_read_b128 v[172:175], v158 offset:2048
	ds_read_b128 v[176:179], v158 offset:3072
	v_add_u32_e32 v158, s65, v149
	ds_read_b128 v[180:183], v158
	ds_read_b128 v[184:187], v158 offset:1024
	ds_read_b128 v[188:191], v158 offset:2048
	ds_read_b128 v[192:195], v158 offset:3072
	s_add_u32 s34, s34, 0x40000
	s_addc_u32 s35, s35, 0
	s_mov_b32 m0, s48
	ds_read_b128 v[196:199], v151 offset:32768
	ds_read_b128 v[214:217], v151 offset:33792
	ds_read_b128 v[218:221], v151 offset:34816
	ds_read_b128 v[222:225], v151 offset:35840
	ds_read_b128 v[226:229], v151 offset:36864
	ds_read_b128 v[230:233], v151 offset:37888
	ds_read_b128 v[234:237], v151 offset:38912
	ds_read_b128 v[238:241], v151 offset:39936
	global_load_lds_dwordx4 v134, s[34:35]
	s_mov_b32 m0, s49
	s_nop 0
	global_load_lds_dwordx4 v132, s[34:35]
	s_setprio 0
	s_waitcnt vmcnt(8)
	s_waitcnt lgkmcnt(0)
	s_barrier
	s_setprio 1
	s_waitcnt lgkmcnt(0)
	v_mfma_f32_16x16x32_bf16 v[62:65], v[144:147], v[196:199], v[62:65]
	v_mfma_f32_16x16x32_bf16 v[58:61], v[172:175], v[196:199], v[58:61]
	v_mfma_f32_16x16x32_bf16 v[54:57], v[144:147], v[218:221], v[54:57]
	v_mfma_f32_16x16x32_bf16 v[50:53], v[172:175], v[218:221], v[50:53]
	v_mfma_f32_16x16x32_bf16 v[46:49], v[144:147], v[226:229], v[46:49]
	v_mfma_f32_16x16x32_bf16 v[42:45], v[172:175], v[226:229], v[42:45]
	v_mfma_f32_16x16x32_bf16 v[38:41], v[144:147], v[234:237], v[38:41]
	v_mfma_f32_16x16x32_bf16 v[34:37], v[172:175], v[234:237], v[34:37]
	v_mfma_f32_16x16x32_bf16 v[62:65], v[152:155], v[214:217], v[62:65]
	v_mfma_f32_16x16x32_bf16 v[58:61], v[176:179], v[214:217], v[58:61]
	v_mfma_f32_16x16x32_bf16 v[54:57], v[152:155], v[222:225], v[54:57]
	v_mfma_f32_16x16x32_bf16 v[50:53], v[176:179], v[222:225], v[50:53]
	v_mfma_f32_16x16x32_bf16 v[46:49], v[152:155], v[230:233], v[46:49]
	v_mfma_f32_16x16x32_bf16 v[42:45], v[176:179], v[230:233], v[42:45]
	v_mfma_f32_16x16x32_bf16 v[38:41], v[152:155], v[238:241], v[38:41]
	v_mfma_f32_16x16x32_bf16 v[34:37], v[176:179], v[238:241], v[34:37]
	s_setprio 0
	s_setprio 1
	v_mfma_f32_16x16x32_bf16 v[126:129], v[180:183], v[196:199], v[126:129]
	v_mfma_f32_16x16x32_bf16 v[122:125], v[188:191], v[196:199], v[122:125]
	v_mfma_f32_16x16x32_bf16 v[118:121], v[180:183], v[218:221], v[118:121]
	v_mfma_f32_16x16x32_bf16 v[114:117], v[188:191], v[218:221], v[114:117]
	v_mfma_f32_16x16x32_bf16 v[110:113], v[180:183], v[226:229], v[110:113]
	v_mfma_f32_16x16x32_bf16 v[106:109], v[188:191], v[226:229], v[106:109]
	v_mfma_f32_16x16x32_bf16 v[102:105], v[180:183], v[234:237], v[102:105]
	v_mfma_f32_16x16x32_bf16 v[98:101], v[188:191], v[234:237], v[98:101]
	v_mfma_f32_16x16x32_bf16 v[126:129], v[184:187], v[214:217], v[126:129]
	v_mfma_f32_16x16x32_bf16 v[122:125], v[192:195], v[214:217], v[122:125]
	v_mfma_f32_16x16x32_bf16 v[118:121], v[184:187], v[222:225], v[118:121]
	v_mfma_f32_16x16x32_bf16 v[114:117], v[192:195], v[222:225], v[114:117]
	v_mfma_f32_16x16x32_bf16 v[110:113], v[184:187], v[230:233], v[110:113]
	v_mfma_f32_16x16x32_bf16 v[106:109], v[192:195], v[230:233], v[106:109]
	v_mfma_f32_16x16x32_bf16 v[102:105], v[184:187], v[238:241], v[102:105]
	v_mfma_f32_16x16x32_bf16 v[98:101], v[192:195], v[238:241], v[98:101]
	s_setprio 0
	s_barrier
	s_setprio 2
	s_add_u32 s98, s34, 0xfffc0080
	s_addc_u32 s99, s35, -1
	s_add_i32 s34, s64, s2
	s_add_u32 s100, s30, 0x80
	s_addc_u32 s101, s31, 0
	s_mov_b32 m0, s34
	ds_read_b128 v[196:199], v151 offset:49152
	ds_read_b128 v[214:217], v151 offset:50176
	ds_read_b128 v[218:221], v151 offset:51200
	ds_read_b128 v[222:225], v151 offset:52224
	ds_read_b128 v[226:229], v151 offset:53248
	ds_read_b128 v[230:233], v151 offset:54272
	ds_read_b128 v[234:237], v151 offset:55296
	ds_read_b128 v[238:241], v151 offset:56320
	global_load_lds_dwordx4 v0, s[100:101]
	s_add_i32 m0, s34, 0x2000
	s_add_u32 s30, s30, 0x40080
	s_addc_u32 s31, s31, 0
	s_add_i32 s34, s65, s2
	global_load_lds_dwordx4 v130, s[100:101]
	s_mov_b32 m0, s34
	s_nop 0
	global_load_lds_dwordx4 v0, s[30:31]
	s_add_i32 m0, s34, 0x2000
	s_nop 0
	global_load_lds_dwordx4 v130, s[30:31]
	s_mov_b32 m0, s52
	s_nop 0
	global_load_lds_dwordx4 v134, s[98:99]
	s_mov_b32 m0, s53
	s_nop 0
	global_load_lds_dwordx4 v132, s[98:99]
	s_setprio 0
	s_waitcnt vmcnt(8)
	s_waitcnt lgkmcnt(0)
	s_barrier
	s_setprio 1
	s_waitcnt lgkmcnt(0)
	v_mfma_f32_16x16x32_bf16 v[30:33], v[144:147], v[196:199], v[30:33]
	v_mfma_f32_16x16x32_bf16 v[26:29], v[172:175], v[196:199], v[26:29]
	v_mfma_f32_16x16x32_bf16 v[22:25], v[144:147], v[218:221], v[22:25]
	v_mfma_f32_16x16x32_bf16 v[18:21], v[172:175], v[218:221], v[18:21]
	v_mfma_f32_16x16x32_bf16 v[14:17], v[144:147], v[226:229], v[14:17]
	v_mfma_f32_16x16x32_bf16 v[10:13], v[172:175], v[226:229], v[10:13]
	v_mfma_f32_16x16x32_bf16 v[6:9], v[144:147], v[234:237], v[6:9]
	v_mfma_f32_16x16x32_bf16 v[2:5], v[172:175], v[234:237], v[2:5]
	v_mfma_f32_16x16x32_bf16 v[30:33], v[152:155], v[214:217], v[30:33]
	v_mfma_f32_16x16x32_bf16 v[26:29], v[176:179], v[214:217], v[26:29]
	v_mfma_f32_16x16x32_bf16 v[22:25], v[152:155], v[222:225], v[22:25]
	v_mfma_f32_16x16x32_bf16 v[18:21], v[176:179], v[222:225], v[18:21]
	v_mfma_f32_16x16x32_bf16 v[14:17], v[152:155], v[230:233], v[14:17]
	v_mfma_f32_16x16x32_bf16 v[10:13], v[176:179], v[230:233], v[10:13]
	v_mfma_f32_16x16x32_bf16 v[6:9], v[152:155], v[238:241], v[6:9]
	v_mfma_f32_16x16x32_bf16 v[2:5], v[176:179], v[238:241], v[2:5]
	s_setprio 0
	s_setprio 1
	v_mfma_f32_16x16x32_bf16 v[94:97], v[180:183], v[196:199], v[94:97]
	v_mfma_f32_16x16x32_bf16 v[90:93], v[188:191], v[196:199], v[90:93]
	v_mfma_f32_16x16x32_bf16 v[86:89], v[180:183], v[218:221], v[86:89]
	v_mfma_f32_16x16x32_bf16 v[82:85], v[188:191], v[218:221], v[82:85]
	v_mfma_f32_16x16x32_bf16 v[78:81], v[180:183], v[226:229], v[78:81]
	v_mfma_f32_16x16x32_bf16 v[74:77], v[188:191], v[226:229], v[74:77]
	v_mfma_f32_16x16x32_bf16 v[70:73], v[180:183], v[234:237], v[70:73]
	v_mfma_f32_16x16x32_bf16 v[66:69], v[188:191], v[234:237], v[66:69]
	v_mfma_f32_16x16x32_bf16 v[94:97], v[184:187], v[214:217], v[94:97]
	v_mfma_f32_16x16x32_bf16 v[90:93], v[192:195], v[214:217], v[90:93]
	v_mfma_f32_16x16x32_bf16 v[86:89], v[184:187], v[222:225], v[86:89]
	v_mfma_f32_16x16x32_bf16 v[82:85], v[192:195], v[222:225], v[82:85]
	v_mfma_f32_16x16x32_bf16 v[78:81], v[184:187], v[230:233], v[78:81]
	v_mfma_f32_16x16x32_bf16 v[74:77], v[192:195], v[230:233], v[74:77]
	v_mfma_f32_16x16x32_bf16 v[70:73], v[184:187], v[238:241], v[70:73]
	v_mfma_f32_16x16x32_bf16 v[66:69], v[192:195], v[238:241], v[66:69]
	s_setprio 0
	s_barrier
	s_setprio 2
	s_add_i32 s63, s63, 2
	s_add_u32 s28, s28, 0x100
	s_addc_u32 s29, s29, 0
	s_add_u32 s61, s61, 0x100
	s_addc_u32 s62, s62, 0
	s_cmp_gt_u32 s63, 13
	s_cbranch_scc0 .LBB0_330
	s_and_b64 vcc, exec, s[14:15]
	s_cbranch_vccz .LBB0_333
	s_barrier

; #define PG8_STAGE(bufoff, gbase, voff) do { _Pragma("unroll") for (int _i = 0; _i < 2; ++_i) \
;         __builtin_amdgcn_global_load_lds((const unsigned*)((const char*)(gbase) + (voff)[_i]), (PG8_LAS unsigned*)(lds + (bufoff) + ldsw + _i * 8192), 16, 0, 0); } while (0)
; #define PG8_LDA(dst, b, h) do { _Pragma("unroll") for (int m = 0; m < 4; ++m) _Pragma("unroll") for (int k = 0; k < 2; ++k) dst[m][k] = *(const PG8_LAS bf16x8*)(lds + PG8_SA(b, h) + aoff + m * 2048 + k * 1024); } while (0)
; #define PG8_LDB(dst, b, h) do { _Pragma("unroll") for (int n = 0; n < 2; ++n) _Pragma("unroll") for (int k = 0; k < 2; ++k) dst[n][k] = *(const PG8_LAS bf16x8*)(lds + PG8_SB(b, h) + boff + n * 2048 + k * 1024); } while (0)
; #define PG8_MMA(ai, bj, At, Bt) do { __builtin_amdgcn_s_setprio(1); _Pragma("unroll") for (int m = 0; m < 4; ++m) _Pragma("unroll") for (int n = 0; n < 2; ++n) _Pragma("unroll") for (int k = 0; k < 2; ++k) \
;         acc[ai][bj][m][n] = __builtin_amdgcn_mfma_f32_16x16x32_bf16(Bt[n][k], At[m][k], acc[ai][bj][m][n], 0, 0, 0); __builtin_amdgcn_s_setprio(0); } while (0)
; #define PG8_WAIT_V(n) asm volatile("s_waitcnt vmcnt(" #n ")" ::: "memory")
; #define PG8_BAR __builtin_amdgcn_s_barrier()
; template <class Epi, class Sched, bool ALIGN_EPI = false, bool SP2 = false>
; __device__ __forceinline__ void gemm_phase(PG8_LAS unsigned char* lds, const Gemm g, const Sched& S, const Epi& E) {
;     ...
;         for (int t = 0; t < nt; t += 2) {
;             const bool last = (t == nt - 2);
;             const char* a1 = cA + (size_t)(t + 1) * kstep;
;             const char* a2 = last ? nA : cA + (size_t)(t + 2) * kstep; const char* b2 = last ? nB : cB + (size_t)(t + 2) * kstep;
;             const char* a3 = a2 + kstep; const char* b3 = b2 + kstep;
;             if (last && has_next) S.a_ready(nxt);
;             if constexpr (SP2) {
;             PG8_LDB(B0, 0, 0); PG8_LDB(B1, 0, 1); PG8_SCHED; PG8_LDA(At, 0, 0); PG8_STAGE(PG8_SA(1, 1), a1 + hstep, voffA);
;             PG8_WAIT_V(8); PG8_WAIT_L(0); PG8_BAR; PG8_MMA(0, 0, At, B0); PG8_MMA(0, 1, At, B1); PG8_BAR; PG8_SCHED;
;             PG8_LDA(At, 0, 1); PG8_STAGE(PG8_SB(0, 0), b2, voffB); PG8_STAGE(PG8_SB(0, 1), b2 + hstep, voffB); PG8_STAGE(PG8_SA(0, 0), a2, voffA);
;             PG8_WAIT_V(8); PG8_WAIT_L(0); PG8_BAR; PG8_MMA(1, 0, At, B0); PG8_MMA(1, 1, At, B1); PG8_BAR; PG8_SCHED;
.LBB0_458:
	s_add_u32 s47, s20, 0x100
	s_addc_u32 s48, s21, 0
	s_mov_b32 s49, -2
	s_waitcnt lgkmcnt(0)
	s_waitcnt vmcnt(0)
	s_add_u32 s20, s18, 0x100
	s_addc_u32 s21, s19, 0
	s_add_i32 s50, 0, 0x10000
	s_cmp_eq_u32 s49, 40
	s_cselect_b32 s25, s9, s21
	s_cselect_b32 s24, s8, s20
	s_cselect_b32 s23, s17, s48
	s_cselect_b32 s22, s16, s47
	s_add_i32 s51, 0, 0x14000
	v_add_u32_e32 v142, s50, v165
	v_add_u32_e32 v182, s51, v165
	ds_read_b128 v[130:133], v142
	ds_read_b128 v[134:137], v142 offset:1024
	ds_read_b128 v[138:141], v142 offset:2048
	ds_read_b128 v[142:145], v142 offset:3072
	ds_read_b128 v[146:149], v182
	ds_read_b128 v[150:153], v182 offset:1024
	ds_read_b128 v[154:157], v182 offset:2048
	ds_read_b128 v[182:185], v182 offset:3072
	s_add_i32 m0, s28, 0xc000
	ds_read_b128 v[186:189], v214
	ds_read_b128 v[190:193], v214 offset:1024
	ds_read_b128 v[194:197], v214 offset:2048
	ds_read_b128 v[216:219], v214 offset:3072
	ds_read_b128 v[220:223], v214 offset:4096
	ds_read_b128 v[224:227], v214 offset:5120
	ds_read_b128 v[228:231], v214 offset:6144
	ds_read_b128 v[232:235], v214 offset:7168
	global_load_lds_dwordx4 v178, s[18:19]
	s_add_i32 m0, s28, 0xe000
	s_nop 0
	global_load_lds_dwordx4 v180, s[18:19]
	s_setprio 0
	s_waitcnt vmcnt(8)
	s_waitcnt lgkmcnt(0)
	s_barrier
	s_setprio 1
	s_waitcnt lgkmcnt(0)
	v_mfma_f32_16x16x32_bf16 v[126:129], v[130:133], v[186:189], 0
	v_mfma_f32_16x16x32_bf16 v[122:125], v[138:141], v[186:189], 0
	v_mfma_f32_16x16x32_bf16 v[110:113], v[130:133], v[194:197], 0
	v_mfma_f32_16x16x32_bf16 v[106:109], v[138:141], v[194:197], 0
	v_mfma_f32_16x16x32_bf16 v[94:97], v[130:133], v[220:223], 0
	v_mfma_f32_16x16x32_bf16 v[90:93], v[138:141], v[220:223], 0
	v_mfma_f32_16x16x32_bf16 v[78:81], v[130:133], v[228:231], 0
	v_mfma_f32_16x16x32_bf16 v[74:77], v[138:141], v[228:231], 0
	v_mfma_f32_16x16x32_bf16 v[126:129], v[134:137], v[190:193], v[126:129]
	v_mfma_f32_16x16x32_bf16 v[122:125], v[142:145], v[190:193], v[122:125]
	v_mfma_f32_16x16x32_bf16 v[110:113], v[134:137], v[216:219], v[110:113]
	v_mfma_f32_16x16x32_bf16 v[106:109], v[142:145], v[216:219], v[106:109]
	v_mfma_f32_16x16x32_bf16 v[94:97], v[134:137], v[224:227], v[94:97]
	v_mfma_f32_16x16x32_bf16 v[90:93], v[142:145], v[224:227], v[90:93]
	v_mfma_f32_16x16x32_bf16 v[78:81], v[134:137], v[232:235], v[78:81]
	v_mfma_f32_16x16x32_bf16 v[74:77], v[142:145], v[232:235], v[74:77]
	s_setprio 0
	s_setprio 1
	v_mfma_f32_16x16x32_bf16 v[118:121], v[146:149], v[186:189], 0
	v_mfma_f32_16x16x32_bf16 v[114:117], v[154:157], v[186:189], 0
	v_mfma_f32_16x16x32_bf16 v[102:105], v[146:149], v[194:197], 0
	v_mfma_f32_16x16x32_bf16 v[98:101], v[154:157], v[194:197], 0
	v_mfma_f32_16x16x32_bf16 v[86:89], v[146:149], v[220:223], 0
	v_mfma_f32_16x16x32_bf16 v[82:85], v[154:157], v[220:223], 0
	v_mfma_f32_16x16x32_bf16 v[70:73], v[146:149], v[228:231], 0
	v_mfma_f32_16x16x32_bf16 v[66:69], v[154:157], v[228:231], 0
	v_mfma_f32_16x16x32_bf16 v[118:121], v[150:153], v[190:193], v[118:121]
	v_mfma_f32_16x16x32_bf16 v[114:117], v[182:185], v[190:193], v[114:117]
	v_mfma_f32_16x16x32_bf16 v[102:105], v[150:153], v[216:219], v[102:105]
	v_mfma_f32_16x16x32_bf16 v[98:101], v[182:185], v[216:219], v[98:101]
	v_mfma_f32_16x16x32_bf16 v[86:89], v[150:153], v[224:227], v[86:89]
	v_mfma_f32_16x16x32_bf16 v[82:85], v[182:185], v[224:227], v[82:85]
	v_mfma_f32_16x16x32_bf16 v[70:73], v[150:153], v[232:235], v[70:73]
	v_mfma_f32_16x16x32_bf16 v[66:69], v[182:185], v[232:235], v[66:69]
	s_setprio 0
	s_barrier
	s_setprio 2
	s_add_i32 s18, s50, s2
	s_mov_b32 m0, s18
	ds_read_b128 v[186:189], v214 offset:16384
	ds_read_b128 v[190:193], v214 offset:17408
	ds_read_b128 v[194:197], v214 offset:18432
	ds_read_b128 v[216:219], v214 offset:19456
	ds_read_b128 v[220:223], v214 offset:20480
	ds_read_b128 v[224:227], v214 offset:21504
	ds_read_b128 v[228:231], v214 offset:22528
	ds_read_b128 v[232:235], v214 offset:23552
	global_load_lds_dwordx4 v0, s[22:23]
	s_add_i32 m0, s18, 0x2000
	s_add_u32 s18, s22, 0xb0000
	s_addc_u32 s19, s23, 0
	s_add_i32 s50, s51, s2
	global_load_lds_dwordx4 v172, s[22:23]
	s_mov_b32 m0, s50
	s_nop 0
	global_load_lds_dwordx4 v0, s[18:19]
	s_add_i32 m0, s50, 0x2000
	s_nop 0
	global_load_lds_dwordx4 v172, s[18:19]
	s_mov_b32 m0, s28
	s_nop 0
	global_load_lds_dwordx4 v176, s[24:25]
	s_mov_b32 m0, s29
	s_nop 0
	global_load_lds_dwordx4 v174, s[24:25]
	s_setprio 0
	s_waitcnt vmcnt(8)
	s_waitcnt lgkmcnt(0)
	s_barrier
	s_setprio 1
	s_waitcnt lgkmcnt(0)
	v_mfma_f32_16x16x32_bf16 v[62:65], v[130:133], v[186:189], 0
	v_mfma_f32_16x16x32_bf16 v[58:61], v[138:141], v[186:189], 0
	v_mfma_f32_16x16x32_bf16 v[46:49], v[130:133], v[194:197], 0
	v_mfma_f32_16x16x32_bf16 v[42:45], v[138:141], v[194:197], 0
	v_mfma_f32_16x16x32_bf16 v[30:33], v[130:133], v[220:223], 0
	v_mfma_f32_16x16x32_bf16 v[26:29], v[138:141], v[220:223], 0
	v_mfma_f32_16x16x32_bf16 v[14:17], v[130:133], v[228:231], 0
	v_mfma_f32_16x16x32_bf16 v[10:13], v[138:141], v[228:231], 0
	v_mfma_f32_16x16x32_bf16 v[62:65], v[134:137], v[190:193], v[62:65]
	v_mfma_f32_16x16x32_bf16 v[58:61], v[142:145], v[190:193], v[58:61]
	v_mfma_f32_16x16x32_bf16 v[46:49], v[134:137], v[216:219], v[46:49]
	v_mfma_f32_16x16x32_bf16 v[42:45], v[142:145], v[216:219], v[42:45]
	v_mfma_f32_16x16x32_bf16 v[30:33], v[134:137], v[224:227], v[30:33]
	v_mfma_f32_16x16x32_bf16 v[26:29], v[142:145], v[224:227], v[26:29]
	v_mfma_f32_16x16x32_bf16 v[14:17], v[134:137], v[232:235], v[14:17]
	v_mfma_f32_16x16x32_bf16 v[10:13], v[142:145], v[232:235], v[10:13]
	s_setprio 0
	s_setprio 1
	v_mfma_f32_16x16x32_bf16 v[54:57], v[146:149], v[186:189], 0
	v_mfma_f32_16x16x32_bf16 v[50:53], v[154:157], v[186:189], 0
	v_mfma_f32_16x16x32_bf16 v[38:41], v[146:149], v[194:197], 0
	v_mfma_f32_16x16x32_bf16 v[34:37], v[154:157], v[194:197], 0
	v_mfma_f32_16x16x32_bf16 v[22:25], v[146:149], v[220:223], 0
	v_mfma_f32_16x16x32_bf16 v[18:21], v[154:157], v[220:223], 0
	v_mfma_f32_16x16x32_bf16 v[6:9], v[146:149], v[228:231], 0
	v_mfma_f32_16x16x32_bf16 v[2:5], v[154:157], v[228:231], 0
	v_mfma_f32_16x16x32_bf16 v[54:57], v[150:153], v[190:193], v[54:57]
	v_mfma_f32_16x16x32_bf16 v[50:53], v[182:185], v[190:193], v[50:53]
	v_mfma_f32_16x16x32_bf16 v[38:41], v[150:153], v[216:219], v[38:41]
	v_mfma_f32_16x16x32_bf16 v[34:37], v[182:185], v[216:219], v[34:37]
	v_mfma_f32_16x16x32_bf16 v[22:25], v[150:153], v[224:227], v[22:25]
	v_mfma_f32_16x16x32_bf16 v[18:21], v[182:185], v[224:227], v[18:21]
	v_mfma_f32_16x16x32_bf16 v[6:9], v[150:153], v[232:235], v[6:9]
	v_mfma_f32_16x16x32_bf16 v[2:5], v[182:185], v[232:235], v[2:5]
	s_setprio 0
	s_barrier
; #define PG8_STAGE(bufoff, gbase, voff) do { _Pragma("unroll") for (int _i = 0; _i < 2; ++_i) \
;         __builtin_amdgcn_global_load_lds((const unsigned*)((const char*)(gbase) + (voff)[_i]), (PG8_LAS unsigned*)(lds + (bufoff) + ldsw + _i * 8192), 16, 0, 0); } while (0)
; #define PG8_LDA(dst, b, h) do { _Pragma("unroll") for (int m = 0; m < 4; ++m) _Pragma("unroll") for (int k = 0; k < 2; ++k) dst[m][k] = *(const PG8_LAS bf16x8*)(lds + PG8_SA(b, h) + aoff + m * 2048 + k * 1024); } while (0)
; #define PG8_LDB(dst, b, h) do { _Pragma("unroll") for (int n = 0; n < 2; ++n) _Pragma("unroll") for (int k = 0; k < 2; ++k) dst[n][k] = *(const PG8_LAS bf16x8*)(lds + PG8_SB(b, h) + boff + n * 2048 + k * 1024); } while (0)
; #define PG8_MMA(ai, bj, At, Bt) do { __builtin_amdgcn_s_setprio(1); _Pragma("unroll") for (int m = 0; m < 4; ++m) _Pragma("unroll") for (int n = 0; n < 2; ++n) _Pragma("unroll") for (int k = 0; k < 2; ++k) \
;         acc[ai][bj][m][n] = __builtin_amdgcn_mfma_f32_16x16x32_bf16(Bt[n][k], At[m][k], acc[ai][bj][m][n], 0, 0, 0); __builtin_amdgcn_s_setprio(0); } while (0)
; #define PG8_WAIT_V(n) asm volatile("s_waitcnt vmcnt(" #n ")" ::: "memory")
; #define PG8_WAIT_L(n) asm volatile("s_waitcnt lgkmcnt(" #n ")" ::: "memory")
; #define PG8_BAR __builtin_amdgcn_s_barrier()
; #define PG8_SCHED __builtin_amdgcn_sched_barrier(0)
; template <class Epi, class Sched, bool ALIGN_EPI = false, bool SP2 = false>
; __device__ __forceinline__ void gemm_phase(PG8_LAS unsigned char* lds, const Gemm g, const Sched& S, const Epi& E) {
;     ...
;             PG8_LDB(B0, 1, 0); PG8_LDB(B1, 1, 1); PG8_SCHED; PG8_LDA(At, 1, 0); PG8_STAGE(PG8_SA(0, 1), a2 + hstep, voffA);
;             PG8_WAIT_V(8); PG8_WAIT_L(0); PG8_BAR; PG8_MMA(0, 0, At, B0); PG8_MMA(0, 1, At, B1); PG8_BAR; PG8_SCHED;
;             PG8_LDA(At, 1, 1); PG8_STAGE(PG8_SB(1, 0), b3, voffB); PG8_STAGE(PG8_SB(1, 1), b3 + hstep, voffB); PG8_STAGE(PG8_SA(1, 0), a3, voffA);
;             PG8_WAIT_V(8); PG8_WAIT_L(0); PG8_BAR; PG8_MMA(1, 0, At, B0); PG8_MMA(1, 1, At, B1); PG8_BAR; PG8_SCHED;
	s_setprio 2
	s_add_i32 s50, 0, 0x18000
	s_add_i32 s51, 0, 0x1c000
	v_add_u32_e32 v142, s50, v165
	v_add_u32_e32 v182, s51, v165
	ds_read_b128 v[130:133], v142
	ds_read_b128 v[134:137], v142 offset:1024
	ds_read_b128 v[138:141], v142 offset:2048
	ds_read_b128 v[142:145], v142 offset:3072
	ds_read_b128 v[146:149], v182
	ds_read_b128 v[150:153], v182 offset:1024
	ds_read_b128 v[154:157], v182 offset:2048
	ds_read_b128 v[182:185], v182 offset:3072
	s_add_u32 s18, s24, 0xb0000
	s_addc_u32 s19, s25, 0
	s_mov_b32 m0, s30
	ds_read_b128 v[186:189], v214 offset:32768
	ds_read_b128 v[190:193], v214 offset:33792
	ds_read_b128 v[194:197], v214 offset:34816
	ds_read_b128 v[216:219], v214 offset:35840
	ds_read_b128 v[220:223], v214 offset:36864
	ds_read_b128 v[224:227], v214 offset:37888
	ds_read_b128 v[228:231], v214 offset:38912
	ds_read_b128 v[232:235], v214 offset:39936
	global_load_lds_dwordx4 v176, s[18:19]
	s_mov_b32 m0, s31
	s_nop 0
	global_load_lds_dwordx4 v174, s[18:19]
	s_setprio 0
	s_waitcnt vmcnt(8)
	s_waitcnt lgkmcnt(0)
	s_barrier
	s_setprio 1
	s_waitcnt lgkmcnt(0)
	v_mfma_f32_16x16x32_bf16 v[126:129], v[130:133], v[186:189], v[126:129]
	v_mfma_f32_16x16x32_bf16 v[122:125], v[138:141], v[186:189], v[122:125]
	v_mfma_f32_16x16x32_bf16 v[110:113], v[130:133], v[194:197], v[110:113]
	v_mfma_f32_16x16x32_bf16 v[106:109], v[138:141], v[194:197], v[106:109]
	v_mfma_f32_16x16x32_bf16 v[94:97], v[130:133], v[220:223], v[94:97]
	v_mfma_f32_16x16x32_bf16 v[90:93], v[138:141], v[220:223], v[90:93]
	v_mfma_f32_16x16x32_bf16 v[78:81], v[130:133], v[228:231], v[78:81]
	v_mfma_f32_16x16x32_bf16 v[74:77], v[138:141], v[228:231], v[74:77]
	v_mfma_f32_16x16x32_bf16 v[126:129], v[134:137], v[190:193], v[126:129]
	v_mfma_f32_16x16x32_bf16 v[122:125], v[142:145], v[190:193], v[122:125]
	v_mfma_f32_16x16x32_bf16 v[110:113], v[134:137], v[216:219], v[110:113]
	v_mfma_f32_16x16x32_bf16 v[106:109], v[142:145], v[216:219], v[106:109]
	v_mfma_f32_16x16x32_bf16 v[94:97], v[134:137], v[224:227], v[94:97]
	v_mfma_f32_16x16x32_bf16 v[90:93], v[142:145], v[224:227], v[90:93]
	v_mfma_f32_16x16x32_bf16 v[78:81], v[134:137], v[232:235], v[78:81]
	v_mfma_f32_16x16x32_bf16 v[74:77], v[142:145], v[232:235], v[74:77]
	s_setprio 0
	s_setprio 1
	v_mfma_f32_16x16x32_bf16 v[118:121], v[146:149], v[186:189], v[118:121]
	v_mfma_f32_16x16x32_bf16 v[114:117], v[154:157], v[186:189], v[114:117]
	v_mfma_f32_16x16x32_bf16 v[102:105], v[146:149], v[194:197], v[102:105]
	v_mfma_f32_16x16x32_bf16 v[98:101], v[154:157], v[194:197], v[98:101]
	v_mfma_f32_16x16x32_bf16 v[86:89], v[146:149], v[220:223], v[86:89]
	v_mfma_f32_16x16x32_bf16 v[82:85], v[154:157], v[220:223], v[82:85]
	v_mfma_f32_16x16x32_bf16 v[70:73], v[146:149], v[228:231], v[70:73]
	v_mfma_f32_16x16x32_bf16 v[66:69], v[154:157], v[228:231], v[66:69]
	v_mfma_f32_16x16x32_bf16 v[118:121], v[150:153], v[190:193], v[118:121]
	v_mfma_f32_16x16x32_bf16 v[114:117], v[182:185], v[190:193], v[114:117]
	v_mfma_f32_16x16x32_bf16 v[102:105], v[150:153], v[216:219], v[102:105]
	v_mfma_f32_16x16x32_bf16 v[98:101], v[182:185], v[216:219], v[98:101]
	v_mfma_f32_16x16x32_bf16 v[86:89], v[150:153], v[224:227], v[86:89]
	v_mfma_f32_16x16x32_bf16 v[82:85], v[182:185], v[224:227], v[82:85]
	v_mfma_f32_16x16x32_bf16 v[70:73], v[150:153], v[232:235], v[70:73]
	v_mfma_f32_16x16x32_bf16 v[66:69], v[182:185], v[232:235], v[66:69]
	s_setprio 0
	s_barrier
	s_setprio 2
	s_add_i32 s18, s50, s2
	s_add_u32 s98, s22, 0x80
	s_addc_u32 s99, s23, 0
	s_add_u32 s100, s24, 0x80
	s_addc_u32 s101, s25, 0
	s_mov_b32 m0, s18
	ds_read_b128 v[186:189], v214 offset:49152
	ds_read_b128 v[190:193], v214 offset:50176
	ds_read_b128 v[194:197], v214 offset:51200
	ds_read_b128 v[216:219], v214 offset:52224
	ds_read_b128 v[220:223], v214 offset:53248
	ds_read_b128 v[224:227], v214 offset:54272
	ds_read_b128 v[228:231], v214 offset:55296
	ds_read_b128 v[232:235], v214 offset:56320
	global_load_lds_dwordx4 v0, s[98:99]
	s_add_i32 m0, s18, 0x2000
	s_add_u32 s18, s22, 0xb0080
	s_addc_u32 s19, s23, 0
	s_add_i32 s22, s51, s2
	global_load_lds_dwordx4 v172, s[98:99]
	s_mov_b32 m0, s22
	s_nop 0
	global_load_lds_dwordx4 v0, s[18:19]
	s_add_i32 m0, s22, 0x2000
	s_nop 0
	global_load_lds_dwordx4 v172, s[18:19]
	s_mov_b32 m0, s35
	s_nop 0
	global_load_lds_dwordx4 v176, s[100:101]
	s_mov_b32 m0, s37
	s_nop 0
	global_load_lds_dwordx4 v174, s[100:101]
	s_setprio 0
	s_waitcnt vmcnt(8)
	s_waitcnt lgkmcnt(0)
	s_barrier
	s_setprio 1
	s_waitcnt lgkmcnt(0)
	v_mfma_f32_16x16x32_bf16 v[62:65], v[130:133], v[186:189], v[62:65]
	v_mfma_f32_16x16x32_bf16 v[58:61], v[138:141], v[186:189], v[58:61]
	v_mfma_f32_16x16x32_bf16 v[46:49], v[130:133], v[194:197], v[46:49]
	v_mfma_f32_16x16x32_bf16 v[42:45], v[138:141], v[194:197], v[42:45]
	v_mfma_f32_16x16x32_bf16 v[30:33], v[130:133], v[220:223], v[30:33]
	v_mfma_f32_16x16x32_bf16 v[26:29], v[138:141], v[220:223], v[26:29]
	v_mfma_f32_16x16x32_bf16 v[14:17], v[130:133], v[228:231], v[14:17]
	v_mfma_f32_16x16x32_bf16 v[10:13], v[138:141], v[228:231], v[10:13]
	v_mfma_f32_16x16x32_bf16 v[62:65], v[134:137], v[190:193], v[62:65]
	v_mfma_f32_16x16x32_bf16 v[58:61], v[142:145], v[190:193], v[58:61]
	v_mfma_f32_16x16x32_bf16 v[46:49], v[134:137], v[216:219], v[46:49]
	v_mfma_f32_16x16x32_bf16 v[42:45], v[142:145], v[216:219], v[42:45]
	v_mfma_f32_16x16x32_bf16 v[30:33], v[134:137], v[224:227], v[30:33]
	v_mfma_f32_16x16x32_bf16 v[26:29], v[142:145], v[224:227], v[26:29]
	v_mfma_f32_16x16x32_bf16 v[14:17], v[134:137], v[232:235], v[14:17]
	v_mfma_f32_16x16x32_bf16 v[10:13], v[142:145], v[232:235], v[10:13]
	s_setprio 0
	s_setprio 1
	v_mfma_f32_16x16x32_bf16 v[54:57], v[146:149], v[186:189], v[54:57]
	v_mfma_f32_16x16x32_bf16 v[50:53], v[154:157], v[186:189], v[50:53]
	v_mfma_f32_16x16x32_bf16 v[38:41], v[146:149], v[194:197], v[38:41]
	v_mfma_f32_16x16x32_bf16 v[34:37], v[154:157], v[194:197], v[34:37]
	v_mfma_f32_16x16x32_bf16 v[22:25], v[146:149], v[220:223], v[22:25]
	v_mfma_f32_16x16x32_bf16 v[18:21], v[154:157], v[220:223], v[18:21]
	v_mfma_f32_16x16x32_bf16 v[6:9], v[146:149], v[228:231], v[6:9]
	v_mfma_f32_16x16x32_bf16 v[2:5], v[154:157], v[228:231], v[2:5]
	v_mfma_f32_16x16x32_bf16 v[54:57], v[150:153], v[190:193], v[54:57]
	v_mfma_f32_16x16x32_bf16 v[50:53], v[182:185], v[190:193], v[50:53]
	v_mfma_f32_16x16x32_bf16 v[38:41], v[150:153], v[216:219], v[38:41]
	v_mfma_f32_16x16x32_bf16 v[34:37], v[182:185], v[216:219], v[34:37]
	v_mfma_f32_16x16x32_bf16 v[22:25], v[150:153], v[224:227], v[22:25]
	v_mfma_f32_16x16x32_bf16 v[18:21], v[182:185], v[224:227], v[18:21]
	v_mfma_f32_16x16x32_bf16 v[6:9], v[150:153], v[232:235], v[6:9]
	v_mfma_f32_16x16x32_bf16 v[2:5], v[182:185], v[232:235], v[2:5]
	s_setprio 0
	s_barrier
	s_setprio 2
	s_add_i32 s49, s49, 2
	s_add_u32 s47, s47, 0x100
	s_addc_u32 s48, s48, 0
	s_mov_b64 s[18:19], s[20:21]
; #define PG8_STAGE(bufoff, gbase, voff) do { _Pragma("unroll") for (int _i = 0; _i < 2; ++_i) \
;         __builtin_amdgcn_global_load_lds((const unsigned*)((const char*)(gbase) + (voff)[_i]), (PG8_LAS unsigned*)(lds + (bufoff) + ldsw + _i * 8192), 16, 0, 0); } while (0)
; #define PG8_LDA(dst, b, h) do { _Pragma("unroll") for (int m = 0; m < 4; ++m) _Pragma("unroll") for (int k = 0; k < 2; ++k) dst[m][k] = *(const PG8_LAS bf16x8*)(lds + PG8_SA(b, h) + aoff + m * 2048 + k * 1024); } while (0)
; #define PG8_LDB(dst, b, h) do { _Pragma("unroll") for (int n = 0; n < 2; ++n) _Pragma("unroll") for (int k = 0; k < 2; ++k) dst[n][k] = *(const PG8_LAS bf16x8*)(lds + PG8_SB(b, h) + boff + n * 2048 + k * 1024); } while (0)
; #define PG8_MMA(ai, bj, At, Bt) do { __builtin_amdgcn_s_setprio(1); _Pragma("unroll") for (int m = 0; m < 4; ++m) _Pragma("unroll") for (int n = 0; n < 2; ++n) _Pragma("unroll") for (int k = 0; k < 2; ++k) \
;         acc[ai][bj][m][n] = __builtin_amdgcn_mfma_f32_16x16x32_bf16(Bt[n][k], At[m][k], acc[ai][bj][m][n], 0, 0, 0); __builtin_amdgcn_s_setprio(0); } while (0)
; #define PG8_WAIT_V(n) asm volatile("s_waitcnt vmcnt(" #n ")" ::: "memory")
; #define PG8_WAIT_L(n) asm volatile("s_waitcnt lgkmcnt(" #n ")" ::: "memory")
; #define PG8_BAR __builtin_amdgcn_s_barrier()
; #define PG8_SCHED __builtin_amdgcn_sched_barrier(0)
; template <class Epi, class Sched, bool ALIGN_EPI = false, bool SP2 = false>
; __device__ __forceinline__ void gemm_phase(PG8_LAS unsigned char* lds, const Gemm g, const Sched& S, const Epi& E) {
;     ...
;             PG8_LDB(B0, 0, 0); PG8_LDB(B1, 0, 1); PG8_SCHED; PG8_LDA(At, 0, 0); PG8_STAGE(PG8_SA(1, 1), a1 + hstep, voffA);
;             PG8_WAIT_V(8); PG8_WAIT_L(0); PG8_BAR; PG8_MMA(0, 0, At, B0); PG8_MMA(0, 1, At, B1); PG8_BAR; PG8_SCHED;
;             PG8_LDA(At, 0, 1); PG8_STAGE(PG8_SB(0, 0), b2, voffB); PG8_STAGE(PG8_SB(0, 1), b2 + hstep, voffB); PG8_STAGE(PG8_SA(0, 0), a2, voffA);
;             PG8_WAIT_V(8); PG8_WAIT_L(0); PG8_BAR; PG8_MMA(1, 0, At, B0); PG8_MMA(1, 1, At, B1); PG8_BAR; PG8_SCHED;
;             PG8_LDB(B0, 1, 0); PG8_LDB(B1, 1, 1); PG8_SCHED; PG8_LDA(At, 1, 0); PG8_STAGE(PG8_SA(0, 1), a2 + hstep, voffA);
;             PG8_WAIT_V(8); PG8_WAIT_L(0); PG8_BAR; PG8_MMA(0, 0, At, B0); PG8_MMA(0, 1, At, B1); PG8_BAR; PG8_SCHED;
.LBB0_459:
	s_add_u32 s20, s18, 0x100
	s_addc_u32 s21, s19, 0
	s_add_i32 s50, 0, 0x10000
	s_cmp_eq_u32 s49, 40
	s_cselect_b32 s25, s9, s21
	s_cselect_b32 s24, s8, s20
	s_cselect_b32 s23, s17, s48
	s_cselect_b32 s22, s16, s47
	s_add_i32 s51, 0, 0x14000
	v_add_u32_e32 v142, s50, v165
	v_add_u32_e32 v182, s51, v165
	ds_read_b128 v[130:133], v142
	ds_read_b128 v[134:137], v142 offset:1024
	ds_read_b128 v[138:141], v142 offset:2048
	ds_read_b128 v[142:145], v142 offset:3072
	ds_read_b128 v[146:149], v182
	ds_read_b128 v[150:153], v182 offset:1024
	ds_read_b128 v[154:157], v182 offset:2048
	ds_read_b128 v[182:185], v182 offset:3072
	s_add_i32 m0, s28, 0xc000
	ds_read_b128 v[186:189], v214
	ds_read_b128 v[190:193], v214 offset:1024
	ds_read_b128 v[194:197], v214 offset:2048
	ds_read_b128 v[216:219], v214 offset:3072
	ds_read_b128 v[220:223], v214 offset:4096
	ds_read_b128 v[224:227], v214 offset:5120
	ds_read_b128 v[228:231], v214 offset:6144
	ds_read_b128 v[232:235], v214 offset:7168
	global_load_lds_dwordx4 v178, s[18:19]
	s_add_i32 m0, s28, 0xe000
	s_nop 0
	global_load_lds_dwordx4 v180, s[18:19]
	s_setprio 0
	s_waitcnt vmcnt(8)
	s_waitcnt lgkmcnt(0)
	s_barrier
	s_setprio 1
	s_waitcnt lgkmcnt(0)
	v_mfma_f32_16x16x32_bf16 v[126:129], v[130:133], v[186:189], v[126:129]
	v_mfma_f32_16x16x32_bf16 v[122:125], v[138:141], v[186:189], v[122:125]
	v_mfma_f32_16x16x32_bf16 v[110:113], v[130:133], v[194:197], v[110:113]
	v_mfma_f32_16x16x32_bf16 v[106:109], v[138:141], v[194:197], v[106:109]
	v_mfma_f32_16x16x32_bf16 v[94:97], v[130:133], v[220:223], v[94:97]
	v_mfma_f32_16x16x32_bf16 v[90:93], v[138:141], v[220:223], v[90:93]
	v_mfma_f32_16x16x32_bf16 v[78:81], v[130:133], v[228:231], v[78:81]
	v_mfma_f32_16x16x32_bf16 v[74:77], v[138:141], v[228:231], v[74:77]
	v_mfma_f32_16x16x32_bf16 v[126:129], v[134:137], v[190:193], v[126:129]
	v_mfma_f32_16x16x32_bf16 v[122:125], v[142:145], v[190:193], v[122:125]
	v_mfma_f32_16x16x32_bf16 v[110:113], v[134:137], v[216:219], v[110:113]
	v_mfma_f32_16x16x32_bf16 v[106:109], v[142:145], v[216:219], v[106:109]
	v_mfma_f32_16x16x32_bf16 v[94:97], v[134:137], v[224:227], v[94:97]
	v_mfma_f32_16x16x32_bf16 v[90:93], v[142:145], v[224:227], v[90:93]
	v_mfma_f32_16x16x32_bf16 v[78:81], v[134:137], v[232:235], v[78:81]
	v_mfma_f32_16x16x32_bf16 v[74:77], v[142:145], v[232:235], v[74:77]
	s_setprio 0
	s_setprio 1
	v_mfma_f32_16x16x32_bf16 v[118:121], v[146:149], v[186:189], v[118:121]
	v_mfma_f32_16x16x32_bf16 v[114:117], v[154:157], v[186:189], v[114:117]
	v_mfma_f32_16x16x32_bf16 v[102:105], v[146:149], v[194:197], v[102:105]
	v_mfma_f32_16x16x32_bf16 v[98:101], v[154:157], v[194:197], v[98:101]
	v_mfma_f32_16x16x32_bf16 v[86:89], v[146:149], v[220:223], v[86:89]
	v_mfma_f32_16x16x32_bf16 v[82:85], v[154:157], v[220:223], v[82:85]
	v_mfma_f32_16x16x32_bf16 v[70:73], v[146:149], v[228:231], v[70:73]
	v_mfma_f32_16x16x32_bf16 v[66:69], v[154:157], v[228:231], v[66:69]
	v_mfma_f32_16x16x32_bf16 v[118:121], v[150:153], v[190:193], v[118:121]
	v_mfma_f32_16x16x32_bf16 v[114:117], v[182:185], v[190:193], v[114:117]
	v_mfma_f32_16x16x32_bf16 v[102:105], v[150:153], v[216:219], v[102:105]
	v_mfma_f32_16x16x32_bf16 v[98:101], v[182:185], v[216:219], v[98:101]
	v_mfma_f32_16x16x32_bf16 v[86:89], v[150:153], v[224:227], v[86:89]
	v_mfma_f32_16x16x32_bf16 v[82:85], v[182:185], v[224:227], v[82:85]
	v_mfma_f32_16x16x32_bf16 v[70:73], v[150:153], v[232:235], v[70:73]
	v_mfma_f32_16x16x32_bf16 v[66:69], v[182:185], v[232:235], v[66:69]
	s_setprio 0
	s_barrier
	s_setprio 2
	s_add_i32 s18, s50, s2
	s_mov_b32 m0, s18
	ds_read_b128 v[186:189], v214 offset:16384
	ds_read_b128 v[190:193], v214 offset:17408
	ds_read_b128 v[194:197], v214 offset:18432
	ds_read_b128 v[216:219], v214 offset:19456
	ds_read_b128 v[220:223], v214 offset:20480
	ds_read_b128 v[224:227], v214 offset:21504
	ds_read_b128 v[228:231], v214 offset:22528
	ds_read_b128 v[232:235], v214 offset:23552
	global_load_lds_dwordx4 v0, s[22:23]
	s_add_i32 m0, s18, 0x2000
	s_add_u32 s18, s22, 0xb0000
	s_addc_u32 s19, s23, 0
	s_add_i32 s50, s51, s2
	global_load_lds_dwordx4 v172, s[22:23]
	s_mov_b32 m0, s50
	s_nop 0
	global_load_lds_dwordx4 v0, s[18:19]
	s_add_i32 m0, s50, 0x2000
	s_nop 0
	global_load_lds_dwordx4 v172, s[18:19]
	s_mov_b32 m0, s28
	s_nop 0
	global_load_lds_dwordx4 v176, s[24:25]
	s_mov_b32 m0, s29
	s_nop 0
	global_load_lds_dwordx4 v174, s[24:25]
	s_setprio 0
	s_waitcnt vmcnt(8)
	s_waitcnt lgkmcnt(0)
	s_barrier
	s_setprio 1
	s_waitcnt lgkmcnt(0)
	v_mfma_f32_16x16x32_bf16 v[62:65], v[130:133], v[186:189], v[62:65]
	v_mfma_f32_16x16x32_bf16 v[58:61], v[138:141], v[186:189], v[58:61]
	v_mfma_f32_16x16x32_bf16 v[46:49], v[130:133], v[194:197], v[46:49]
	v_mfma_f32_16x16x32_bf16 v[42:45], v[138:141], v[194:197], v[42:45]
	v_mfma_f32_16x16x32_bf16 v[30:33], v[130:133], v[220:223], v[30:33]
	v_mfma_f32_16x16x32_bf16 v[26:29], v[138:141], v[220:223], v[26:29]
	v_mfma_f32_16x16x32_bf16 v[14:17], v[130:133], v[228:231], v[14:17]
	v_mfma_f32_16x16x32_bf16 v[10:13], v[138:141], v[228:231], v[10:13]
	v_mfma_f32_16x16x32_bf16 v[62:65], v[134:137], v[190:193], v[62:65]
	v_mfma_f32_16x16x32_bf16 v[58:61], v[142:145], v[190:193], v[58:61]
	v_mfma_f32_16x16x32_bf16 v[46:49], v[134:137], v[216:219], v[46:49]
	v_mfma_f32_16x16x32_bf16 v[42:45], v[142:145], v[216:219], v[42:45]
	v_mfma_f32_16x16x32_bf16 v[30:33], v[134:137], v[224:227], v[30:33]
	v_mfma_f32_16x16x32_bf16 v[26:29], v[142:145], v[224:227], v[26:29]
	v_mfma_f32_16x16x32_bf16 v[14:17], v[134:137], v[232:235], v[14:17]
	v_mfma_f32_16x16x32_bf16 v[10:13], v[142:145], v[232:235], v[10:13]
	s_setprio 0
	s_setprio 1
	v_mfma_f32_16x16x32_bf16 v[54:57], v[146:149], v[186:189], v[54:57]
	v_mfma_f32_16x16x32_bf16 v[50:53], v[154:157], v[186:189], v[50:53]
	v_mfma_f32_16x16x32_bf16 v[38:41], v[146:149], v[194:197], v[38:41]
	v_mfma_f32_16x16x32_bf16 v[34:37], v[154:157], v[194:197], v[34:37]
	v_mfma_f32_16x16x32_bf16 v[22:25], v[146:149], v[220:223], v[22:25]
	v_mfma_f32_16x16x32_bf16 v[18:21], v[154:157], v[220:223], v[18:21]
	v_mfma_f32_16x16x32_bf16 v[6:9], v[146:149], v[228:231], v[6:9]
	v_mfma_f32_16x16x32_bf16 v[2:5], v[154:157], v[228:231], v[2:5]
	v_mfma_f32_16x16x32_bf16 v[54:57], v[150:153], v[190:193], v[54:57]
	v_mfma_f32_16x16x32_bf16 v[50:53], v[182:185], v[190:193], v[50:53]
	v_mfma_f32_16x16x32_bf16 v[38:41], v[150:153], v[216:219], v[38:41]
	v_mfma_f32_16x16x32_bf16 v[34:37], v[182:185], v[216:219], v[34:37]
	v_mfma_f32_16x16x32_bf16 v[22:25], v[150:153], v[224:227], v[22:25]
	v_mfma_f32_16x16x32_bf16 v[18:21], v[182:185], v[224:227], v[18:21]
	v_mfma_f32_16x16x32_bf16 v[6:9], v[150:153], v[232:235], v[6:9]
	v_mfma_f32_16x16x32_bf16 v[2:5], v[182:185], v[232:235], v[2:5]
	s_setprio 0
	s_barrier
; #define PG8_STAGE(bufoff, gbase, voff) do { _Pragma("unroll") for (int _i = 0; _i < 2; ++_i) \
;         __builtin_amdgcn_global_load_lds((const unsigned*)((const char*)(gbase) + (voff)[_i]), (PG8_LAS unsigned*)(lds + (bufoff) + ldsw + _i * 8192), 16, 0, 0); } while (0)
; #define PG8_LDA(dst, b, h) do { _Pragma("unroll") for (int m = 0; m < 4; ++m) _Pragma("unroll") for (int k = 0; k < 2; ++k) dst[m][k] = *(const PG8_LAS bf16x8*)(lds + PG8_SA(b, h) + aoff + m * 2048 + k * 1024); } while (0)
; #define PG8_LDB(dst, b, h) do { _Pragma("unroll") for (int n = 0; n < 2; ++n) _Pragma("unroll") for (int k = 0; k < 2; ++k) dst[n][k] = *(const PG8_LAS bf16x8*)(lds + PG8_SB(b, h) + boff + n * 2048 + k * 1024); } while (0)
; #define PG8_MMA(ai, bj, At, Bt) do { __builtin_amdgcn_s_setprio(1); _Pragma("unroll") for (int m = 0; m < 4; ++m) _Pragma("unroll") for (int n = 0; n < 2; ++n) _Pragma("unroll") for (int k = 0; k < 2; ++k) \
;         acc[ai][bj][m][n] = __builtin_amdgcn_mfma_f32_16x16x32_bf16(Bt[n][k], At[m][k], acc[ai][bj][m][n], 0, 0, 0); __builtin_amdgcn_s_setprio(0); } while (0)
; #define PG8_WAIT_V(n) asm volatile("s_waitcnt vmcnt(" #n ")" ::: "memory")
; #define PG8_WAIT_L(n) asm volatile("s_waitcnt lgkmcnt(" #n ")" ::: "memory")
; #define PG8_BAR __builtin_amdgcn_s_barrier()
; #define PG8_SCHED __builtin_amdgcn_sched_barrier(0)
; template <class Epi, class Sched, bool ALIGN_EPI = false, bool SP2 = false>
; __device__ __forceinline__ void gemm_phase(PG8_LAS unsigned char* lds, const Gemm g, const Sched& S, const Epi& E) {
;     ...
;             PG8_LDB(B0, 1, 0); PG8_LDB(B1, 1, 1); PG8_SCHED; PG8_LDA(At, 1, 0); PG8_STAGE(PG8_SA(0, 1), a2 + hstep, voffA);
;             PG8_WAIT_V(8); PG8_WAIT_L(0); PG8_BAR; PG8_MMA(0, 0, At, B0); PG8_MMA(0, 1, At, B1); PG8_BAR; PG8_SCHED;
;             PG8_LDA(At, 1, 1); PG8_STAGE(PG8_SB(1, 0), b3, voffB); PG8_STAGE(PG8_SB(1, 1), b3 + hstep, voffB); PG8_STAGE(PG8_SA(1, 0), a3, voffA);
;             PG8_WAIT_V(8); PG8_WAIT_L(0); PG8_BAR; PG8_MMA(1, 0, At, B0); PG8_MMA(1, 1, At, B1); PG8_BAR; PG8_SCHED;
	s_setprio 2
	s_add_i32 s50, 0, 0x18000
	s_add_i32 s51, 0, 0x1c000
	v_add_u32_e32 v142, s50, v165
	v_add_u32_e32 v182, s51, v165
	ds_read_b128 v[130:133], v142
	ds_read_b128 v[134:137], v142 offset:1024
	ds_read_b128 v[138:141], v142 offset:2048
	ds_read_b128 v[142:145], v142 offset:3072
	ds_read_b128 v[146:149], v182
	ds_read_b128 v[150:153], v182 offset:1024
	ds_read_b128 v[154:157], v182 offset:2048
	ds_read_b128 v[182:185], v182 offset:3072
	s_add_u32 s18, s24, 0xb0000
	s_addc_u32 s19, s25, 0
	s_mov_b32 m0, s30
	ds_read_b128 v[186:189], v214 offset:32768
	ds_read_b128 v[190:193], v214 offset:33792
	ds_read_b128 v[194:197], v214 offset:34816
	ds_read_b128 v[216:219], v214 offset:35840
	ds_read_b128 v[220:223], v214 offset:36864
	ds_read_b128 v[224:227], v214 offset:37888
	ds_read_b128 v[228:231], v214 offset:38912
	ds_read_b128 v[232:235], v214 offset:39936
	global_load_lds_dwordx4 v176, s[18:19]
	s_mov_b32 m0, s31
	s_nop 0
	global_load_lds_dwordx4 v174, s[18:19]
	s_setprio 0
	s_waitcnt vmcnt(8)
	s_waitcnt lgkmcnt(0)
	s_barrier
	s_setprio 1
	s_waitcnt lgkmcnt(0)
	v_mfma_f32_16x16x32_bf16 v[126:129], v[130:133], v[186:189], v[126:129]
	v_mfma_f32_16x16x32_bf16 v[122:125], v[138:141], v[186:189], v[122:125]
	v_mfma_f32_16x16x32_bf16 v[110:113], v[130:133], v[194:197], v[110:113]
	v_mfma_f32_16x16x32_bf16 v[106:109], v[138:141], v[194:197], v[106:109]
	v_mfma_f32_16x16x32_bf16 v[94:97], v[130:133], v[220:223], v[94:97]
	v_mfma_f32_16x16x32_bf16 v[90:93], v[138:141], v[220:223], v[90:93]
	v_mfma_f32_16x16x32_bf16 v[78:81], v[130:133], v[228:231], v[78:81]
	v_mfma_f32_16x16x32_bf16 v[74:77], v[138:141], v[228:231], v[74:77]
	v_mfma_f32_16x16x32_bf16 v[126:129], v[134:137], v[190:193], v[126:129]
	v_mfma_f32_16x16x32_bf16 v[122:125], v[142:145], v[190:193], v[122:125]
	v_mfma_f32_16x16x32_bf16 v[110:113], v[134:137], v[216:219], v[110:113]
	v_mfma_f32_16x16x32_bf16 v[106:109], v[142:145], v[216:219], v[106:109]
	v_mfma_f32_16x16x32_bf16 v[94:97], v[134:137], v[224:227], v[94:97]
	v_mfma_f32_16x16x32_bf16 v[90:93], v[142:145], v[224:227], v[90:93]
	v_mfma_f32_16x16x32_bf16 v[78:81], v[134:137], v[232:235], v[78:81]
	v_mfma_f32_16x16x32_bf16 v[74:77], v[142:145], v[232:235], v[74:77]
	s_setprio 0
	s_setprio 1
	v_mfma_f32_16x16x32_bf16 v[118:121], v[146:149], v[186:189], v[118:121]
	v_mfma_f32_16x16x32_bf16 v[114:117], v[154:157], v[186:189], v[114:117]
	v_mfma_f32_16x16x32_bf16 v[102:105], v[146:149], v[194:197], v[102:105]
	v_mfma_f32_16x16x32_bf16 v[98:101], v[154:157], v[194:197], v[98:101]
	v_mfma_f32_16x16x32_bf16 v[86:89], v[146:149], v[220:223], v[86:89]
	v_mfma_f32_16x16x32_bf16 v[82:85], v[154:157], v[220:223], v[82:85]
	v_mfma_f32_16x16x32_bf16 v[70:73], v[146:149], v[228:231], v[70:73]
	v_mfma_f32_16x16x32_bf16 v[66:69], v[154:157], v[228:231], v[66:69]
	v_mfma_f32_16x16x32_bf16 v[118:121], v[150:153], v[190:193], v[118:121]
	v_mfma_f32_16x16x32_bf16 v[114:117], v[182:185], v[190:193], v[114:117]
	v_mfma_f32_16x16x32_bf16 v[102:105], v[150:153], v[216:219], v[102:105]
	v_mfma_f32_16x16x32_bf16 v[98:101], v[182:185], v[216:219], v[98:101]
	v_mfma_f32_16x16x32_bf16 v[86:89], v[150:153], v[224:227], v[86:89]
	v_mfma_f32_16x16x32_bf16 v[82:85], v[182:185], v[224:227], v[82:85]
	v_mfma_f32_16x16x32_bf16 v[70:73], v[150:153], v[232:235], v[70:73]
	v_mfma_f32_16x16x32_bf16 v[66:69], v[182:185], v[232:235], v[66:69]
	s_setprio 0
	s_barrier
	s_setprio 2
	s_add_i32 s18, s50, s2
	s_add_u32 s98, s22, 0x80
	s_addc_u32 s99, s23, 0
	s_add_u32 s100, s24, 0x80
	s_addc_u32 s101, s25, 0
	s_mov_b32 m0, s18
	ds_read_b128 v[186:189], v214 offset:49152
	ds_read_b128 v[190:193], v214 offset:50176
	ds_read_b128 v[194:197], v214 offset:51200
	ds_read_b128 v[216:219], v214 offset:52224
	ds_read_b128 v[220:223], v214 offset:53248
	ds_read_b128 v[224:227], v214 offset:54272
	ds_read_b128 v[228:231], v214 offset:55296
	ds_read_b128 v[232:235], v214 offset:56320
	global_load_lds_dwordx4 v0, s[98:99]
	s_add_i32 m0, s18, 0x2000
	s_add_u32 s18, s22, 0xb0080
	s_addc_u32 s19, s23, 0
	s_add_i32 s22, s51, s2
	global_load_lds_dwordx4 v172, s[98:99]
	s_mov_b32 m0, s22
	s_nop 0
	global_load_lds_dwordx4 v0, s[18:19]
	s_add_i32 m0, s22, 0x2000
	s_nop 0
	global_load_lds_dwordx4 v172, s[18:19]
	s_mov_b32 m0, s35
	s_nop 0
	global_load_lds_dwordx4 v176, s[100:101]
	s_mov_b32 m0, s37
	s_nop 0
	global_load_lds_dwordx4 v174, s[100:101]
	s_setprio 0
	s_waitcnt vmcnt(8)
	s_waitcnt lgkmcnt(0)
	s_barrier
; #define PG8_MMA(ai, bj, At, Bt) do { __builtin_amdgcn_s_setprio(1); _Pragma("unroll") for (int m = 0; m < 4; ++m) _Pragma("unroll") for (int n = 0; n < 2; ++n) _Pragma("unroll") for (int k = 0; k < 2; ++k) \
;         acc[ai][bj][m][n] = __builtin_amdgcn_mfma_f32_16x16x32_bf16(Bt[n][k], At[m][k], acc[ai][bj][m][n], 0, 0, 0); __builtin_amdgcn_s_setprio(0); } while (0)
; #define PG8_WAIT_V(n) asm volatile("s_waitcnt vmcnt(" #n ")" ::: "memory")
; #define PG8_WAIT_L(n) asm volatile("s_waitcnt lgkmcnt(" #n ")" ::: "memory")
; #define PG8_BAR __builtin_amdgcn_s_barrier()
; #define PG8_SCHED __builtin_amdgcn_sched_barrier(0)
; template <class Epi, class Sched, bool ALIGN_EPI = false, bool SP2 = false>
; __device__ __forceinline__ void gemm_phase(PG8_LAS unsigned char* lds, const Gemm g, const Sched& S, const Epi& E) {
;     ...
;             PG8_WAIT_V(8); PG8_WAIT_L(0); PG8_BAR; PG8_MMA(1, 0, At, B0); PG8_MMA(1, 1, At, B1); PG8_BAR; PG8_SCHED;
;     __device__ __forceinline__ void operator()(const f32x4 (&acc)[2][2][4][2], const Unit& u, int wr, int wc, int fr, int fq) const {
;     ...
; #pragma unroll
;         for (int ai = 0; ai < 2; ++ai) {
;             u32x4 xv[4][2];
; #pragma unroll
;             for (int m = 0; m < 4; ++m)
; #pragma unroll
;                 for (int bj = 0; bj < 2; ++bj) xv[m][bj] = *(const u32x4*)(XB + (size_t)(row0 + ai * HALF + m * 16) * 1024 + col0 + bj * HALF);
;             asm volatile("" ::: "memory");
	s_setprio 1
	s_waitcnt lgkmcnt(0)
	v_mfma_f32_16x16x32_bf16 v[62:65], v[130:133], v[186:189], v[62:65]
	v_mfma_f32_16x16x32_bf16 v[58:61], v[138:141], v[186:189], v[58:61]
	v_mfma_f32_16x16x32_bf16 v[46:49], v[130:133], v[194:197], v[46:49]
	v_mfma_f32_16x16x32_bf16 v[42:45], v[138:141], v[194:197], v[42:45]
	v_mfma_f32_16x16x32_bf16 v[30:33], v[130:133], v[220:223], v[30:33]
	v_mfma_f32_16x16x32_bf16 v[26:29], v[138:141], v[220:223], v[26:29]
	v_mfma_f32_16x16x32_bf16 v[14:17], v[130:133], v[228:231], v[14:17]
	v_mfma_f32_16x16x32_bf16 v[10:13], v[138:141], v[228:231], v[10:13]
	v_mfma_f32_16x16x32_bf16 v[62:65], v[134:137], v[190:193], v[62:65]
	v_mfma_f32_16x16x32_bf16 v[58:61], v[142:145], v[190:193], v[58:61]
	v_mfma_f32_16x16x32_bf16 v[46:49], v[134:137], v[216:219], v[46:49]
	v_mfma_f32_16x16x32_bf16 v[42:45], v[142:145], v[216:219], v[42:45]
	v_mfma_f32_16x16x32_bf16 v[30:33], v[134:137], v[224:227], v[30:33]
	v_mfma_f32_16x16x32_bf16 v[26:29], v[142:145], v[224:227], v[26:29]
	v_mfma_f32_16x16x32_bf16 v[14:17], v[134:137], v[232:235], v[14:17]
	v_mfma_f32_16x16x32_bf16 v[10:13], v[142:145], v[232:235], v[10:13]
	s_setprio 0
	s_setprio 1
	v_mfma_f32_16x16x32_bf16 v[54:57], v[146:149], v[186:189], v[54:57]
	v_mfma_f32_16x16x32_bf16 v[50:53], v[154:157], v[186:189], v[50:53]
	v_mfma_f32_16x16x32_bf16 v[38:41], v[146:149], v[194:197], v[38:41]
	v_mfma_f32_16x16x32_bf16 v[34:37], v[154:157], v[194:197], v[34:37]
	v_mfma_f32_16x16x32_bf16 v[22:25], v[146:149], v[220:223], v[22:25]
	v_mfma_f32_16x16x32_bf16 v[18:21], v[154:157], v[220:223], v[18:21]
	v_mfma_f32_16x16x32_bf16 v[6:9], v[146:149], v[228:231], v[6:9]
	v_mfma_f32_16x16x32_bf16 v[2:5], v[154:157], v[228:231], v[2:5]
	v_mfma_f32_16x16x32_bf16 v[54:57], v[150:153], v[190:193], v[54:57]
	v_mfma_f32_16x16x32_bf16 v[50:53], v[182:185], v[190:193], v[50:53]
	v_mfma_f32_16x16x32_bf16 v[38:41], v[150:153], v[216:219], v[38:41]
	v_mfma_f32_16x16x32_bf16 v[34:37], v[182:185], v[216:219], v[34:37]
	v_mfma_f32_16x16x32_bf16 v[22:25], v[150:153], v[224:227], v[22:25]
	v_mfma_f32_16x16x32_bf16 v[18:21], v[182:185], v[224:227], v[18:21]
	v_mfma_f32_16x16x32_bf16 v[6:9], v[150:153], v[232:235], v[6:9]
	v_mfma_f32_16x16x32_bf16 v[2:5], v[182:185], v[232:235], v[2:5]
	s_setprio 0
	s_barrier
	s_setprio 2
	s_add_i32 s49, s49, 2
	s_add_u32 s47, s47, 0x100
	s_addc_u32 s48, s48, 0
	s_cmp_gt_u32 s49, 41
	s_mov_b64 s[18:19], s[20:21]
	s_cbranch_scc0 .LBB0_459
	v_lshl_or_b32 v198, s45, 8, v213
	v_lshl_add_u32 v217, s46, 8, v158
	v_lshlrev_b32_e32 v246, 1, v198
	v_lshl_add_u32 v246, v217, 11, v246
	v_mov_b32_e32 v247, 0
	s_mov_b32 s18, 0x8000
	s_mov_b32 s19, 0
	s_mov_b32 s88, 0x28000
	v_lshl_add_u64 v[246:247], s[94:95], 0, v[246:247]
	v_xor_b32_e32 v215, 16, v201
	v_xor_b32_e32 v216, 32, v201
	v_mov_b32_e32 v198, v246
	v_mov_b32_e32 v199, v247
	global_load_dwordx4 v[130:133], v[246:247], off
	global_load_dwordx4 v[134:137], v[246:247], off offset:256
	v_lshl_add_u64 v[246:247], v[246:247], 0, s[18:19]
	global_load_dwordx4 v[138:141], v[246:247], off
	global_load_dwordx4 v[142:145], v[246:247], off offset:256
	v_lshl_add_u64 v[246:247], v[246:247], 0, s[18:19]
	global_load_dwordx4 v[146:149], v[246:247], off
	global_load_dwordx4 v[150:153], v[246:247], off offset:256
	v_lshl_add_u64 v[246:247], v[246:247], 0, s[18:19]
	global_load_dwordx4 v[154:157], v[246:247], off
	global_load_dwordx4 v[218:221], v[246:247], off offset:256
	v_lshl_add_u64 v[246:247], v[246:247], 0, s[88:89]
	global_load_dwordx4 v[182:185], v[246:247], off
	global_load_dwordx4 v[186:189], v[246:247], off offset:256
	v_lshl_add_u64 v[246:247], v[246:247], 0, s[18:19]
	global_load_dwordx4 v[190:193], v[246:247], off
	global_load_dwordx4 v[194:197], v[246:247], off offset:256
	v_lshl_add_u64 v[246:247], v[246:247], 0, s[18:19]
	global_load_dwordx4 v[222:225], v[246:247], off
	global_load_dwordx4 v[226:229], v[246:247], off offset:256
	v_lshl_add_u64 v[246:247], v[246:247], 0, s[18:19]
	global_load_dwordx4 v[230:233], v[246:247], off
	global_load_dwordx4 v[234:237], v[246:247], off offset:256
	v_lshlrev_b32_e32 v215, 2, v215
	v_lshlrev_b32_e32 v216, 2, v216
	s_and_b64 vcc, exec, s[14:15]
	s_cbranch_vccz .LBB0_462
	s_barrier

; #define PG8_STAGE(bufoff, gbase, voff) do { _Pragma("unroll") for (int _i = 0; _i < 2; ++_i) \
;         __builtin_amdgcn_global_load_lds((const unsigned*)((const char*)(gbase) + (voff)[_i]), (PG8_LAS unsigned*)(lds + (bufoff) + ldsw + _i * 8192), 16, 0, 0); } while (0)
; #define PG8_LDA(dst, b, h) do { _Pragma("unroll") for (int m = 0; m < 4; ++m) _Pragma("unroll") for (int k = 0; k < 2; ++k) dst[m][k] = *(const PG8_LAS bf16x8*)(lds + PG8_SA(b, h) + aoff + m * 2048 + k * 1024); } while (0)
; #define PG8_LDB(dst, b, h) do { _Pragma("unroll") for (int n = 0; n < 2; ++n) _Pragma("unroll") for (int k = 0; k < 2; ++k) dst[n][k] = *(const PG8_LAS bf16x8*)(lds + PG8_SB(b, h) + boff + n * 2048 + k * 1024); } while (0)
; #define PG8_WAIT_V(n) asm volatile("s_waitcnt vmcnt(" #n ")" ::: "memory")
; #define PG8_WAIT_L(n) asm volatile("s_waitcnt lgkmcnt(" #n ")" ::: "memory")
; #define PG8_BAR __builtin_amdgcn_s_barrier()
; #define PG8_SCHED __builtin_amdgcn_sched_barrier(0)
; template <class Epi, class Sched, bool ALIGN_EPI = false, bool SP2 = false>
; __device__ __forceinline__ void gemm_phase(PG8_LAS unsigned char* lds, const Gemm g, const Sched& S, const Epi& E) {
;     ...
;         const char* nA = has_next ? (const char*)g.A + (size_t)nxt.pm * tstep : cA; const char* nB = has_next ? (const char*)g.Bt + (size_t)nxt.pn * tstep : cB;
;         for (int t = 0; t < nt; t += 2) {
;             const bool last = (t == nt - 2);
;             const char* a1 = cA + (size_t)(t + 1) * kstep;
;             const char* a2 = last ? nA : cA + (size_t)(t + 2) * kstep; const char* b2 = last ? nB : cB + (size_t)(t + 2) * kstep;
;             const char* a3 = a2 + kstep; const char* b3 = b2 + kstep;
;             if (last && has_next) S.a_ready(nxt);
;             if constexpr (SP2) {
;             PG8_LDB(B0, 0, 0); PG8_LDB(B1, 0, 1); PG8_SCHED; PG8_LDA(At, 0, 0); PG8_STAGE(PG8_SA(1, 1), a1 + hstep, voffA);
;             PG8_WAIT_V(8); PG8_WAIT_L(0); PG8_BAR; PG8_MMA(0, 0, At, B0); PG8_MMA(0, 1, At, B1); PG8_BAR; PG8_SCHED;
;             PG8_LDA(At, 0, 1); PG8_STAGE(PG8_SB(0, 0), b2, voffB); PG8_STAGE(PG8_SB(0, 1), b2 + hstep, voffB); PG8_STAGE(PG8_SA(0, 0), a2, voffA);
;             PG8_WAIT_V(8); PG8_WAIT_L(0); PG8_BAR; PG8_MMA(1, 0, At, B0); PG8_MMA(1, 1, At, B1); PG8_BAR; PG8_SCHED;
.LBB0_492:
	s_ashr_i32 s17, s16, 31
	s_lshl_b64 s[18:19], s[16:17], 19
	s_add_u32 s18, s94, s18
	s_addc_u32 s19, s95, s19
	s_and_b64 s[20:21], s[4:5], exec
	s_cselect_b32 s17, s19, s23
	s_cselect_b32 s46, s18, s22
	s_ashr_i32 s15, s14, 31
	s_lshl_b64 s[20:21], s[14:15], 19
	s_add_u32 s20, s28, s20
	s_addc_u32 s21, s29, s21
	s_and_b64 s[26:27], s[4:5], exec
	s_cselect_b32 s15, s21, s25
	s_cselect_b32 s47, s20, s24
	s_add_u32 s22, s22, 0x40080
	s_addc_u32 s23, s23, 0
	s_add_u32 s48, s24, 0x100
	s_addc_u32 s49, s25, 0
	s_mov_b32 s50, -2
	s_add_u32 s24, s22, 0xfffc0080
	s_addc_u32 s25, s23, -1
	s_add_i32 s51, 0, 0x10000
	s_cmp_eq_u32 s50, 12
	s_cselect_b32 s27, s17, s25
	s_cselect_b32 s26, s46, s24
	v_add_u32_e32 v146, s51, v149
	s_cselect_b32 s25, s15, s49
	s_cselect_b32 s24, s47, s48
	s_add_i32 s54, 0, 0x14000
	ds_read_b128 v[142:145], v146
	ds_read_b128 v[152:155], v146 offset:1024
	ds_read_b128 v[172:175], v146 offset:2048
	ds_read_b128 v[176:179], v146 offset:3072
	v_add_u32_e32 v146, s54, v149
	ds_read_b128 v[180:183], v146
	ds_read_b128 v[184:187], v146 offset:1024
	ds_read_b128 v[188:191], v146 offset:2048
	ds_read_b128 v[192:195], v146 offset:3072
	s_add_i32 m0, s30, 0xc000
	ds_read_b128 v[196:199], v151
	ds_read_b128 v[214:217], v151 offset:1024
	ds_read_b128 v[218:221], v151 offset:2048
	ds_read_b128 v[222:225], v151 offset:3072
	ds_read_b128 v[226:229], v151 offset:4096
	ds_read_b128 v[230:233], v151 offset:5120
	ds_read_b128 v[234:237], v151 offset:6144
	ds_read_b128 v[238:241], v151 offset:7168
	global_load_lds_dwordx4 v138, s[22:23]
	s_add_i32 m0, s30, 0xe000
	s_nop 0
	global_load_lds_dwordx4 v140, s[22:23]
	s_setprio 0
	s_waitcnt vmcnt(8)
	s_waitcnt lgkmcnt(0)
	s_barrier
	s_setprio 1
	s_waitcnt lgkmcnt(0)
	v_mfma_f32_16x16x32_bf16 v[126:129], v[142:145], v[196:199], 0
	v_mfma_f32_16x16x32_bf16 v[118:121], v[172:175], v[196:199], 0
	v_mfma_f32_16x16x32_bf16 v[110:113], v[142:145], v[218:221], 0
	v_mfma_f32_16x16x32_bf16 v[102:105], v[172:175], v[218:221], 0
	v_mfma_f32_16x16x32_bf16 v[94:97], v[142:145], v[226:229], 0
	v_mfma_f32_16x16x32_bf16 v[86:89], v[172:175], v[226:229], 0
	v_mfma_f32_16x16x32_bf16 v[78:81], v[142:145], v[234:237], 0
	v_mfma_f32_16x16x32_bf16 v[70:73], v[172:175], v[234:237], 0
	v_mfma_f32_16x16x32_bf16 v[126:129], v[152:155], v[214:217], v[126:129]
	v_mfma_f32_16x16x32_bf16 v[118:121], v[176:179], v[214:217], v[118:121]
	v_mfma_f32_16x16x32_bf16 v[110:113], v[152:155], v[222:225], v[110:113]
	v_mfma_f32_16x16x32_bf16 v[102:105], v[176:179], v[222:225], v[102:105]
	v_mfma_f32_16x16x32_bf16 v[94:97], v[152:155], v[230:233], v[94:97]
	v_mfma_f32_16x16x32_bf16 v[86:89], v[176:179], v[230:233], v[86:89]
	v_mfma_f32_16x16x32_bf16 v[78:81], v[152:155], v[238:241], v[78:81]
	v_mfma_f32_16x16x32_bf16 v[70:73], v[176:179], v[238:241], v[70:73]
	s_setprio 0
	s_setprio 1
	v_mfma_f32_16x16x32_bf16 v[122:125], v[180:183], v[196:199], 0
	v_mfma_f32_16x16x32_bf16 v[114:117], v[188:191], v[196:199], 0
	v_mfma_f32_16x16x32_bf16 v[106:109], v[180:183], v[218:221], 0
	v_mfma_f32_16x16x32_bf16 v[98:101], v[188:191], v[218:221], 0
	v_mfma_f32_16x16x32_bf16 v[90:93], v[180:183], v[226:229], 0
	v_mfma_f32_16x16x32_bf16 v[82:85], v[188:191], v[226:229], 0
	v_mfma_f32_16x16x32_bf16 v[74:77], v[180:183], v[234:237], 0
	v_mfma_f32_16x16x32_bf16 v[66:69], v[188:191], v[234:237], 0
	v_mfma_f32_16x16x32_bf16 v[122:125], v[184:187], v[214:217], v[122:125]
	v_mfma_f32_16x16x32_bf16 v[114:117], v[192:195], v[214:217], v[114:117]
	v_mfma_f32_16x16x32_bf16 v[106:109], v[184:187], v[222:225], v[106:109]
	v_mfma_f32_16x16x32_bf16 v[98:101], v[192:195], v[222:225], v[98:101]
	v_mfma_f32_16x16x32_bf16 v[90:93], v[184:187], v[230:233], v[90:93]
	v_mfma_f32_16x16x32_bf16 v[82:85], v[192:195], v[230:233], v[82:85]
	v_mfma_f32_16x16x32_bf16 v[74:77], v[184:187], v[238:241], v[74:77]
	v_mfma_f32_16x16x32_bf16 v[66:69], v[192:195], v[238:241], v[66:69]
	s_setprio 0
	s_barrier
	s_setprio 2
	s_add_i32 s51, s51, s2
	s_mov_b32 m0, s51
	ds_read_b128 v[196:199], v151 offset:16384
	ds_read_b128 v[214:217], v151 offset:17408
	ds_read_b128 v[218:221], v151 offset:18432
	ds_read_b128 v[222:225], v151 offset:19456
	ds_read_b128 v[226:229], v151 offset:20480
	ds_read_b128 v[230:233], v151 offset:21504
	ds_read_b128 v[234:237], v151 offset:22528
	ds_read_b128 v[238:241], v151 offset:23552
	global_load_lds_dwordx4 v0, s[24:25]
	s_add_i32 m0, s51, 0x2000
	s_add_u32 s52, s24, 0x40000
	s_addc_u32 s53, s25, 0
	s_add_i32 s51, s54, s2
	global_load_lds_dwordx4 v130, s[24:25]
	s_mov_b32 m0, s51
	s_nop 0
	global_load_lds_dwordx4 v0, s[52:53]
	s_add_i32 m0, s51, 0x2000
	s_nop 0
	global_load_lds_dwordx4 v130, s[52:53]
	s_mov_b32 m0, s30
	s_nop 0
	global_load_lds_dwordx4 v134, s[26:27]
	s_mov_b32 m0, s31
	s_nop 0
	global_load_lds_dwordx4 v132, s[26:27]
	s_setprio 0
	s_waitcnt vmcnt(8)
	s_waitcnt lgkmcnt(0)
	s_barrier
; #define PG8_STAGE(bufoff, gbase, voff) do { _Pragma("unroll") for (int _i = 0; _i < 2; ++_i) \
;         __builtin_amdgcn_global_load_lds((const unsigned*)((const char*)(gbase) + (voff)[_i]), (PG8_LAS unsigned*)(lds + (bufoff) + ldsw + _i * 8192), 16, 0, 0); } while (0)
; #define PG8_LDA(dst, b, h) do { _Pragma("unroll") for (int m = 0; m < 4; ++m) _Pragma("unroll") for (int k = 0; k < 2; ++k) dst[m][k] = *(const PG8_LAS bf16x8*)(lds + PG8_SA(b, h) + aoff + m * 2048 + k * 1024); } while (0)
; #define PG8_LDB(dst, b, h) do { _Pragma("unroll") for (int n = 0; n < 2; ++n) _Pragma("unroll") for (int k = 0; k < 2; ++k) dst[n][k] = *(const PG8_LAS bf16x8*)(lds + PG8_SB(b, h) + boff + n * 2048 + k * 1024); } while (0)
; #define PG8_MMA(ai, bj, At, Bt) do { __builtin_amdgcn_s_setprio(1); _Pragma("unroll") for (int m = 0; m < 4; ++m) _Pragma("unroll") for (int n = 0; n < 2; ++n) _Pragma("unroll") for (int k = 0; k < 2; ++k) \
;         acc[ai][bj][m][n] = __builtin_amdgcn_mfma_f32_16x16x32_bf16(Bt[n][k], At[m][k], acc[ai][bj][m][n], 0, 0, 0); __builtin_amdgcn_s_setprio(0); } while (0)
; #define PG8_WAIT_V(n) asm volatile("s_waitcnt vmcnt(" #n ")" ::: "memory")
; #define PG8_WAIT_L(n) asm volatile("s_waitcnt lgkmcnt(" #n ")" ::: "memory")
; #define PG8_BAR __builtin_amdgcn_s_barrier()
; #define PG8_SCHED __builtin_amdgcn_sched_barrier(0)
; template <class Epi, class Sched, bool ALIGN_EPI = false, bool SP2 = false>
; __device__ __forceinline__ void gemm_phase(PG8_LAS unsigned char* lds, const Gemm g, const Sched& S, const Epi& E) {
;     ...
;             PG8_WAIT_V(8); PG8_WAIT_L(0); PG8_BAR; PG8_MMA(1, 0, At, B0); PG8_MMA(1, 1, At, B1); PG8_BAR; PG8_SCHED;
;             PG8_LDB(B0, 1, 0); PG8_LDB(B1, 1, 1); PG8_SCHED; PG8_LDA(At, 1, 0); PG8_STAGE(PG8_SA(0, 1), a2 + hstep, voffA);
;             PG8_WAIT_V(8); PG8_WAIT_L(0); PG8_BAR; PG8_MMA(0, 0, At, B0); PG8_MMA(0, 1, At, B1); PG8_BAR; PG8_SCHED;
	s_setprio 1
	s_waitcnt lgkmcnt(0)
	v_mfma_f32_16x16x32_bf16 v[62:65], v[142:145], v[196:199], 0
	v_mfma_f32_16x16x32_bf16 v[54:57], v[172:175], v[196:199], 0
	v_mfma_f32_16x16x32_bf16 v[46:49], v[142:145], v[218:221], 0
	v_mfma_f32_16x16x32_bf16 v[38:41], v[172:175], v[218:221], 0
	v_mfma_f32_16x16x32_bf16 v[30:33], v[142:145], v[226:229], 0
	v_mfma_f32_16x16x32_bf16 v[22:25], v[172:175], v[226:229], 0
	v_mfma_f32_16x16x32_bf16 v[14:17], v[142:145], v[234:237], 0
	v_mfma_f32_16x16x32_bf16 v[6:9], v[172:175], v[234:237], 0
	v_mfma_f32_16x16x32_bf16 v[62:65], v[152:155], v[214:217], v[62:65]
	v_mfma_f32_16x16x32_bf16 v[54:57], v[176:179], v[214:217], v[54:57]
	v_mfma_f32_16x16x32_bf16 v[46:49], v[152:155], v[222:225], v[46:49]
	v_mfma_f32_16x16x32_bf16 v[38:41], v[176:179], v[222:225], v[38:41]
	v_mfma_f32_16x16x32_bf16 v[30:33], v[152:155], v[230:233], v[30:33]
	v_mfma_f32_16x16x32_bf16 v[22:25], v[176:179], v[230:233], v[22:25]
	v_mfma_f32_16x16x32_bf16 v[14:17], v[152:155], v[238:241], v[14:17]
	v_mfma_f32_16x16x32_bf16 v[6:9], v[176:179], v[238:241], v[6:9]
	s_setprio 0
	s_setprio 1
	v_mfma_f32_16x16x32_bf16 v[58:61], v[180:183], v[196:199], 0
	v_mfma_f32_16x16x32_bf16 v[50:53], v[188:191], v[196:199], 0
	v_mfma_f32_16x16x32_bf16 v[42:45], v[180:183], v[218:221], 0
	v_mfma_f32_16x16x32_bf16 v[34:37], v[188:191], v[218:221], 0
	v_mfma_f32_16x16x32_bf16 v[26:29], v[180:183], v[226:229], 0
	v_mfma_f32_16x16x32_bf16 v[18:21], v[188:191], v[226:229], 0
	v_mfma_f32_16x16x32_bf16 v[10:13], v[180:183], v[234:237], 0
	v_mfma_f32_16x16x32_bf16 v[2:5], v[188:191], v[234:237], 0
	v_mfma_f32_16x16x32_bf16 v[58:61], v[184:187], v[214:217], v[58:61]
	v_mfma_f32_16x16x32_bf16 v[50:53], v[192:195], v[214:217], v[50:53]
	v_mfma_f32_16x16x32_bf16 v[42:45], v[184:187], v[222:225], v[42:45]
	v_mfma_f32_16x16x32_bf16 v[34:37], v[192:195], v[222:225], v[34:37]
	v_mfma_f32_16x16x32_bf16 v[26:29], v[184:187], v[230:233], v[26:29]
	v_mfma_f32_16x16x32_bf16 v[18:21], v[192:195], v[230:233], v[18:21]
	v_mfma_f32_16x16x32_bf16 v[10:13], v[184:187], v[238:241], v[10:13]
	v_mfma_f32_16x16x32_bf16 v[2:5], v[192:195], v[238:241], v[2:5]
	s_setprio 0
	s_barrier
	s_setprio 2
	s_add_i32 s51, 0, 0x18000
	v_add_u32_e32 v158, s51, v149
	s_add_i32 s52, 0, 0x1c000
	ds_read_b128 v[142:145], v158
	ds_read_b128 v[152:155], v158 offset:1024
	ds_read_b128 v[172:175], v158 offset:2048
	ds_read_b128 v[176:179], v158 offset:3072
	v_add_u32_e32 v158, s52, v149
	ds_read_b128 v[180:183], v158
	ds_read_b128 v[184:187], v158 offset:1024
	ds_read_b128 v[188:191], v158 offset:2048
	ds_read_b128 v[192:195], v158 offset:3072
	s_add_u32 s26, s26, 0x40000
	s_addc_u32 s27, s27, 0
	s_mov_b32 m0, s34
	ds_read_b128 v[196:199], v151 offset:32768
	ds_read_b128 v[214:217], v151 offset:33792
	ds_read_b128 v[218:221], v151 offset:34816
	ds_read_b128 v[222:225], v151 offset:35840
	ds_read_b128 v[226:229], v151 offset:36864
	ds_read_b128 v[230:233], v151 offset:37888
	ds_read_b128 v[234:237], v151 offset:38912
	ds_read_b128 v[238:241], v151 offset:39936
	global_load_lds_dwordx4 v134, s[26:27]
	s_mov_b32 m0, s35
	s_nop 0
	global_load_lds_dwordx4 v132, s[26:27]
	s_setprio 0
	s_waitcnt vmcnt(8)
	s_waitcnt lgkmcnt(0)
	s_barrier
	s_setprio 1
	s_waitcnt lgkmcnt(0)
	v_mfma_f32_16x16x32_bf16 v[126:129], v[142:145], v[196:199], v[126:129]
	v_mfma_f32_16x16x32_bf16 v[118:121], v[172:175], v[196:199], v[118:121]
	v_mfma_f32_16x16x32_bf16 v[110:113], v[142:145], v[218:221], v[110:113]
	v_mfma_f32_16x16x32_bf16 v[102:105], v[172:175], v[218:221], v[102:105]
	v_mfma_f32_16x16x32_bf16 v[94:97], v[142:145], v[226:229], v[94:97]
	v_mfma_f32_16x16x32_bf16 v[86:89], v[172:175], v[226:229], v[86:89]
	v_mfma_f32_16x16x32_bf16 v[78:81], v[142:145], v[234:237], v[78:81]
	v_mfma_f32_16x16x32_bf16 v[70:73], v[172:175], v[234:237], v[70:73]
	v_mfma_f32_16x16x32_bf16 v[126:129], v[152:155], v[214:217], v[126:129]
	v_mfma_f32_16x16x32_bf16 v[118:121], v[176:179], v[214:217], v[118:121]
	v_mfma_f32_16x16x32_bf16 v[110:113], v[152:155], v[222:225], v[110:113]
	v_mfma_f32_16x16x32_bf16 v[102:105], v[176:179], v[222:225], v[102:105]
	v_mfma_f32_16x16x32_bf16 v[94:97], v[152:155], v[230:233], v[94:97]
	v_mfma_f32_16x16x32_bf16 v[86:89], v[176:179], v[230:233], v[86:89]
	v_mfma_f32_16x16x32_bf16 v[78:81], v[152:155], v[238:241], v[78:81]
	v_mfma_f32_16x16x32_bf16 v[70:73], v[176:179], v[238:241], v[70:73]
	s_setprio 0
	s_setprio 1
	v_mfma_f32_16x16x32_bf16 v[122:125], v[180:183], v[196:199], v[122:125]
	v_mfma_f32_16x16x32_bf16 v[114:117], v[188:191], v[196:199], v[114:117]
	v_mfma_f32_16x16x32_bf16 v[106:109], v[180:183], v[218:221], v[106:109]
	v_mfma_f32_16x16x32_bf16 v[98:101], v[188:191], v[218:221], v[98:101]
	v_mfma_f32_16x16x32_bf16 v[90:93], v[180:183], v[226:229], v[90:93]
	v_mfma_f32_16x16x32_bf16 v[82:85], v[188:191], v[226:229], v[82:85]
	v_mfma_f32_16x16x32_bf16 v[74:77], v[180:183], v[234:237], v[74:77]
	v_mfma_f32_16x16x32_bf16 v[66:69], v[188:191], v[234:237], v[66:69]
	v_mfma_f32_16x16x32_bf16 v[122:125], v[184:187], v[214:217], v[122:125]
	v_mfma_f32_16x16x32_bf16 v[114:117], v[192:195], v[214:217], v[114:117]
	v_mfma_f32_16x16x32_bf16 v[106:109], v[184:187], v[222:225], v[106:109]
	v_mfma_f32_16x16x32_bf16 v[98:101], v[192:195], v[222:225], v[98:101]
	v_mfma_f32_16x16x32_bf16 v[90:93], v[184:187], v[230:233], v[90:93]
	v_mfma_f32_16x16x32_bf16 v[82:85], v[192:195], v[230:233], v[82:85]
	v_mfma_f32_16x16x32_bf16 v[74:77], v[184:187], v[238:241], v[74:77]
	v_mfma_f32_16x16x32_bf16 v[66:69], v[192:195], v[238:241], v[66:69]
	s_setprio 0
	s_barrier
; #define PG8_STAGE(bufoff, gbase, voff) do { _Pragma("unroll") for (int _i = 0; _i < 2; ++_i) \
;         __builtin_amdgcn_global_load_lds((const unsigned*)((const char*)(gbase) + (voff)[_i]), (PG8_LAS unsigned*)(lds + (bufoff) + ldsw + _i * 8192), 16, 0, 0); } while (0)
; #define PG8_LDA(dst, b, h) do { _Pragma("unroll") for (int m = 0; m < 4; ++m) _Pragma("unroll") for (int k = 0; k < 2; ++k) dst[m][k] = *(const PG8_LAS bf16x8*)(lds + PG8_SA(b, h) + aoff + m * 2048 + k * 1024); } while (0)
; #define PG8_LDB(dst, b, h) do { _Pragma("unroll") for (int n = 0; n < 2; ++n) _Pragma("unroll") for (int k = 0; k < 2; ++k) dst[n][k] = *(const PG8_LAS bf16x8*)(lds + PG8_SB(b, h) + boff + n * 2048 + k * 1024); } while (0)
; #define PG8_MMA(ai, bj, At, Bt) do { __builtin_amdgcn_s_setprio(1); _Pragma("unroll") for (int m = 0; m < 4; ++m) _Pragma("unroll") for (int n = 0; n < 2; ++n) _Pragma("unroll") for (int k = 0; k < 2; ++k) \
;         acc[ai][bj][m][n] = __builtin_amdgcn_mfma_f32_16x16x32_bf16(Bt[n][k], At[m][k], acc[ai][bj][m][n], 0, 0, 0); __builtin_amdgcn_s_setprio(0); } while (0)
; #define PG8_WAIT_V(n) asm volatile("s_waitcnt vmcnt(" #n ")" ::: "memory")
; #define PG8_BAR __builtin_amdgcn_s_barrier()
; template <class Epi, class Sched, bool ALIGN_EPI = false, bool SP2 = false>
; __device__ __forceinline__ void gemm_phase(PG8_LAS unsigned char* lds, const Gemm g, const Sched& S, const Epi& E) {
;     ...
;         for (int t = 0; t < nt; t += 2) {
;             const bool last = (t == nt - 2);
;             const char* a1 = cA + (size_t)(t + 1) * kstep;
;             const char* a2 = last ? nA : cA + (size_t)(t + 2) * kstep; const char* b2 = last ? nB : cB + (size_t)(t + 2) * kstep;
;             const char* a3 = a2 + kstep; const char* b3 = b2 + kstep;
;             if (last && has_next) S.a_ready(nxt);
;             if constexpr (SP2) {
;             PG8_LDB(B0, 0, 0); PG8_LDB(B1, 0, 1); PG8_SCHED; PG8_LDA(At, 0, 0); PG8_STAGE(PG8_SA(1, 1), a1 + hstep, voffA);
;             PG8_WAIT_V(8); PG8_WAIT_L(0); PG8_BAR; PG8_MMA(0, 0, At, B0); PG8_MMA(0, 1, At, B1); PG8_BAR; PG8_SCHED;
;     ...
;             PG8_LDA(At, 1, 1); PG8_STAGE(PG8_SB(1, 0), b3, voffB); PG8_STAGE(PG8_SB(1, 1), b3 + hstep, voffB); PG8_STAGE(PG8_SA(1, 0), a3, voffA);
;             PG8_WAIT_V(8); PG8_WAIT_L(0); PG8_BAR; PG8_MMA(1, 0, At, B0); PG8_MMA(1, 1, At, B1); PG8_BAR; PG8_SCHED;
	s_setprio 2
	s_add_u32 s98, s26, 0xfffc0080
	s_addc_u32 s99, s27, -1
	s_add_i32 s26, s51, s2
	s_add_u32 s100, s24, 0x80
	s_addc_u32 s101, s25, 0
	s_mov_b32 m0, s26
	ds_read_b128 v[196:199], v151 offset:49152
	ds_read_b128 v[214:217], v151 offset:50176
	ds_read_b128 v[218:221], v151 offset:51200
	ds_read_b128 v[222:225], v151 offset:52224
	ds_read_b128 v[226:229], v151 offset:53248
	ds_read_b128 v[230:233], v151 offset:54272
	ds_read_b128 v[234:237], v151 offset:55296
	ds_read_b128 v[238:241], v151 offset:56320
	global_load_lds_dwordx4 v0, s[100:101]
	s_add_i32 m0, s26, 0x2000
	s_add_u32 s24, s24, 0x40080
	s_addc_u32 s25, s25, 0
	s_add_i32 s26, s52, s2
	global_load_lds_dwordx4 v130, s[100:101]
	s_mov_b32 m0, s26
	s_nop 0
	global_load_lds_dwordx4 v0, s[24:25]
	s_add_i32 m0, s26, 0x2000
	s_nop 0
	global_load_lds_dwordx4 v130, s[24:25]
	s_mov_b32 m0, s37
	s_nop 0
	global_load_lds_dwordx4 v134, s[98:99]
	s_mov_b32 m0, s38
	s_nop 0
	global_load_lds_dwordx4 v132, s[98:99]
	s_setprio 0
	s_waitcnt vmcnt(8)
	s_waitcnt lgkmcnt(0)
	s_barrier
	s_setprio 1
	s_waitcnt lgkmcnt(0)
	v_mfma_f32_16x16x32_bf16 v[62:65], v[142:145], v[196:199], v[62:65]
	v_mfma_f32_16x16x32_bf16 v[54:57], v[172:175], v[196:199], v[54:57]
	v_mfma_f32_16x16x32_bf16 v[46:49], v[142:145], v[218:221], v[46:49]
	v_mfma_f32_16x16x32_bf16 v[38:41], v[172:175], v[218:221], v[38:41]
	v_mfma_f32_16x16x32_bf16 v[30:33], v[142:145], v[226:229], v[30:33]
	v_mfma_f32_16x16x32_bf16 v[22:25], v[172:175], v[226:229], v[22:25]
	v_mfma_f32_16x16x32_bf16 v[14:17], v[142:145], v[234:237], v[14:17]
	v_mfma_f32_16x16x32_bf16 v[6:9], v[172:175], v[234:237], v[6:9]
	v_mfma_f32_16x16x32_bf16 v[62:65], v[152:155], v[214:217], v[62:65]
	v_mfma_f32_16x16x32_bf16 v[54:57], v[176:179], v[214:217], v[54:57]
	v_mfma_f32_16x16x32_bf16 v[46:49], v[152:155], v[222:225], v[46:49]
	v_mfma_f32_16x16x32_bf16 v[38:41], v[176:179], v[222:225], v[38:41]
	v_mfma_f32_16x16x32_bf16 v[30:33], v[152:155], v[230:233], v[30:33]
	v_mfma_f32_16x16x32_bf16 v[22:25], v[176:179], v[230:233], v[22:25]
	v_mfma_f32_16x16x32_bf16 v[14:17], v[152:155], v[238:241], v[14:17]
	v_mfma_f32_16x16x32_bf16 v[6:9], v[176:179], v[238:241], v[6:9]
	s_setprio 0
	s_setprio 1
	v_mfma_f32_16x16x32_bf16 v[58:61], v[180:183], v[196:199], v[58:61]
	v_mfma_f32_16x16x32_bf16 v[50:53], v[188:191], v[196:199], v[50:53]
	v_mfma_f32_16x16x32_bf16 v[42:45], v[180:183], v[218:221], v[42:45]
	v_mfma_f32_16x16x32_bf16 v[34:37], v[188:191], v[218:221], v[34:37]
	v_mfma_f32_16x16x32_bf16 v[26:29], v[180:183], v[226:229], v[26:29]
	v_mfma_f32_16x16x32_bf16 v[18:21], v[188:191], v[226:229], v[18:21]
	v_mfma_f32_16x16x32_bf16 v[10:13], v[180:183], v[234:237], v[10:13]
	v_mfma_f32_16x16x32_bf16 v[2:5], v[188:191], v[234:237], v[2:5]
	v_mfma_f32_16x16x32_bf16 v[58:61], v[184:187], v[214:217], v[58:61]
	v_mfma_f32_16x16x32_bf16 v[50:53], v[192:195], v[214:217], v[50:53]
	v_mfma_f32_16x16x32_bf16 v[42:45], v[184:187], v[222:225], v[42:45]
	v_mfma_f32_16x16x32_bf16 v[34:37], v[192:195], v[222:225], v[34:37]
	v_mfma_f32_16x16x32_bf16 v[26:29], v[184:187], v[230:233], v[26:29]
	v_mfma_f32_16x16x32_bf16 v[18:21], v[192:195], v[230:233], v[18:21]
	v_mfma_f32_16x16x32_bf16 v[10:13], v[184:187], v[238:241], v[10:13]
	v_mfma_f32_16x16x32_bf16 v[2:5], v[192:195], v[238:241], v[2:5]
	s_setprio 0
	s_barrier
	s_setprio 2
	s_add_i32 s50, s50, 2
	s_add_u32 s22, s22, 0x100
	s_addc_u32 s23, s23, 0
	s_add_u32 s48, s48, 0x100
	s_addc_u32 s49, s49, 0
.LBB0_493:
	s_add_u32 s24, s22, 0xfffc0080
	s_addc_u32 s25, s23, -1
	s_add_i32 s51, 0, 0x10000
	s_cmp_eq_u32 s50, 12
	s_cselect_b32 s27, s17, s25
	s_cselect_b32 s26, s46, s24
	v_add_u32_e32 v146, s51, v149
	s_cselect_b32 s25, s15, s49
	s_cselect_b32 s24, s47, s48
	s_add_i32 s54, 0, 0x14000
	ds_read_b128 v[142:145], v146
	ds_read_b128 v[152:155], v146 offset:1024
	ds_read_b128 v[172:175], v146 offset:2048
	ds_read_b128 v[176:179], v146 offset:3072
	v_add_u32_e32 v146, s54, v149
	ds_read_b128 v[180:183], v146
	ds_read_b128 v[184:187], v146 offset:1024
	ds_read_b128 v[188:191], v146 offset:2048
	ds_read_b128 v[192:195], v146 offset:3072
	s_add_i32 m0, s30, 0xc000
	ds_read_b128 v[196:199], v151
	ds_read_b128 v[214:217], v151 offset:1024
	ds_read_b128 v[218:221], v151 offset:2048
	ds_read_b128 v[222:225], v151 offset:3072
	ds_read_b128 v[226:229], v151 offset:4096
	ds_read_b128 v[230:233], v151 offset:5120
	ds_read_b128 v[234:237], v151 offset:6144
	ds_read_b128 v[238:241], v151 offset:7168
	global_load_lds_dwordx4 v138, s[22:23]
	s_add_i32 m0, s30, 0xe000
	s_nop 0
	global_load_lds_dwordx4 v140, s[22:23]
	s_setprio 0
	s_waitcnt vmcnt(8)
	s_waitcnt lgkmcnt(0)
	s_barrier
; #define PG8_STAGE(bufoff, gbase, voff) do { _Pragma("unroll") for (int _i = 0; _i < 2; ++_i) \
;         __builtin_amdgcn_global_load_lds((const unsigned*)((const char*)(gbase) + (voff)[_i]), (PG8_LAS unsigned*)(lds + (bufoff) + ldsw + _i * 8192), 16, 0, 0); } while (0)
; #define PG8_LDA(dst, b, h) do { _Pragma("unroll") for (int m = 0; m < 4; ++m) _Pragma("unroll") for (int k = 0; k < 2; ++k) dst[m][k] = *(const PG8_LAS bf16x8*)(lds + PG8_SA(b, h) + aoff + m * 2048 + k * 1024); } while (0)
; #define PG8_LDB(dst, b, h) do { _Pragma("unroll") for (int n = 0; n < 2; ++n) _Pragma("unroll") for (int k = 0; k < 2; ++k) dst[n][k] = *(const PG8_LAS bf16x8*)(lds + PG8_SB(b, h) + boff + n * 2048 + k * 1024); } while (0)
; #define PG8_MMA(ai, bj, At, Bt) do { __builtin_amdgcn_s_setprio(1); _Pragma("unroll") for (int m = 0; m < 4; ++m) _Pragma("unroll") for (int n = 0; n < 2; ++n) _Pragma("unroll") for (int k = 0; k < 2; ++k) \
;         acc[ai][bj][m][n] = __builtin_amdgcn_mfma_f32_16x16x32_bf16(Bt[n][k], At[m][k], acc[ai][bj][m][n], 0, 0, 0); __builtin_amdgcn_s_setprio(0); } while (0)
; #define PG8_WAIT_V(n) asm volatile("s_waitcnt vmcnt(" #n ")" ::: "memory")
; #define PG8_WAIT_L(n) asm volatile("s_waitcnt lgkmcnt(" #n ")" ::: "memory")
; #define PG8_BAR __builtin_amdgcn_s_barrier()
; #define PG8_SCHED __builtin_amdgcn_sched_barrier(0)
; template <class Epi, class Sched, bool ALIGN_EPI = false, bool SP2 = false>
; __device__ __forceinline__ void gemm_phase(PG8_LAS unsigned char* lds, const Gemm g, const Sched& S, const Epi& E) {
;     ...
;             PG8_WAIT_V(8); PG8_WAIT_L(0); PG8_BAR; PG8_MMA(0, 0, At, B0); PG8_MMA(0, 1, At, B1); PG8_BAR; PG8_SCHED;
;             PG8_LDA(At, 0, 1); PG8_STAGE(PG8_SB(0, 0), b2, voffB); PG8_STAGE(PG8_SB(0, 1), b2 + hstep, voffB); PG8_STAGE(PG8_SA(0, 0), a2, voffA);
;             PG8_WAIT_V(8); PG8_WAIT_L(0); PG8_BAR; PG8_MMA(1, 0, At, B0); PG8_MMA(1, 1, At, B1); PG8_BAR; PG8_SCHED;
;             PG8_LDB(B0, 1, 0); PG8_LDB(B1, 1, 1); PG8_SCHED; PG8_LDA(At, 1, 0); PG8_STAGE(PG8_SA(0, 1), a2 + hstep, voffA);
;             PG8_WAIT_V(8); PG8_WAIT_L(0); PG8_BAR; PG8_MMA(0, 0, At, B0); PG8_MMA(0, 1, At, B1); PG8_BAR; PG8_SCHED;
	s_setprio 1
	s_waitcnt lgkmcnt(0)
	v_mfma_f32_16x16x32_bf16 v[126:129], v[142:145], v[196:199], v[126:129]
	v_mfma_f32_16x16x32_bf16 v[118:121], v[172:175], v[196:199], v[118:121]
	v_mfma_f32_16x16x32_bf16 v[110:113], v[142:145], v[218:221], v[110:113]
	v_mfma_f32_16x16x32_bf16 v[102:105], v[172:175], v[218:221], v[102:105]
	v_mfma_f32_16x16x32_bf16 v[94:97], v[142:145], v[226:229], v[94:97]
	v_mfma_f32_16x16x32_bf16 v[86:89], v[172:175], v[226:229], v[86:89]
	v_mfma_f32_16x16x32_bf16 v[78:81], v[142:145], v[234:237], v[78:81]
	v_mfma_f32_16x16x32_bf16 v[70:73], v[172:175], v[234:237], v[70:73]
	v_mfma_f32_16x16x32_bf16 v[126:129], v[152:155], v[214:217], v[126:129]
	v_mfma_f32_16x16x32_bf16 v[118:121], v[176:179], v[214:217], v[118:121]
	v_mfma_f32_16x16x32_bf16 v[110:113], v[152:155], v[222:225], v[110:113]
	v_mfma_f32_16x16x32_bf16 v[102:105], v[176:179], v[222:225], v[102:105]
	v_mfma_f32_16x16x32_bf16 v[94:97], v[152:155], v[230:233], v[94:97]
	v_mfma_f32_16x16x32_bf16 v[86:89], v[176:179], v[230:233], v[86:89]
	v_mfma_f32_16x16x32_bf16 v[78:81], v[152:155], v[238:241], v[78:81]
	v_mfma_f32_16x16x32_bf16 v[70:73], v[176:179], v[238:241], v[70:73]
	s_setprio 0
	s_setprio 1
	v_mfma_f32_16x16x32_bf16 v[122:125], v[180:183], v[196:199], v[122:125]
	v_mfma_f32_16x16x32_bf16 v[114:117], v[188:191], v[196:199], v[114:117]
	v_mfma_f32_16x16x32_bf16 v[106:109], v[180:183], v[218:221], v[106:109]
	v_mfma_f32_16x16x32_bf16 v[98:101], v[188:191], v[218:221], v[98:101]
	v_mfma_f32_16x16x32_bf16 v[90:93], v[180:183], v[226:229], v[90:93]
	v_mfma_f32_16x16x32_bf16 v[82:85], v[188:191], v[226:229], v[82:85]
	v_mfma_f32_16x16x32_bf16 v[74:77], v[180:183], v[234:237], v[74:77]
	v_mfma_f32_16x16x32_bf16 v[66:69], v[188:191], v[234:237], v[66:69]
	v_mfma_f32_16x16x32_bf16 v[122:125], v[184:187], v[214:217], v[122:125]
	v_mfma_f32_16x16x32_bf16 v[114:117], v[192:195], v[214:217], v[114:117]
	v_mfma_f32_16x16x32_bf16 v[106:109], v[184:187], v[222:225], v[106:109]
	v_mfma_f32_16x16x32_bf16 v[98:101], v[192:195], v[222:225], v[98:101]
	v_mfma_f32_16x16x32_bf16 v[90:93], v[184:187], v[230:233], v[90:93]
	v_mfma_f32_16x16x32_bf16 v[82:85], v[192:195], v[230:233], v[82:85]
	v_mfma_f32_16x16x32_bf16 v[74:77], v[184:187], v[238:241], v[74:77]
	v_mfma_f32_16x16x32_bf16 v[66:69], v[192:195], v[238:241], v[66:69]
	s_setprio 0
	s_barrier
	s_setprio 2
	s_add_i32 s51, s51, s2
	s_mov_b32 m0, s51
	ds_read_b128 v[196:199], v151 offset:16384
	ds_read_b128 v[214:217], v151 offset:17408
	ds_read_b128 v[218:221], v151 offset:18432
	ds_read_b128 v[222:225], v151 offset:19456
	ds_read_b128 v[226:229], v151 offset:20480
	ds_read_b128 v[230:233], v151 offset:21504
	ds_read_b128 v[234:237], v151 offset:22528
	ds_read_b128 v[238:241], v151 offset:23552
	global_load_lds_dwordx4 v0, s[24:25]
	s_add_i32 m0, s51, 0x2000
	s_add_u32 s52, s24, 0x40000
	s_addc_u32 s53, s25, 0
	s_add_i32 s51, s54, s2
	global_load_lds_dwordx4 v130, s[24:25]
	s_mov_b32 m0, s51
	s_nop 0
	global_load_lds_dwordx4 v0, s[52:53]
	s_add_i32 m0, s51, 0x2000
	s_nop 0
	global_load_lds_dwordx4 v130, s[52:53]
	s_mov_b32 m0, s30
	s_nop 0
	global_load_lds_dwordx4 v134, s[26:27]
	s_mov_b32 m0, s31
	s_nop 0
	global_load_lds_dwordx4 v132, s[26:27]
	s_setprio 0
	s_waitcnt vmcnt(8)
	s_waitcnt lgkmcnt(0)
	s_barrier
	s_setprio 1
	s_waitcnt lgkmcnt(0)
	v_mfma_f32_16x16x32_bf16 v[62:65], v[142:145], v[196:199], v[62:65]
	v_mfma_f32_16x16x32_bf16 v[54:57], v[172:175], v[196:199], v[54:57]
	v_mfma_f32_16x16x32_bf16 v[46:49], v[142:145], v[218:221], v[46:49]
	v_mfma_f32_16x16x32_bf16 v[38:41], v[172:175], v[218:221], v[38:41]
	v_mfma_f32_16x16x32_bf16 v[30:33], v[142:145], v[226:229], v[30:33]
	v_mfma_f32_16x16x32_bf16 v[22:25], v[172:175], v[226:229], v[22:25]
	v_mfma_f32_16x16x32_bf16 v[14:17], v[142:145], v[234:237], v[14:17]
	v_mfma_f32_16x16x32_bf16 v[6:9], v[172:175], v[234:237], v[6:9]
	v_mfma_f32_16x16x32_bf16 v[62:65], v[152:155], v[214:217], v[62:65]
	v_mfma_f32_16x16x32_bf16 v[54:57], v[176:179], v[214:217], v[54:57]
	v_mfma_f32_16x16x32_bf16 v[46:49], v[152:155], v[222:225], v[46:49]
	v_mfma_f32_16x16x32_bf16 v[38:41], v[176:179], v[222:225], v[38:41]
	v_mfma_f32_16x16x32_bf16 v[30:33], v[152:155], v[230:233], v[30:33]
	v_mfma_f32_16x16x32_bf16 v[22:25], v[176:179], v[230:233], v[22:25]
	v_mfma_f32_16x16x32_bf16 v[14:17], v[152:155], v[238:241], v[14:17]
	v_mfma_f32_16x16x32_bf16 v[6:9], v[176:179], v[238:241], v[6:9]
	s_setprio 0
	s_setprio 1
	v_mfma_f32_16x16x32_bf16 v[58:61], v[180:183], v[196:199], v[58:61]
	v_mfma_f32_16x16x32_bf16 v[50:53], v[188:191], v[196:199], v[50:53]
	v_mfma_f32_16x16x32_bf16 v[42:45], v[180:183], v[218:221], v[42:45]
	v_mfma_f32_16x16x32_bf16 v[34:37], v[188:191], v[218:221], v[34:37]
	v_mfma_f32_16x16x32_bf16 v[26:29], v[180:183], v[226:229], v[26:29]
	v_mfma_f32_16x16x32_bf16 v[18:21], v[188:191], v[226:229], v[18:21]
	v_mfma_f32_16x16x32_bf16 v[10:13], v[180:183], v[234:237], v[10:13]
	v_mfma_f32_16x16x32_bf16 v[2:5], v[188:191], v[234:237], v[2:5]
	v_mfma_f32_16x16x32_bf16 v[58:61], v[184:187], v[214:217], v[58:61]
	v_mfma_f32_16x16x32_bf16 v[50:53], v[192:195], v[214:217], v[50:53]
	v_mfma_f32_16x16x32_bf16 v[42:45], v[184:187], v[222:225], v[42:45]
	v_mfma_f32_16x16x32_bf16 v[34:37], v[192:195], v[222:225], v[34:37]
	v_mfma_f32_16x16x32_bf16 v[26:29], v[184:187], v[230:233], v[26:29]
	v_mfma_f32_16x16x32_bf16 v[18:21], v[192:195], v[230:233], v[18:21]
	v_mfma_f32_16x16x32_bf16 v[10:13], v[184:187], v[238:241], v[10:13]
	v_mfma_f32_16x16x32_bf16 v[2:5], v[192:195], v[238:241], v[2:5]
	s_setprio 0
	s_barrier
; #define PG8_STAGE(bufoff, gbase, voff) do { _Pragma("unroll") for (int _i = 0; _i < 2; ++_i) \
;         __builtin_amdgcn_global_load_lds((const unsigned*)((const char*)(gbase) + (voff)[_i]), (PG8_LAS unsigned*)(lds + (bufoff) + ldsw + _i * 8192), 16, 0, 0); } while (0)
; #define PG8_LDA(dst, b, h) do { _Pragma("unroll") for (int m = 0; m < 4; ++m) _Pragma("unroll") for (int k = 0; k < 2; ++k) dst[m][k] = *(const PG8_LAS bf16x8*)(lds + PG8_SA(b, h) + aoff + m * 2048 + k * 1024); } while (0)
; #define PG8_LDB(dst, b, h) do { _Pragma("unroll") for (int n = 0; n < 2; ++n) _Pragma("unroll") for (int k = 0; k < 2; ++k) dst[n][k] = *(const PG8_LAS bf16x8*)(lds + PG8_SB(b, h) + boff + n * 2048 + k * 1024); } while (0)
; #define PG8_MMA(ai, bj, At, Bt) do { __builtin_amdgcn_s_setprio(1); _Pragma("unroll") for (int m = 0; m < 4; ++m) _Pragma("unroll") for (int n = 0; n < 2; ++n) _Pragma("unroll") for (int k = 0; k < 2; ++k) \
;         acc[ai][bj][m][n] = __builtin_amdgcn_mfma_f32_16x16x32_bf16(Bt[n][k], At[m][k], acc[ai][bj][m][n], 0, 0, 0); __builtin_amdgcn_s_setprio(0); } while (0)
; #define PG8_WAIT_V(n) asm volatile("s_waitcnt vmcnt(" #n ")" ::: "memory")
; #define PG8_WAIT_L(n) asm volatile("s_waitcnt lgkmcnt(" #n ")" ::: "memory")
; #define PG8_BAR __builtin_amdgcn_s_barrier()
; #define PG8_SCHED __builtin_amdgcn_sched_barrier(0)
; template <class Epi, class Sched, bool ALIGN_EPI = false, bool SP2 = false>
; __device__ __forceinline__ void gemm_phase(PG8_LAS unsigned char* lds, const Gemm g, const Sched& S, const Epi& E) {
;     ...
;             PG8_LDB(B0, 1, 0); PG8_LDB(B1, 1, 1); PG8_SCHED; PG8_LDA(At, 1, 0); PG8_STAGE(PG8_SA(0, 1), a2 + hstep, voffA);
;             PG8_WAIT_V(8); PG8_WAIT_L(0); PG8_BAR; PG8_MMA(0, 0, At, B0); PG8_MMA(0, 1, At, B1); PG8_BAR; PG8_SCHED;
;             PG8_LDA(At, 1, 1); PG8_STAGE(PG8_SB(1, 0), b3, voffB); PG8_STAGE(PG8_SB(1, 1), b3 + hstep, voffB); PG8_STAGE(PG8_SA(1, 0), a3, voffA);
;             PG8_WAIT_V(8); PG8_WAIT_L(0); PG8_BAR; PG8_MMA(1, 0, At, B0); PG8_MMA(1, 1, At, B1); PG8_BAR; PG8_SCHED;
	s_setprio 2
	s_add_i32 s51, 0, 0x18000
	v_add_u32_e32 v158, s51, v149
	s_add_i32 s52, 0, 0x1c000
	ds_read_b128 v[142:145], v158
	ds_read_b128 v[152:155], v158 offset:1024
	ds_read_b128 v[172:175], v158 offset:2048
	ds_read_b128 v[176:179], v158 offset:3072
	v_add_u32_e32 v158, s52, v149
	ds_read_b128 v[180:183], v158
	ds_read_b128 v[184:187], v158 offset:1024
	ds_read_b128 v[188:191], v158 offset:2048
	ds_read_b128 v[192:195], v158 offset:3072
	s_add_u32 s26, s26, 0x40000
	s_addc_u32 s27, s27, 0
	s_mov_b32 m0, s34
	ds_read_b128 v[196:199], v151 offset:32768
	ds_read_b128 v[214:217], v151 offset:33792
	ds_read_b128 v[218:221], v151 offset:34816
	ds_read_b128 v[222:225], v151 offset:35840
	ds_read_b128 v[226:229], v151 offset:36864
	ds_read_b128 v[230:233], v151 offset:37888
	ds_read_b128 v[234:237], v151 offset:38912
	ds_read_b128 v[238:241], v151 offset:39936
	global_load_lds_dwordx4 v134, s[26:27]
	s_mov_b32 m0, s35
	s_nop 0
	global_load_lds_dwordx4 v132, s[26:27]
	s_setprio 0
	s_waitcnt vmcnt(8)
	s_waitcnt lgkmcnt(0)
	s_barrier
	s_setprio 1
	s_waitcnt lgkmcnt(0)
	v_mfma_f32_16x16x32_bf16 v[126:129], v[142:145], v[196:199], v[126:129]
	v_mfma_f32_16x16x32_bf16 v[118:121], v[172:175], v[196:199], v[118:121]
	v_mfma_f32_16x16x32_bf16 v[110:113], v[142:145], v[218:221], v[110:113]
	v_mfma_f32_16x16x32_bf16 v[102:105], v[172:175], v[218:221], v[102:105]
	v_mfma_f32_16x16x32_bf16 v[94:97], v[142:145], v[226:229], v[94:97]
	v_mfma_f32_16x16x32_bf16 v[86:89], v[172:175], v[226:229], v[86:89]
	v_mfma_f32_16x16x32_bf16 v[78:81], v[142:145], v[234:237], v[78:81]
	v_mfma_f32_16x16x32_bf16 v[70:73], v[172:175], v[234:237], v[70:73]
	v_mfma_f32_16x16x32_bf16 v[126:129], v[152:155], v[214:217], v[126:129]
	v_mfma_f32_16x16x32_bf16 v[118:121], v[176:179], v[214:217], v[118:121]
	v_mfma_f32_16x16x32_bf16 v[110:113], v[152:155], v[222:225], v[110:113]
	v_mfma_f32_16x16x32_bf16 v[102:105], v[176:179], v[222:225], v[102:105]
	v_mfma_f32_16x16x32_bf16 v[94:97], v[152:155], v[230:233], v[94:97]
	v_mfma_f32_16x16x32_bf16 v[86:89], v[176:179], v[230:233], v[86:89]
	v_mfma_f32_16x16x32_bf16 v[78:81], v[152:155], v[238:241], v[78:81]
	v_mfma_f32_16x16x32_bf16 v[70:73], v[176:179], v[238:241], v[70:73]
	s_setprio 0
	s_setprio 1
	v_mfma_f32_16x16x32_bf16 v[122:125], v[180:183], v[196:199], v[122:125]
	v_mfma_f32_16x16x32_bf16 v[114:117], v[188:191], v[196:199], v[114:117]
	v_mfma_f32_16x16x32_bf16 v[106:109], v[180:183], v[218:221], v[106:109]
	v_mfma_f32_16x16x32_bf16 v[98:101], v[188:191], v[218:221], v[98:101]
	v_mfma_f32_16x16x32_bf16 v[90:93], v[180:183], v[226:229], v[90:93]
	v_mfma_f32_16x16x32_bf16 v[82:85], v[188:191], v[226:229], v[82:85]
	v_mfma_f32_16x16x32_bf16 v[74:77], v[180:183], v[234:237], v[74:77]
	v_mfma_f32_16x16x32_bf16 v[66:69], v[188:191], v[234:237], v[66:69]
	v_mfma_f32_16x16x32_bf16 v[122:125], v[184:187], v[214:217], v[122:125]
	v_mfma_f32_16x16x32_bf16 v[114:117], v[192:195], v[214:217], v[114:117]
	v_mfma_f32_16x16x32_bf16 v[106:109], v[184:187], v[222:225], v[106:109]
	v_mfma_f32_16x16x32_bf16 v[98:101], v[192:195], v[222:225], v[98:101]
	v_mfma_f32_16x16x32_bf16 v[90:93], v[184:187], v[230:233], v[90:93]
	v_mfma_f32_16x16x32_bf16 v[82:85], v[192:195], v[230:233], v[82:85]
	v_mfma_f32_16x16x32_bf16 v[74:77], v[184:187], v[238:241], v[74:77]
	v_mfma_f32_16x16x32_bf16 v[66:69], v[192:195], v[238:241], v[66:69]
	s_setprio 0
	s_barrier
	s_setprio 2
	s_add_u32 s98, s26, 0xfffc0080
	s_addc_u32 s99, s27, -1
	s_add_i32 s26, s51, s2
	s_add_u32 s100, s24, 0x80
	s_addc_u32 s101, s25, 0
	s_mov_b32 m0, s26
	ds_read_b128 v[196:199], v151 offset:49152
	ds_read_b128 v[214:217], v151 offset:50176
	ds_read_b128 v[218:221], v151 offset:51200
	ds_read_b128 v[222:225], v151 offset:52224
	ds_read_b128 v[226:229], v151 offset:53248
	ds_read_b128 v[230:233], v151 offset:54272
	ds_read_b128 v[234:237], v151 offset:55296
	ds_read_b128 v[238:241], v151 offset:56320
	global_load_lds_dwordx4 v0, s[100:101]
	s_add_i32 m0, s26, 0x2000
	s_add_u32 s24, s24, 0x40080
	s_addc_u32 s25, s25, 0
	s_add_i32 s26, s52, s2
	global_load_lds_dwordx4 v130, s[100:101]
	s_mov_b32 m0, s26
	s_nop 0
	global_load_lds_dwordx4 v0, s[24:25]
	s_add_i32 m0, s26, 0x2000
	s_nop 0
	global_load_lds_dwordx4 v130, s[24:25]
	s_mov_b32 m0, s37
	s_nop 0
	global_load_lds_dwordx4 v134, s[98:99]
	s_mov_b32 m0, s38
	s_nop 0
	global_load_lds_dwordx4 v132, s[98:99]
	s_setprio 0
	s_waitcnt vmcnt(8)
	s_waitcnt lgkmcnt(0)
	s_barrier
; #define PG8_WAIT_V(n) asm volatile("s_waitcnt vmcnt(" #n ")" ::: "memory")
; template <class Epi, class Sched, bool ALIGN_EPI = false, bool SP2 = false>
; __device__ __forceinline__ void gemm_phase(PG8_LAS unsigned char* lds, const Gemm g, const Sched& S, const Epi& E) {
;     ...
;             PG8_WAIT_V(8); PG8_WAIT_L(0); PG8_BAR; PG8_MMA(1, 0, At, B0); PG8_MMA(1, 1, At, B1); PG8_BAR; PG8_SCHED;
;             } else {
;             PG8_LDB(B0, 0, 0); PG8_SCHED; PG8_LDA(At, 0, 0); PG8_STAGE(PG8_SA(1, 1), a1 + hstep, voffA);
;             PG8_WAIT_L(8); PG8_BAR; PG8_WAIT_L(0); PG8_MMA(0, 0, At, B0); PG8_BAR; PG8_SCHED;
;             PG8_LDB(B1, 0, 1); PG8_STAGE(PG8_SB(0, 0), b2, voffB);
;             PG8_BAR; PG8_WAIT_L(0); PG8_MMA(0, 1, At, B1); PG8_BAR;
;             PG8_LDA(At, 0, 1); PG8_STAGE(PG8_SA(0, 0), a2, voffA);
;             PG8_BAR; PG8_WAIT_L(0); PG8_MMA(1, 0, At, B0); PG8_BAR; PG8_SCHED;
;             PG8_STAGE(PG8_SB(0, 1), b2 + hstep, voffB);
;             PG8_WAIT_V(6); PG8_BAR; PG8_MMA(1, 1, At, B1); PG8_BAR;
;             PG8_LDB(B0, 1, 0); PG8_SCHED; PG8_LDA(At, 1, 0); PG8_STAGE(PG8_SA(0, 1), a2 + hstep, voffA);
;             PG8_WAIT_L(8); PG8_BAR; PG8_WAIT_L(0); PG8_MMA(0, 0, At, B0); PG8_BAR; PG8_SCHED;
;             PG8_LDB(B1, 1, 1); PG8_STAGE(PG8_SB(1, 0), b3, voffB);
;             PG8_BAR; PG8_WAIT_L(0); PG8_MMA(0, 1, At, B1); PG8_BAR;
;             PG8_LDA(At, 1, 1); PG8_STAGE(PG8_SA(1, 0), a3, voffA);
;             PG8_BAR; PG8_WAIT_L(0); PG8_MMA(1, 0, At, B0); PG8_BAR; PG8_SCHED;
;             PG8_STAGE(PG8_SB(1, 1), b3 + hstep, voffB);
;             PG8_WAIT_V(6); PG8_BAR; PG8_MMA(1, 1, At, B1); PG8_BAR;
;             }
;         }
;         if constexpr (ALIGN_EPI) { if (wr == 0) PG8_BAR; }
; __device__ __forceinline__ float row_rstd(const float* rsp, int row, int fq) {
;     const f32x4 v = *(const f32x4*)(rsp + (size_t)row * 16 + 4 * fq);
;     float s = (v[0] + v[1]) + (v[2] + v[3]); s += __shfl_xor(s, 16); s += __shfl_xor(s, 32);
;     return rsqrtf(s * (1.0f / 1024.0f) + RMS_EPS);
; }
;     __device__ __forceinline__ void operator()(const f32x4 (&acc)[2][2][4][2], const Unit& u, int wr, int wc, int fr, int fq) const {
;         const int row0 = u.pm * BM + wr * 64 + fr, col0 = u.pn * HALF + wc * 32 + 8 * fq;
; #pragma unroll
;         for (int ai = 0; ai < 2; ++ai)
; #pragma unroll
;             for (int m = 0; m < 4; ++m) {
	s_setprio 1
	s_waitcnt lgkmcnt(0)
	v_mfma_f32_16x16x32_bf16 v[62:65], v[142:145], v[196:199], v[62:65]
	v_mfma_f32_16x16x32_bf16 v[54:57], v[172:175], v[196:199], v[54:57]
	v_mfma_f32_16x16x32_bf16 v[46:49], v[142:145], v[218:221], v[46:49]
	v_mfma_f32_16x16x32_bf16 v[38:41], v[172:175], v[218:221], v[38:41]
	v_mfma_f32_16x16x32_bf16 v[30:33], v[142:145], v[226:229], v[30:33]
	v_mfma_f32_16x16x32_bf16 v[22:25], v[172:175], v[226:229], v[22:25]
	v_mfma_f32_16x16x32_bf16 v[14:17], v[142:145], v[234:237], v[14:17]
	v_mfma_f32_16x16x32_bf16 v[6:9], v[172:175], v[234:237], v[6:9]
	v_mfma_f32_16x16x32_bf16 v[62:65], v[152:155], v[214:217], v[62:65]
	v_mfma_f32_16x16x32_bf16 v[54:57], v[176:179], v[214:217], v[54:57]
	v_mfma_f32_16x16x32_bf16 v[46:49], v[152:155], v[222:225], v[46:49]
	v_mfma_f32_16x16x32_bf16 v[38:41], v[176:179], v[222:225], v[38:41]
	v_mfma_f32_16x16x32_bf16 v[30:33], v[152:155], v[230:233], v[30:33]
	v_mfma_f32_16x16x32_bf16 v[22:25], v[176:179], v[230:233], v[22:25]
	v_mfma_f32_16x16x32_bf16 v[14:17], v[152:155], v[238:241], v[14:17]
	v_mfma_f32_16x16x32_bf16 v[6:9], v[176:179], v[238:241], v[6:9]
	s_setprio 0
	s_setprio 1
	v_mfma_f32_16x16x32_bf16 v[58:61], v[180:183], v[196:199], v[58:61]
	v_mfma_f32_16x16x32_bf16 v[50:53], v[188:191], v[196:199], v[50:53]
	v_mfma_f32_16x16x32_bf16 v[42:45], v[180:183], v[218:221], v[42:45]
	v_mfma_f32_16x16x32_bf16 v[34:37], v[188:191], v[218:221], v[34:37]
	v_mfma_f32_16x16x32_bf16 v[26:29], v[180:183], v[226:229], v[26:29]
	v_mfma_f32_16x16x32_bf16 v[18:21], v[188:191], v[226:229], v[18:21]
	v_mfma_f32_16x16x32_bf16 v[10:13], v[180:183], v[234:237], v[10:13]
	v_mfma_f32_16x16x32_bf16 v[2:5], v[188:191], v[234:237], v[2:5]
	v_mfma_f32_16x16x32_bf16 v[58:61], v[184:187], v[214:217], v[58:61]
	v_mfma_f32_16x16x32_bf16 v[50:53], v[192:195], v[214:217], v[50:53]
	v_mfma_f32_16x16x32_bf16 v[42:45], v[184:187], v[222:225], v[42:45]
	v_mfma_f32_16x16x32_bf16 v[34:37], v[192:195], v[222:225], v[34:37]
	v_mfma_f32_16x16x32_bf16 v[26:29], v[184:187], v[230:233], v[26:29]
	v_mfma_f32_16x16x32_bf16 v[18:21], v[192:195], v[230:233], v[18:21]
	v_mfma_f32_16x16x32_bf16 v[10:13], v[184:187], v[238:241], v[10:13]
	v_mfma_f32_16x16x32_bf16 v[2:5], v[192:195], v[238:241], v[2:5]
	s_setprio 0
	s_barrier
	s_setprio 2
	s_add_i32 s50, s50, 2
	s_add_u32 s22, s22, 0x100
	s_addc_u32 s23, s23, 0
	s_add_u32 s48, s48, 0x100
	s_addc_u32 s49, s49, 0
	s_cmp_gt_u32 s50, 13
	s_cbranch_scc0 .LBB0_493
	v_lshl_add_u32 v142, s45, 8, v148
	v_mov_b32_e32 v143, 0
	s_mov_b32 s26, 0x2000
	s_mov_b32 s27, 0
	v_lshlrev_b64 v[146:147], 6, v[142:143]
	v_lshl_add_u64 v[146:147], v[136:137], 0, v[146:147]
	v_lshl_add_u64 v[156:157], v[146:147], 0, s[26:27]
	global_load_dwordx4 v[172:175], v[146:147], off
	global_load_dwordx4 v[176:179], v[146:147], off offset:1024
	global_load_dwordx4 v[180:183], v[146:147], off offset:2048
	global_load_dwordx4 v[184:187], v[146:147], off offset:3072
	global_load_dwordx4 v[188:191], v[156:157], off
	global_load_dwordx4 v[192:195], v[156:157], off offset:1024
	global_load_dwordx4 v[196:199], v[156:157], off offset:2048
	global_load_dwordx4 v[214:217], v[156:157], off offset:3072
	v_xor_b32_e32 v152, 16, v201
	v_xor_b32_e32 v153, 32, v201
	v_lshlrev_b32_e32 v152, 2, v152
	v_lshlrev_b32_e32 v153, 2, v153
	v_lshl_or_b32 v144, s44, 7, v150
	v_mov_b32_e32 v145, 0
	v_mov_b32_e32 v238, s0
	v_mov_b32_e32 v239, s1
	v_mad_i64_i32 v[236:237], s[22:23], v142, s93, v[238:239]
	v_lshlrev_b64 v[240:241], 1, v[144:145]
	v_mov_b32_e32 v234, 1.0
	v_mov_b32_e32 v235, 1.0
	v_lshl_add_u64 v[236:237], v[236:237], 0, v[240:241]
	s_mov_b32 s26, 0x16000
	s_mov_b32 s24, 0x6e000
	s_mov_b32 s25, 0
	s_and_b64 vcc, exec, s[12:13]
	s_cbranch_vccz .LBB0_496
	s_barrier
